# weight-copy items: the 16 per-row gain loads of an item issued together (were serialised round trips), stacked on the previous version
# speedup vs baseline: 1.0064x; 1.0035x over previous
.LBB0_35:
	s_cmpk_gt_i32 s3, 0x2bf
	s_mov_b64 s[28:29], -1
	s_cbranch_scc0 .LBB0_61
	s_add_i32 s2, s3, 0xfd40
	s_and_b32 s8, s2, 0xffff
	s_mul_i32 s8, s8, 0xba2f
	s_lshr_b32 s8, s8, 21
	s_mul_i32 s9, s8, 44
	s_sub_i32 s30, s2, s9
	s_lshl_b32 s2, s8, 6
	v_or_b32_e32 v79, s2, v68
	s_lshl_b32 s8, s30, 8
	s_and_b32 s26, s8, 0x3ff00
	v_mul_u32_u24_e32 v6, 0xb00, v79
	v_lshl_add_u64 v[2:3], v[74:75], 0, s[26:27]
	v_lshlrev_b32_e32 v70, 2, v6
	v_mad_u64_u32 v[4:5], s[28:29], v79, s42, v[2:3]
	v_lshl_add_u64 v[2:3], v[2:3], 0, v[70:71]
	s_mov_b32 s8, 0xb000
	v_add_co_u32_e32 v6, vcc, s8, v2
	s_mov_b32 s8, 0x16000
	s_nop 0
	v_addc_co_u32_e32 v7, vcc, 0, v3, vcc
	global_load_dwordx4 v[62:65], v[4:5], off nt
	global_load_dwordx4 v[58:61], v[6:7], off nt
	v_add_co_u32_e32 v4, vcc, s8, v2
	s_mov_b32 s8, 0x21000
	s_nop 0
	v_addc_co_u32_e32 v5, vcc, 0, v3, vcc
	v_add_co_u32_e32 v6, vcc, s8, v2
	s_mov_b32 s8, 0x2c000
	s_nop 0
	v_addc_co_u32_e32 v7, vcc, 0, v3, vcc
	global_load_dwordx4 v[54:57], v[4:5], off nt
	global_load_dwordx4 v[50:53], v[6:7], off nt
	v_add_co_u32_e32 v4, vcc, s8, v2
	s_mov_b32 s8, 0x37000
	s_nop 0
	v_addc_co_u32_e32 v5, vcc, 0, v3, vcc
	v_add_co_u32_e32 v6, vcc, s8, v2
	s_mov_b32 s8, 0x42000
	s_nop 0
	v_addc_co_u32_e32 v7, vcc, 0, v3, vcc
	global_load_dwordx4 v[46:49], v[4:5], off nt
	global_load_dwordx4 v[42:45], v[6:7], off nt
	v_add_co_u32_e32 v4, vcc, s8, v2
	s_mov_b32 s8, 0x4d000
	s_nop 0
	v_addc_co_u32_e32 v5, vcc, 0, v3, vcc
	v_add_co_u32_e32 v6, vcc, s8, v2
	s_mov_b32 s8, 0x58000
	s_nop 0
	v_addc_co_u32_e32 v7, vcc, 0, v3, vcc
	global_load_dwordx4 v[38:41], v[4:5], off nt
	global_load_dwordx4 v[34:37], v[6:7], off nt
	v_add_co_u32_e32 v4, vcc, s8, v2
	s_mov_b32 s8, 0x63000
	s_nop 0
	v_addc_co_u32_e32 v5, vcc, 0, v3, vcc
	v_add_co_u32_e32 v6, vcc, s8, v2
	s_mov_b32 s8, 0x6e000
	s_nop 0
	v_addc_co_u32_e32 v7, vcc, 0, v3, vcc
	global_load_dwordx4 v[30:33], v[4:5], off nt
	global_load_dwordx4 v[26:29], v[6:7], off nt
	v_add_co_u32_e32 v4, vcc, s8, v2
	s_mov_b32 s8, 0x79000
	s_nop 0
	v_addc_co_u32_e32 v5, vcc, 0, v3, vcc
	v_add_co_u32_e32 v6, vcc, s8, v2
	s_mov_b32 s8, 0x84000
	s_nop 0
	v_addc_co_u32_e32 v7, vcc, 0, v3, vcc
	global_load_dwordx4 v[22:25], v[4:5], off nt
	global_load_dwordx4 v[18:21], v[6:7], off nt
	v_add_co_u32_e32 v4, vcc, s8, v2
	v_add_lshl_u32 v78, s2, v68, 2
	s_nop 0
	v_addc_co_u32_e32 v5, vcc, 0, v3, vcc
	v_add_co_u32_e32 v6, vcc, 0x8f000, v2
	s_nop 1
	v_addc_co_u32_e32 v7, vcc, 0, v3, vcc
	global_load_dwordx4 v[14:17], v[4:5], off nt
	global_load_dwordx4 v[10:13], v[6:7], off nt
	v_add_co_u32_e32 v4, vcc, 0x9a000, v2
	s_nop 1
	v_addc_co_u32_e32 v5, vcc, 0, v3, vcc
	v_add_co_u32_e32 v2, vcc, 0xa5000, v2
	s_nop 1
	v_addc_co_u32_e32 v3, vcc, 0, v3, vcc
	global_load_dwordx4 v[6:9], v[4:5], off nt
	s_nop 0
	global_load_dwordx4 v[2:5], v[2:3], off nt
	s_and_b64 vcc, exec, s[4:5]
	s_cbranch_vccnz .LBB0_85
	v_readlane_b32 s72, v254, 10
	v_lshlrev_b32_e32 v70, 2, v79
	v_readlane_b32 s82, v254, 20
	v_readlane_b32 s83, v254, 21
	s_nop 4
	global_load_dword v188, v70, s[82:83]
	global_load_dword v190, v78, s[82:83] offset:16
	global_load_dword v192, v78, s[82:83] offset:32
	global_load_dword v194, v78, s[82:83] offset:48
	global_load_dword v196, v78, s[82:83] offset:64
	global_load_dword v198, v78, s[82:83] offset:80
	global_load_dword v200, v78, s[82:83] offset:96
	global_load_dword v202, v78, s[82:83] offset:112
	global_load_dword v204, v78, s[82:83] offset:128
	global_load_dword v206, v78, s[82:83] offset:144
	global_load_dword v208, v78, s[82:83] offset:160
	global_load_dword v210, v78, s[82:83] offset:176
	global_load_dword v212, v78, s[82:83] offset:192
	global_load_dword v214, v78, s[82:83] offset:208
	global_load_dword v216, v78, s[82:83] offset:224
	global_load_dword v218, v78, s[82:83] offset:240
	s_nop 0
	v_add_u32_e32 v79, v80, v81
	v_readlane_b32 s73, v254, 11
	v_readlane_b32 s74, v254, 12
	v_readlane_b32 s75, v254, 13
	v_readlane_b32 s76, v254, 14
	v_readlane_b32 s77, v254, 15
	v_readlane_b32 s78, v254, 16
	v_readlane_b32 s79, v254, 17
	v_readlane_b32 s80, v254, 18
	v_readlane_b32 s81, v254, 19
	v_readlane_b32 s84, v254, 22
	v_readlane_b32 s85, v254, 23
	v_readlane_b32 s86, v254, 24
	v_readlane_b32 s87, v254, 25
	s_waitcnt vmcnt(0)
	v_pk_mul_f32 v[108:109], v[62:63], v[188:189] op_sel_hi:[1,0]
	v_pk_mul_f32 v[106:107], v[64:65], v[188:189] op_sel_hi:[1,0]
	ds_write2_b32 v79, v108, v109 offset1:1
	ds_write2_b32 v79, v106, v107 offset0:2 offset1:3
	s_cbranch_execnz .LBB0_39
.LBB0_38:
	s_waitcnt vmcnt(0)
	v_add_u32_e32 v70, v80, v81
	ds_write2_b32 v70, v62, v63 offset1:1
	ds_write2_b32 v70, v64, v65 offset0:2 offset1:3
	v_mov_b32_e32 v190, 1.0
.LBB0_39:
	s_waitcnt vmcnt(0)
	v_pk_mul_f32 v[58:59], v[58:59], v[190:191] op_sel_hi:[1,0]
	v_add_u32_e32 v62, v80, v95
	ds_write2_b32 v62, v58, v59 offset1:1
	v_pk_mul_f32 v[58:59], v[60:61], v[190:191] op_sel_hi:[1,0]
	s_and_b64 vcc, exec, s[4:5]
	ds_write2_b32 v62, v58, v59 offset0:2 offset1:3
	s_cbranch_vccnz .LBB0_86
	v_readlane_b32 s72, v254, 10
	v_readlane_b32 s82, v254, 20
	v_readlane_b32 s83, v254, 21
	s_nop 4
	v_add_u32_e32 v59, v80, v96
	v_readlane_b32 s73, v254, 11
	v_readlane_b32 s74, v254, 12
	v_readlane_b32 s75, v254, 13
	v_readlane_b32 s76, v254, 14
	v_readlane_b32 s77, v254, 15
	v_readlane_b32 s78, v254, 16
	v_readlane_b32 s79, v254, 17
	v_readlane_b32 s80, v254, 18
	v_readlane_b32 s81, v254, 19
	v_readlane_b32 s84, v254, 22
	v_readlane_b32 s85, v254, 23
	v_readlane_b32 s86, v254, 24
	v_readlane_b32 s87, v254, 25
	s_waitcnt vmcnt(1)
	v_pk_mul_f32 v[62:63], v[54:55], v[192:193] op_sel_hi:[1,0]
	v_pk_mul_f32 v[60:61], v[56:57], v[192:193] op_sel_hi:[1,0]
	ds_write2_b32 v59, v62, v63 offset1:1
	ds_write2_b32 v59, v60, v61 offset0:2 offset1:3
	s_cbranch_execnz .LBB0_42
.LBB0_41:
	s_waitcnt vmcnt(0)
	v_add_u32_e32 v58, v80, v96
	ds_write2_b32 v58, v54, v55 offset1:1
	ds_write2_b32 v58, v56, v57 offset0:2 offset1:3
	v_mov_b32_e32 v194, 1.0
.LBB0_42:
	s_waitcnt vmcnt(0)
	v_pk_mul_f32 v[50:51], v[50:51], v[194:195] op_sel_hi:[1,0]
	v_add_u32_e32 v54, v80, v97
	ds_write2_b32 v54, v50, v51 offset1:1
	v_pk_mul_f32 v[50:51], v[52:53], v[194:195] op_sel_hi:[1,0]
	s_and_b64 vcc, exec, s[4:5]
	ds_write2_b32 v54, v50, v51 offset0:2 offset1:3
	s_cbranch_vccnz .LBB0_87
	v_readlane_b32 s72, v254, 10
	v_readlane_b32 s82, v254, 20
	v_readlane_b32 s83, v254, 21
	s_nop 4
	v_add_u32_e32 v51, v80, v98
	v_readlane_b32 s73, v254, 11
	v_readlane_b32 s74, v254, 12
	v_readlane_b32 s75, v254, 13
	v_readlane_b32 s76, v254, 14
	v_readlane_b32 s77, v254, 15
	v_readlane_b32 s78, v254, 16
	v_readlane_b32 s79, v254, 17
	v_readlane_b32 s80, v254, 18
	v_readlane_b32 s81, v254, 19
	v_readlane_b32 s84, v254, 22
	v_readlane_b32 s85, v254, 23
	v_readlane_b32 s86, v254, 24
	v_readlane_b32 s87, v254, 25
	s_waitcnt vmcnt(1)
	v_pk_mul_f32 v[54:55], v[46:47], v[196:197] op_sel_hi:[1,0]
	v_pk_mul_f32 v[52:53], v[48:49], v[196:197] op_sel_hi:[1,0]
	ds_write2_b32 v51, v54, v55 offset1:1
	ds_write2_b32 v51, v52, v53 offset0:2 offset1:3
	s_cbranch_execnz .LBB0_45
.LBB0_44:
	s_waitcnt vmcnt(0)
	v_add_u32_e32 v50, v80, v98
	ds_write2_b32 v50, v46, v47 offset1:1
	ds_write2_b32 v50, v48, v49 offset0:2 offset1:3
	v_mov_b32_e32 v198, 1.0
.LBB0_45:
	s_waitcnt vmcnt(0)
	v_pk_mul_f32 v[42:43], v[42:43], v[198:199] op_sel_hi:[1,0]
	v_add_u32_e32 v46, v80, v99
	ds_write2_b32 v46, v42, v43 offset1:1
	v_pk_mul_f32 v[42:43], v[44:45], v[198:199] op_sel_hi:[1,0]
	s_and_b64 vcc, exec, s[4:5]
	ds_write2_b32 v46, v42, v43 offset0:2 offset1:3
	s_cbranch_vccnz .LBB0_88
	v_readlane_b32 s72, v254, 10
	v_readlane_b32 s82, v254, 20
	v_readlane_b32 s83, v254, 21
	s_nop 4
	v_add_u32_e32 v43, v80, v100
	v_readlane_b32 s73, v254, 11
	v_readlane_b32 s74, v254, 12
	v_readlane_b32 s75, v254, 13
	v_readlane_b32 s76, v254, 14
	v_readlane_b32 s77, v254, 15
	v_readlane_b32 s78, v254, 16
	v_readlane_b32 s79, v254, 17
	v_readlane_b32 s80, v254, 18
	v_readlane_b32 s81, v254, 19
	v_readlane_b32 s84, v254, 22
	v_readlane_b32 s85, v254, 23
	v_readlane_b32 s86, v254, 24
	v_readlane_b32 s87, v254, 25
	s_waitcnt vmcnt(1)
	v_pk_mul_f32 v[46:47], v[38:39], v[200:201] op_sel_hi:[1,0]
	v_pk_mul_f32 v[44:45], v[40:41], v[200:201] op_sel_hi:[1,0]
	ds_write2_b32 v43, v46, v47 offset1:1
	ds_write2_b32 v43, v44, v45 offset0:2 offset1:3
	s_cbranch_execnz .LBB0_48
.LBB0_47:
	s_waitcnt vmcnt(0)
	v_add_u32_e32 v42, v80, v100
	ds_write2_b32 v42, v38, v39 offset1:1
	ds_write2_b32 v42, v40, v41 offset0:2 offset1:3
	v_mov_b32_e32 v202, 1.0
.LBB0_48:
	s_waitcnt vmcnt(0)
	v_pk_mul_f32 v[34:35], v[34:35], v[202:203] op_sel_hi:[1,0]
	v_add_u32_e32 v38, v80, v101
	ds_write2_b32 v38, v34, v35 offset1:1
	v_pk_mul_f32 v[34:35], v[36:37], v[202:203] op_sel_hi:[1,0]
	s_and_b64 vcc, exec, s[4:5]
	ds_write2_b32 v38, v34, v35 offset0:2 offset1:3
	s_cbranch_vccnz .LBB0_89
	v_readlane_b32 s72, v254, 10
	v_readlane_b32 s82, v254, 20
	v_readlane_b32 s83, v254, 21
	s_nop 4
	v_add_u32_e32 v35, v80, v102
	v_readlane_b32 s73, v254, 11
	v_readlane_b32 s74, v254, 12
	v_readlane_b32 s75, v254, 13
	v_readlane_b32 s76, v254, 14
	v_readlane_b32 s77, v254, 15
	v_readlane_b32 s78, v254, 16
	v_readlane_b32 s79, v254, 17
	v_readlane_b32 s80, v254, 18
	v_readlane_b32 s81, v254, 19
	v_readlane_b32 s84, v254, 22
	v_readlane_b32 s85, v254, 23
	v_readlane_b32 s86, v254, 24
	v_readlane_b32 s87, v254, 25
	s_waitcnt vmcnt(1)
	v_pk_mul_f32 v[38:39], v[30:31], v[204:205] op_sel_hi:[1,0]
	v_pk_mul_f32 v[36:37], v[32:33], v[204:205] op_sel_hi:[1,0]
	ds_write2_b32 v35, v38, v39 offset1:1
	ds_write2_b32 v35, v36, v37 offset0:2 offset1:3
	s_cbranch_execnz .LBB0_51
.LBB0_50:
	s_waitcnt vmcnt(0)
	v_add_u32_e32 v34, v80, v102
	ds_write2_b32 v34, v30, v31 offset1:1
	ds_write2_b32 v34, v32, v33 offset0:2 offset1:3
	v_mov_b32_e32 v206, 1.0
.LBB0_51:
	s_waitcnt vmcnt(0)
	v_pk_mul_f32 v[26:27], v[26:27], v[206:207] op_sel_hi:[1,0]
	v_add_u32_e32 v30, v80, v103
	ds_write2_b32 v30, v26, v27 offset1:1
	v_pk_mul_f32 v[26:27], v[28:29], v[206:207] op_sel_hi:[1,0]
	s_and_b64 vcc, exec, s[4:5]
	ds_write2_b32 v30, v26, v27 offset0:2 offset1:3
	s_cbranch_vccnz .LBB0_90
	v_readlane_b32 s72, v254, 10
	v_readlane_b32 s82, v254, 20
	v_readlane_b32 s83, v254, 21
	s_nop 4
	v_add_u32_e32 v27, v80, v104
	v_readlane_b32 s73, v254, 11
	v_readlane_b32 s74, v254, 12
	v_readlane_b32 s75, v254, 13
	v_readlane_b32 s76, v254, 14
	v_readlane_b32 s77, v254, 15
	v_readlane_b32 s78, v254, 16
	v_readlane_b32 s79, v254, 17
	v_readlane_b32 s80, v254, 18
	v_readlane_b32 s81, v254, 19
	v_readlane_b32 s84, v254, 22
	v_readlane_b32 s85, v254, 23
	v_readlane_b32 s86, v254, 24
	v_readlane_b32 s87, v254, 25
	s_waitcnt vmcnt(1)
	v_pk_mul_f32 v[30:31], v[22:23], v[208:209] op_sel_hi:[1,0]
	v_pk_mul_f32 v[28:29], v[24:25], v[208:209] op_sel_hi:[1,0]
	ds_write2_b32 v27, v30, v31 offset1:1
	ds_write2_b32 v27, v28, v29 offset0:2 offset1:3
	s_cbranch_execnz .LBB0_54
.LBB0_53:
	s_waitcnt vmcnt(0)
	v_add_u32_e32 v26, v80, v104
	ds_write2_b32 v26, v22, v23 offset1:1
	ds_write2_b32 v26, v24, v25 offset0:2 offset1:3
	v_mov_b32_e32 v210, 1.0
.LBB0_54:
	s_waitcnt vmcnt(0)
	v_pk_mul_f32 v[22:23], v[18:19], v[210:211] op_sel_hi:[1,0]
	v_add_u32_e32 v19, v80, v104
	v_add_u32_e32 v18, 0x410, v19
	ds_write2_b32 v18, v22, v23 offset1:1
	v_pk_mul_f32 v[20:21], v[20:21], v[210:211] op_sel_hi:[1,0]
	v_add_u32_e32 v18, 0x418, v19
	ds_write2_b32 v18, v20, v21 offset1:1
	s_and_b64 vcc, exec, s[4:5]
	v_add_u32_e32 v20, 0x820, v19
	v_add_u32_e32 v21, 0x828, v19
	s_cbranch_vccnz .LBB0_91
	v_readlane_b32 s72, v254, 10
	v_readlane_b32 s82, v254, 20
	v_readlane_b32 s83, v254, 21
	s_nop 4
	v_readlane_b32 s73, v254, 11
	v_readlane_b32 s74, v254, 12
	v_readlane_b32 s75, v254, 13
	v_readlane_b32 s76, v254, 14
	v_readlane_b32 s77, v254, 15
	v_readlane_b32 s78, v254, 16
	v_readlane_b32 s79, v254, 17
	v_readlane_b32 s80, v254, 18
	v_readlane_b32 s81, v254, 19
	v_readlane_b32 s84, v254, 22
	v_readlane_b32 s85, v254, 23
	v_readlane_b32 s86, v254, 24
	v_readlane_b32 s87, v254, 25
	s_waitcnt vmcnt(1)
	v_pk_mul_f32 v[24:25], v[14:15], v[212:213] op_sel_hi:[1,0]
	v_pk_mul_f32 v[22:23], v[16:17], v[212:213] op_sel_hi:[1,0]
	ds_write2_b32 v20, v24, v25 offset1:1
	ds_write2_b32 v21, v22, v23 offset1:1
	s_cbranch_execnz .LBB0_57
.LBB0_56:
	s_waitcnt vmcnt(0)
	v_mov_b32_e32 v214, 1.0
	ds_write2_b32 v20, v14, v15 offset1:1
	ds_write2_b32 v21, v16, v17 offset1:1
.LBB0_57:
	s_waitcnt vmcnt(0)
	v_pk_mul_f32 v[10:11], v[10:11], v[214:215] op_sel_hi:[1,0]
	v_add_u32_e32 v14, 0xc30, v19
	ds_write2_b32 v14, v10, v11 offset1:1
	v_pk_mul_f32 v[10:11], v[12:13], v[214:215] op_sel_hi:[1,0]
	v_add_u32_e32 v12, 0xc38, v19
	ds_write2_b32 v12, v10, v11 offset1:1
	s_and_b64 vcc, exec, s[4:5]
	v_add_u32_e32 v11, 0x1040, v19
	v_add_u32_e32 v12, 0x1048, v19
	s_cbranch_vccnz .LBB0_92
	v_readlane_b32 s72, v254, 10
	v_readlane_b32 s82, v254, 20
	v_readlane_b32 s83, v254, 21
	s_nop 4
	v_readlane_b32 s73, v254, 11
	v_readlane_b32 s74, v254, 12
	v_readlane_b32 s75, v254, 13
	v_readlane_b32 s76, v254, 14
	v_readlane_b32 s77, v254, 15
	v_readlane_b32 s78, v254, 16
	v_readlane_b32 s79, v254, 17
	v_readlane_b32 s80, v254, 18
	v_readlane_b32 s81, v254, 19
	v_readlane_b32 s84, v254, 22
	v_readlane_b32 s85, v254, 23
	v_readlane_b32 s86, v254, 24
	v_readlane_b32 s87, v254, 25
	s_waitcnt vmcnt(1)
	v_pk_mul_f32 v[16:17], v[6:7], v[216:217] op_sel_hi:[1,0]
	v_pk_mul_f32 v[14:15], v[8:9], v[216:217] op_sel_hi:[1,0]
	ds_write2_b32 v11, v16, v17 offset1:1
	ds_write2_b32 v12, v14, v15 offset1:1
	s_cbranch_execnz .LBB0_60
.LBB0_59:
	s_waitcnt vmcnt(0)
	v_mov_b32_e32 v218, 1.0
	ds_write2_b32 v11, v6, v7 offset1:1
	ds_write2_b32 v12, v8, v9 offset1:1
.LBB0_60:
	s_waitcnt vmcnt(0)
	v_pk_mul_f32 v[2:3], v[2:3], v[218:219] op_sel_hi:[1,0]
	v_add_u32_e32 v6, 0x1450, v19
	s_lshl_b32 s8, s30, 6
	ds_write2_b32 v6, v2, v3 offset1:1
	v_pk_mul_f32 v[2:3], v[4:5], v[218:219] op_sel_hi:[1,0]
	v_add_u32_e32 v4, 0x1458, v19
	s_and_b32 s8, 0xffff, s8
	ds_write2_b32 v4, v2, v3 offset1:1
	s_lshl_b32 s9, s8, 1
	s_waitcnt lgkmcnt(0)
	s_and_b32 s8, s8, 64
	s_and_b32 s9, s9, 0x1f00
	s_or_b32 s28, s8, s9
	ds_read2_b32 v[2:3], v83 offset1:65
	s_bitset1_b32 s28, 7
	s_waitcnt lgkmcnt(0)
	v_cvt_pk_bf16_f32 v2, v2, v3
	ds_read2_b32 v[4:5], v83 offset0:130 offset1:195
	v_add_u32_e32 v12, 0x400, v83
	s_lshl_b32 s26, s2, 1
	v_or_b32_e32 v10, s28, v82
	s_waitcnt lgkmcnt(0)
	v_cvt_pk_bf16_f32 v3, v4, v5
	ds_read2_b32 v[4:5], v12 offset0:4 offset1:69
	v_lshl_add_u64 v[8:9], v[72:73], 0, s[26:27]
	v_lshlrev_b32_e32 v70, 11, v10
	s_waitcnt lgkmcnt(0)
	v_cvt_pk_bf16_f32 v4, v4, v5
	ds_read2_b32 v[6:7], v12 offset0:134 offset1:199
	s_waitcnt lgkmcnt(0)
	v_cvt_pk_bf16_f32 v5, v6, v7
	v_lshl_add_u64 v[10:11], v[8:9], 0, v[70:71]
	ds_read2_b32 v[6:7], v83 offset0:8 offset1:73
	global_store_dwordx4 v[10:11], v[2:5], off
	v_or_b32_e32 v10, s28, v88
	v_lshlrev_b32_e32 v70, 11, v10
	s_waitcnt lgkmcnt(0)
	v_cvt_pk_bf16_f32 v2, v6, v7
	ds_read2_b32 v[4:5], v83 offset0:138 offset1:203
	s_waitcnt lgkmcnt(0)
	v_cvt_pk_bf16_f32 v3, v4, v5
	ds_read2_b32 v[4:5], v12 offset0:12 offset1:77
	s_waitcnt lgkmcnt(0)
	v_cvt_pk_bf16_f32 v4, v4, v5
	ds_read2_b32 v[6:7], v12 offset0:142 offset1:207
	s_waitcnt lgkmcnt(0)
	v_cvt_pk_bf16_f32 v5, v6, v7
	v_lshl_add_u64 v[10:11], v[8:9], 0, v[70:71]
	ds_read2_b32 v[6:7], v83 offset0:16 offset1:81
	global_store_dwordx4 v[10:11], v[2:5], off
	v_or_b32_e32 v10, s28, v89
	v_lshlrev_b32_e32 v70, 11, v10
	s_waitcnt lgkmcnt(0)
	v_cvt_pk_bf16_f32 v2, v6, v7
	ds_read2_b32 v[4:5], v83 offset0:146 offset1:211
	s_waitcnt lgkmcnt(0)
	v_cvt_pk_bf16_f32 v3, v4, v5
	ds_read2_b32 v[4:5], v12 offset0:20 offset1:85
	s_waitcnt lgkmcnt(0)
	v_cvt_pk_bf16_f32 v4, v4, v5
	ds_read2_b32 v[6:7], v12 offset0:150 offset1:215
	s_waitcnt lgkmcnt(0)
	v_cvt_pk_bf16_f32 v5, v6, v7
	v_lshl_add_u64 v[10:11], v[8:9], 0, v[70:71]
	ds_read2_b32 v[6:7], v83 offset0:24 offset1:89
	global_store_dwordx4 v[10:11], v[2:5], off
	v_or_b32_e32 v10, s28, v90
	v_lshlrev_b32_e32 v70, 11, v10
	s_waitcnt lgkmcnt(0)
	v_cvt_pk_bf16_f32 v2, v6, v7
	ds_read2_b32 v[4:5], v83 offset0:154 offset1:219
	s_waitcnt lgkmcnt(0)
	v_cvt_pk_bf16_f32 v3, v4, v5
	ds_read2_b32 v[4:5], v12 offset0:28 offset1:93
	s_waitcnt lgkmcnt(0)
	v_cvt_pk_bf16_f32 v4, v4, v5
	ds_read2_b32 v[6:7], v12 offset0:158 offset1:223
	s_waitcnt lgkmcnt(0)
	v_cvt_pk_bf16_f32 v5, v6, v7
	v_lshl_add_u64 v[10:11], v[8:9], 0, v[70:71]
	ds_read2_b32 v[6:7], v83 offset0:32 offset1:97
	global_store_dwordx4 v[10:11], v[2:5], off
	v_or_b32_e32 v10, s28, v91
	v_lshlrev_b32_e32 v70, 11, v10
	s_waitcnt lgkmcnt(0)
	v_cvt_pk_bf16_f32 v2, v6, v7
	ds_read2_b32 v[4:5], v83 offset0:162 offset1:227
	s_waitcnt lgkmcnt(0)
	v_cvt_pk_bf16_f32 v3, v4, v5
	ds_read2_b32 v[4:5], v12 offset0:36 offset1:101
	s_waitcnt lgkmcnt(0)
	v_cvt_pk_bf16_f32 v4, v4, v5
	ds_read2_b32 v[6:7], v12 offset0:166 offset1:231
	s_waitcnt lgkmcnt(0)
	v_cvt_pk_bf16_f32 v5, v6, v7
	v_lshl_add_u64 v[10:11], v[8:9], 0, v[70:71]
	ds_read2_b32 v[6:7], v83 offset0:40 offset1:105
	global_store_dwordx4 v[10:11], v[2:5], off
	v_or_b32_e32 v10, s28, v92
	v_lshlrev_b32_e32 v70, 11, v10
	s_waitcnt lgkmcnt(0)
	v_cvt_pk_bf16_f32 v2, v6, v7
	ds_read2_b32 v[4:5], v83 offset0:170 offset1:235
	s_waitcnt lgkmcnt(0)
	v_cvt_pk_bf16_f32 v3, v4, v5
	ds_read2_b32 v[4:5], v12 offset0:44 offset1:109
	s_waitcnt lgkmcnt(0)
	v_cvt_pk_bf16_f32 v4, v4, v5
	ds_read2_b32 v[6:7], v12 offset0:174 offset1:239
	s_waitcnt lgkmcnt(0)
	v_cvt_pk_bf16_f32 v5, v6, v7
	v_lshl_add_u64 v[10:11], v[8:9], 0, v[70:71]
	ds_read2_b32 v[6:7], v83 offset0:48 offset1:113
	global_store_dwordx4 v[10:11], v[2:5], off
	v_or_b32_e32 v10, s28, v93
	v_lshlrev_b32_e32 v70, 11, v10
	s_waitcnt lgkmcnt(0)
	v_cvt_pk_bf16_f32 v2, v6, v7
	ds_read2_b32 v[4:5], v83 offset0:178 offset1:243
	s_waitcnt lgkmcnt(0)
	v_cvt_pk_bf16_f32 v3, v4, v5
	ds_read2_b32 v[4:5], v12 offset0:52 offset1:117
	s_waitcnt lgkmcnt(0)
	v_cvt_pk_bf16_f32 v4, v4, v5
	ds_read2_b32 v[6:7], v12 offset0:182 offset1:247
	s_waitcnt lgkmcnt(0)
	v_cvt_pk_bf16_f32 v5, v6, v7
	v_lshl_add_u64 v[10:11], v[8:9], 0, v[70:71]
	ds_read2_b32 v[6:7], v83 offset0:56 offset1:121
	global_store_dwordx4 v[10:11], v[2:5], off
	s_waitcnt lgkmcnt(0)
	s_nop 0
	v_cvt_pk_bf16_f32 v2, v6, v7
	ds_read2_b32 v[4:5], v83 offset0:186 offset1:251
	s_waitcnt lgkmcnt(0)
	v_cvt_pk_bf16_f32 v3, v4, v5
	ds_read2_b32 v[4:5], v12 offset0:60 offset1:125
	s_waitcnt lgkmcnt(0)
	v_cvt_pk_bf16_f32 v4, v4, v5
	v_or_b32_e32 v5, s28, v94
	ds_read2_b32 v[6:7], v12 offset0:190 offset1:255
	v_lshlrev_b32_e32 v70, 11, v5
	s_waitcnt lgkmcnt(0)
	v_cvt_pk_bf16_f32 v5, v6, v7
	v_lshl_add_u64 v[6:7], v[8:9], 0, v[70:71]
	global_store_dwordx4 v[6:7], v[2:5], off
	s_waitcnt lgkmcnt(0)
	s_mov_b64 s[28:29], 0

.LBB0_461:
	s_lshl_b32 s0, s2, 6
	s_and_b32 s24, s0, 0xffc0
	v_or_b32_e32 v107, s24, v66
	s_lshl_b32 s12, s10, 2
	s_waitcnt vmcnt(0)
	v_mul_u32_u24_e32 v6, 0x1800, v107
	v_lshl_add_u64 v[2:3], v[92:93], 0, s[12:13]
	s_movk_i32 s0, 0x6000
	v_lshlrev_b32_e32 v68, 2, v6
	v_mad_u64_u32 v[4:5], s[0:1], v107, s0, v[2:3]
	v_lshl_add_u64 v[2:3], v[2:3], 0, v[68:69]
	v_add_co_u32_e32 v6, vcc, 0x18000, v2
	v_cndmask_b32_e64 v68, 0, 1, s[4:5]
	s_nop 0
	v_addc_co_u32_e32 v7, vcc, 0, v3, vcc
	global_load_dwordx4 v[62:65], v[4:5], off nt
	global_load_dwordx4 v[58:61], v[6:7], off nt
	v_add_co_u32_e32 v4, vcc, 0x30000, v2
	v_cmp_ne_u32_e64 s[0:1], 1, v68
	s_nop 0
	v_addc_co_u32_e32 v5, vcc, 0, v3, vcc
	v_add_co_u32_e32 v6, vcc, 0x48000, v2
	v_add_lshl_u32 v106, v66, s24, 2
	s_nop 0
	v_addc_co_u32_e32 v7, vcc, 0, v3, vcc
	global_load_dwordx4 v[54:57], v[4:5], off nt
	global_load_dwordx4 v[50:53], v[6:7], off nt
	v_add_co_u32_e32 v4, vcc, 0x60000, v2
	s_nop 1
	v_addc_co_u32_e32 v5, vcc, 0, v3, vcc
	v_add_co_u32_e32 v6, vcc, 0x78000, v2
	s_nop 1
	v_addc_co_u32_e32 v7, vcc, 0, v3, vcc
	global_load_dwordx4 v[46:49], v[4:5], off nt
	global_load_dwordx4 v[42:45], v[6:7], off nt
	v_add_co_u32_e32 v4, vcc, 0x90000, v2
	s_nop 1
	v_addc_co_u32_e32 v5, vcc, 0, v3, vcc
	v_add_co_u32_e32 v6, vcc, 0xa8000, v2
	s_nop 1
	v_addc_co_u32_e32 v7, vcc, 0, v3, vcc
	global_load_dwordx4 v[38:41], v[4:5], off nt
	global_load_dwordx4 v[34:37], v[6:7], off nt
	v_add_co_u32_e32 v4, vcc, 0xc0000, v2
	s_nop 1
	v_addc_co_u32_e32 v5, vcc, 0, v3, vcc
	v_add_co_u32_e32 v6, vcc, 0xd8000, v2
	s_nop 1
	v_addc_co_u32_e32 v7, vcc, 0, v3, vcc
	global_load_dwordx4 v[30:33], v[4:5], off nt
	global_load_dwordx4 v[26:29], v[6:7], off nt
	v_add_co_u32_e32 v4, vcc, 0xf0000, v2
	s_nop 1
	v_addc_co_u32_e32 v5, vcc, 0, v3, vcc
	v_add_co_u32_e32 v6, vcc, 0x108000, v2
	s_nop 1
	v_addc_co_u32_e32 v7, vcc, 0, v3, vcc
	global_load_dwordx4 v[22:25], v[4:5], off nt
	global_load_dwordx4 v[18:21], v[6:7], off nt
	v_add_co_u32_e32 v4, vcc, 0x120000, v2
	s_nop 1
	v_addc_co_u32_e32 v5, vcc, 0, v3, vcc
	v_add_co_u32_e32 v6, vcc, 0x138000, v2
	s_nop 1
	v_addc_co_u32_e32 v7, vcc, 0, v3, vcc
	global_load_dwordx4 v[14:17], v[4:5], off nt
	global_load_dwordx4 v[10:13], v[6:7], off nt
	v_add_co_u32_e32 v4, vcc, 0x150000, v2
	s_nop 1
	v_addc_co_u32_e32 v5, vcc, 0, v3, vcc
	v_add_co_u32_e32 v2, vcc, 0x168000, v2
	s_nop 1
	v_addc_co_u32_e32 v3, vcc, 0, v3, vcc
	global_load_dwordx4 v[6:9], v[4:5], off nt
	s_nop 0
	global_load_dwordx4 v[2:5], v[2:3], off nt
	s_andn2_b64 vcc, exec, s[4:5]
	s_cbranch_vccnz .LBB0_608
	v_readlane_b32 s72, v254, 29
	v_lshlrev_b32_e32 v68, 2, v107
	v_readlane_b32 s74, v254, 31
	v_readlane_b32 s75, v254, 32
	v_readlane_b32 s73, v254, 30
	v_readlane_b32 s76, v254, 33
	v_readlane_b32 s77, v254, 34
	v_readlane_b32 s78, v254, 35
	s_nop 0
	global_load_dword v188, v68, s[74:75]
	global_load_dword v190, v106, s[74:75] offset:16
	global_load_dword v192, v106, s[74:75] offset:32
	global_load_dword v194, v106, s[74:75] offset:48
	global_load_dword v196, v106, s[74:75] offset:64
	global_load_dword v198, v106, s[74:75] offset:80
	global_load_dword v200, v106, s[74:75] offset:96
	global_load_dword v202, v106, s[74:75] offset:112
	global_load_dword v204, v106, s[74:75] offset:128
	global_load_dword v206, v106, s[74:75] offset:144
	global_load_dword v208, v106, s[74:75] offset:160
	global_load_dword v210, v106, s[74:75] offset:176
	global_load_dword v212, v106, s[74:75] offset:192
	global_load_dword v214, v106, s[74:75] offset:208
	global_load_dword v216, v106, s[74:75] offset:224
	global_load_dword v218, v106, s[74:75] offset:240
	v_readlane_b32 s79, v254, 36
	v_readlane_b32 s80, v254, 37
	v_readlane_b32 s81, v254, 38
	v_readlane_b32 s82, v254, 39
	v_readlane_b32 s83, v254, 40
	v_readlane_b32 s84, v254, 41
	v_readlane_b32 s85, v254, 42
	v_readlane_b32 s86, v254, 43
	v_readlane_b32 s87, v254, 44
	s_waitcnt vmcnt(0)
	v_pk_mul_f32 v[130:131], v[62:63], v[188:189] op_sel_hi:[1,0]
	ds_write2_b32 v109, v130, v131 offset1:1
	v_pk_mul_f32 v[130:131], v[64:65], v[188:189] op_sel_hi:[1,0]
	ds_write2_b32 v109, v130, v131 offset0:2 offset1:3
	s_cbranch_execnz .LBB0_464
.LBB0_463:
	s_waitcnt vmcnt(0)
	v_mov_b32_e32 v190, 1.0
	ds_write2_b32 v109, v62, v63 offset1:1
	ds_write2_b32 v109, v64, v65 offset0:2 offset1:3
.LBB0_464:
	s_waitcnt vmcnt(0)
	v_pk_mul_f32 v[58:59], v[58:59], v[190:191] op_sel_hi:[1,0]
	v_add_u32_e32 v62, v108, v119
	ds_write2_b32 v62, v58, v59 offset1:1
	v_pk_mul_f32 v[58:59], v[60:61], v[190:191] op_sel_hi:[1,0]
	s_and_b64 vcc, exec, s[0:1]
	ds_write2_b32 v62, v58, v59 offset0:2 offset1:3
	s_cbranch_vccnz .LBB0_609
	v_readlane_b32 s72, v254, 29
	v_readlane_b32 s74, v254, 31
	v_readlane_b32 s75, v254, 32
	v_add_u32_e32 v62, v108, v120
	v_readlane_b32 s73, v254, 30
	v_readlane_b32 s76, v254, 33
	v_readlane_b32 s77, v254, 34
	s_nop 0
	v_readlane_b32 s78, v254, 35
	v_readlane_b32 s79, v254, 36
	v_readlane_b32 s80, v254, 37
	v_readlane_b32 s81, v254, 38
	v_readlane_b32 s82, v254, 39
	v_readlane_b32 s83, v254, 40
	v_readlane_b32 s84, v254, 41
	v_readlane_b32 s85, v254, 42
	v_readlane_b32 s86, v254, 43
	v_readlane_b32 s87, v254, 44
	s_waitcnt vmcnt(0)
	v_pk_mul_f32 v[60:61], v[54:55], v[192:193] op_sel_hi:[1,0]
	v_pk_mul_f32 v[58:59], v[56:57], v[192:193] op_sel_hi:[1,0]
	ds_write2_b32 v62, v58, v59 offset0:2 offset1:3
	ds_write2_b32 v62, v60, v61 offset1:1
	s_cbranch_execnz .LBB0_467
.LBB0_466:
	s_waitcnt vmcnt(0)
	v_add_u32_e32 v58, v108, v120
	ds_write2_b32 v58, v54, v55 offset1:1
	ds_write2_b32 v58, v56, v57 offset0:2 offset1:3
	v_mov_b32_e32 v194, 1.0
.LBB0_467:
	s_waitcnt vmcnt(0)
	v_pk_mul_f32 v[50:51], v[50:51], v[194:195] op_sel_hi:[1,0]
	v_add_u32_e32 v54, v108, v121
	ds_write2_b32 v54, v50, v51 offset1:1
	v_pk_mul_f32 v[50:51], v[52:53], v[194:195] op_sel_hi:[1,0]
	s_and_b64 vcc, exec, s[0:1]
	ds_write2_b32 v54, v50, v51 offset0:2 offset1:3
	s_cbranch_vccnz .LBB0_610
	v_readlane_b32 s72, v254, 29
	v_readlane_b32 s74, v254, 31
	v_readlane_b32 s75, v254, 32
	v_add_u32_e32 v54, v108, v122
	v_readlane_b32 s73, v254, 30
	v_readlane_b32 s76, v254, 33
	v_readlane_b32 s77, v254, 34
	s_nop 0
	v_readlane_b32 s78, v254, 35
	v_readlane_b32 s79, v254, 36
	v_readlane_b32 s80, v254, 37
	v_readlane_b32 s81, v254, 38
	v_readlane_b32 s82, v254, 39
	v_readlane_b32 s83, v254, 40
	v_readlane_b32 s84, v254, 41
	v_readlane_b32 s85, v254, 42
	v_readlane_b32 s86, v254, 43
	v_readlane_b32 s87, v254, 44
	s_waitcnt vmcnt(0)
	v_pk_mul_f32 v[52:53], v[46:47], v[196:197] op_sel_hi:[1,0]
	v_pk_mul_f32 v[50:51], v[48:49], v[196:197] op_sel_hi:[1,0]
	ds_write2_b32 v54, v50, v51 offset0:2 offset1:3
	ds_write2_b32 v54, v52, v53 offset1:1
	s_cbranch_execnz .LBB0_470
.LBB0_469:
	s_waitcnt vmcnt(0)
	v_add_u32_e32 v50, v108, v122
	ds_write2_b32 v50, v46, v47 offset1:1
	ds_write2_b32 v50, v48, v49 offset0:2 offset1:3
	v_mov_b32_e32 v198, 1.0
.LBB0_470:
	s_waitcnt vmcnt(0)
	v_pk_mul_f32 v[42:43], v[42:43], v[198:199] op_sel_hi:[1,0]
	v_add_u32_e32 v46, v108, v123
	ds_write2_b32 v46, v42, v43 offset1:1
	v_pk_mul_f32 v[42:43], v[44:45], v[198:199] op_sel_hi:[1,0]
	s_and_b64 vcc, exec, s[0:1]
	ds_write2_b32 v46, v42, v43 offset0:2 offset1:3
	s_cbranch_vccnz .LBB0_611
	v_readlane_b32 s72, v254, 29
	v_readlane_b32 s74, v254, 31
	v_readlane_b32 s75, v254, 32
	v_add_u32_e32 v46, v108, v124
	v_readlane_b32 s73, v254, 30
	v_readlane_b32 s76, v254, 33
	v_readlane_b32 s77, v254, 34
	s_nop 0
	v_readlane_b32 s78, v254, 35
	v_readlane_b32 s79, v254, 36
	v_readlane_b32 s80, v254, 37
	v_readlane_b32 s81, v254, 38
	v_readlane_b32 s82, v254, 39
	v_readlane_b32 s83, v254, 40
	v_readlane_b32 s84, v254, 41
	v_readlane_b32 s85, v254, 42
	v_readlane_b32 s86, v254, 43
	v_readlane_b32 s87, v254, 44
	s_waitcnt vmcnt(0)
	v_pk_mul_f32 v[44:45], v[38:39], v[200:201] op_sel_hi:[1,0]
	v_pk_mul_f32 v[42:43], v[40:41], v[200:201] op_sel_hi:[1,0]
	ds_write2_b32 v46, v42, v43 offset0:2 offset1:3
	ds_write2_b32 v46, v44, v45 offset1:1
	s_cbranch_execnz .LBB0_473
.LBB0_472:
	s_waitcnt vmcnt(0)
	v_add_u32_e32 v42, v108, v124
	ds_write2_b32 v42, v38, v39 offset1:1
	ds_write2_b32 v42, v40, v41 offset0:2 offset1:3
	v_mov_b32_e32 v202, 1.0
.LBB0_473:
	s_waitcnt vmcnt(0)
	v_pk_mul_f32 v[34:35], v[34:35], v[202:203] op_sel_hi:[1,0]
	v_add_u32_e32 v38, v108, v125
	ds_write2_b32 v38, v34, v35 offset1:1
	v_pk_mul_f32 v[34:35], v[36:37], v[202:203] op_sel_hi:[1,0]
	s_and_b64 vcc, exec, s[0:1]
	ds_write2_b32 v38, v34, v35 offset0:2 offset1:3
	s_cbranch_vccnz .LBB0_612
	v_readlane_b32 s72, v254, 29
	v_readlane_b32 s74, v254, 31
	v_readlane_b32 s75, v254, 32
	v_add_u32_e32 v38, v108, v126
	v_readlane_b32 s73, v254, 30
	v_readlane_b32 s76, v254, 33
	v_readlane_b32 s77, v254, 34
	s_nop 0
	v_readlane_b32 s78, v254, 35
	v_readlane_b32 s79, v254, 36
	v_readlane_b32 s80, v254, 37
	v_readlane_b32 s81, v254, 38
	v_readlane_b32 s82, v254, 39
	v_readlane_b32 s83, v254, 40
	v_readlane_b32 s84, v254, 41
	v_readlane_b32 s85, v254, 42
	v_readlane_b32 s86, v254, 43
	v_readlane_b32 s87, v254, 44
	s_waitcnt vmcnt(0)
	v_pk_mul_f32 v[36:37], v[30:31], v[204:205] op_sel_hi:[1,0]
	v_pk_mul_f32 v[34:35], v[32:33], v[204:205] op_sel_hi:[1,0]
	ds_write2_b32 v38, v34, v35 offset0:2 offset1:3
	ds_write2_b32 v38, v36, v37 offset1:1
	s_cbranch_execnz .LBB0_476
.LBB0_475:
	s_waitcnt vmcnt(0)
	v_add_u32_e32 v34, v108, v126
	ds_write2_b32 v34, v30, v31 offset1:1
	ds_write2_b32 v34, v32, v33 offset0:2 offset1:3
	v_mov_b32_e32 v206, 1.0
.LBB0_476:
	s_waitcnt vmcnt(0)
	v_pk_mul_f32 v[26:27], v[26:27], v[206:207] op_sel_hi:[1,0]
	v_add_u32_e32 v30, v108, v127
	ds_write2_b32 v30, v26, v27 offset1:1
	v_pk_mul_f32 v[26:27], v[28:29], v[206:207] op_sel_hi:[1,0]
	s_and_b64 vcc, exec, s[0:1]
	ds_write2_b32 v30, v26, v27 offset0:2 offset1:3
	s_cbranch_vccnz .LBB0_613
	v_readlane_b32 s72, v254, 29
	v_readlane_b32 s74, v254, 31
	v_readlane_b32 s75, v254, 32
	v_add_u32_e32 v30, v108, v128
	v_readlane_b32 s73, v254, 30
	v_readlane_b32 s76, v254, 33
	v_readlane_b32 s77, v254, 34
	s_nop 0
	v_readlane_b32 s78, v254, 35
	v_readlane_b32 s79, v254, 36
	v_readlane_b32 s80, v254, 37
	v_readlane_b32 s81, v254, 38
	v_readlane_b32 s82, v254, 39
	v_readlane_b32 s83, v254, 40
	v_readlane_b32 s84, v254, 41
	v_readlane_b32 s85, v254, 42
	v_readlane_b32 s86, v254, 43
	v_readlane_b32 s87, v254, 44
	s_waitcnt vmcnt(0)
	v_pk_mul_f32 v[28:29], v[22:23], v[208:209] op_sel_hi:[1,0]
	v_pk_mul_f32 v[26:27], v[24:25], v[208:209] op_sel_hi:[1,0]
	ds_write2_b32 v30, v26, v27 offset0:2 offset1:3
	ds_write2_b32 v30, v28, v29 offset1:1
	s_cbranch_execnz .LBB0_479
.LBB0_478:
	s_waitcnt vmcnt(0)
	v_add_u32_e32 v26, v108, v128
	ds_write2_b32 v26, v22, v23 offset1:1
	ds_write2_b32 v26, v24, v25 offset0:2 offset1:3
	v_mov_b32_e32 v210, 1.0
.LBB0_479:
	s_waitcnt vmcnt(0)
	v_pk_mul_f32 v[22:23], v[18:19], v[210:211] op_sel_hi:[1,0]
	v_add_u32_e32 v19, v108, v129
	v_pk_mul_f32 v[20:21], v[20:21], v[210:211] op_sel_hi:[1,0]
	ds_write2_b32 v19, v20, v21 offset0:2 offset1:3
	s_and_b64 vcc, exec, s[0:1]
	v_add_u32_e32 v20, 0x410, v19
	v_add_u32_e32 v21, 0x418, v19
	ds_write2_b32 v19, v22, v23 offset1:1
	s_cbranch_vccnz .LBB0_614
	v_readlane_b32 s72, v254, 29
	v_readlane_b32 s74, v254, 31
	v_readlane_b32 s75, v254, 32
	v_readlane_b32 s73, v254, 30
	v_readlane_b32 s76, v254, 33
	v_readlane_b32 s77, v254, 34
	v_readlane_b32 s78, v254, 35
	s_nop 0
	v_readlane_b32 s79, v254, 36
	v_readlane_b32 s80, v254, 37
	v_readlane_b32 s81, v254, 38
	v_readlane_b32 s82, v254, 39
	v_readlane_b32 s83, v254, 40
	v_readlane_b32 s84, v254, 41
	v_readlane_b32 s85, v254, 42
	v_readlane_b32 s86, v254, 43
	v_readlane_b32 s87, v254, 44
	s_waitcnt vmcnt(0)
	v_pk_mul_f32 v[22:23], v[14:15], v[212:213] op_sel_hi:[1,0]
	ds_write2_b32 v20, v22, v23 offset1:1
	v_pk_mul_f32 v[22:23], v[16:17], v[212:213] op_sel_hi:[1,0]
	ds_write2_b32 v21, v22, v23 offset1:1
	s_cbranch_execnz .LBB0_482

.LBB0_482:
	s_waitcnt vmcnt(0)
	v_pk_mul_f32 v[10:11], v[10:11], v[214:215] op_sel_hi:[1,0]
	v_add_u32_e32 v14, 0x820, v19
	ds_write2_b32 v14, v10, v11 offset1:1
	v_pk_mul_f32 v[10:11], v[12:13], v[214:215] op_sel_hi:[1,0]
	v_add_u32_e32 v12, 0x828, v19
	ds_write2_b32 v12, v10, v11 offset1:1
	s_and_b64 vcc, exec, s[0:1]
	v_add_u32_e32 v11, 0xc30, v19
	v_add_u32_e32 v12, 0xc38, v19
	s_cbranch_vccnz .LBB0_615
	v_readlane_b32 s72, v254, 29
	v_readlane_b32 s74, v254, 31
	v_readlane_b32 s75, v254, 32
	v_readlane_b32 s73, v254, 30
	v_readlane_b32 s76, v254, 33
	v_readlane_b32 s77, v254, 34
	v_readlane_b32 s78, v254, 35
	s_nop 0
	v_readlane_b32 s79, v254, 36
	v_readlane_b32 s80, v254, 37
	v_readlane_b32 s81, v254, 38
	v_readlane_b32 s82, v254, 39
	v_readlane_b32 s83, v254, 40
	v_readlane_b32 s84, v254, 41
	v_readlane_b32 s85, v254, 42
	v_readlane_b32 s86, v254, 43
	v_readlane_b32 s87, v254, 44
	s_waitcnt vmcnt(0)
	v_pk_mul_f32 v[14:15], v[6:7], v[216:217] op_sel_hi:[1,0]
	ds_write2_b32 v11, v14, v15 offset1:1
	v_pk_mul_f32 v[14:15], v[8:9], v[216:217] op_sel_hi:[1,0]
	ds_write2_b32 v12, v14, v15 offset1:1
	s_cbranch_execnz .LBB0_485

.LBB0_485:
	s_waitcnt vmcnt(0)
	v_pk_mul_f32 v[2:3], v[2:3], v[218:219] op_sel_hi:[1,0]
	v_add_u32_e32 v6, 0x1040, v19
	ds_write2_b32 v6, v2, v3 offset1:1
	v_pk_mul_f32 v[2:3], v[4:5], v[218:219] op_sel_hi:[1,0]
	v_add_u32_e32 v4, 0x1048, v19
	ds_write2_b32 v4, v2, v3 offset1:1
	s_waitcnt lgkmcnt(0)
	ds_read2_b32 v[4:5], v111 offset1:65
	s_waitcnt lgkmcnt(0)
	v_cvt_pk_bf16_f32 v4, v4, v5
	ds_read2_b32 v[6:7], v111 offset0:130 offset1:195
	v_add_u32_e32 v10, 0x400, v111
	s_waitcnt lgkmcnt(0)
	v_cvt_pk_bf16_f32 v5, v6, v7
	ds_read2_b32 v[6:7], v10 offset0:4 offset1:69
	s_lshl_b32 s12, s24, 1
	s_waitcnt lgkmcnt(0)
	v_cvt_pk_bf16_f32 v6, v6, v7
	ds_read2_b32 v[8:9], v10 offset0:134 offset1:199
	v_add_u32_e32 v68, s3, v110
	v_lshl_add_u64 v[2:3], v[76:77], 0, s[12:13]
	s_waitcnt lgkmcnt(0)
	v_cvt_pk_bf16_f32 v7, v8, v9
	v_lshlrev_b64 v[8:9], 11, v[68:69]
	v_lshl_add_u64 v[8:9], v[2:3], 0, v[8:9]
	global_store_dwordx4 v[8:9], v[4:7], off
	ds_read2_b32 v[4:5], v111 offset0:8 offset1:73
	v_add_u32_e32 v68, s3, v112
	s_waitcnt lgkmcnt(0)
	v_cvt_pk_bf16_f32 v4, v4, v5
	ds_read2_b32 v[6:7], v111 offset0:138 offset1:203
	s_waitcnt lgkmcnt(0)
	v_cvt_pk_bf16_f32 v5, v6, v7
	ds_read2_b32 v[6:7], v10 offset0:12 offset1:77
	s_waitcnt lgkmcnt(0)
	v_cvt_pk_bf16_f32 v6, v6, v7
	ds_read2_b32 v[8:9], v10 offset0:142 offset1:207
	s_waitcnt lgkmcnt(0)
	v_cvt_pk_bf16_f32 v7, v8, v9
	v_lshlrev_b64 v[8:9], 11, v[68:69]
	v_lshl_add_u64 v[8:9], v[2:3], 0, v[8:9]
	global_store_dwordx4 v[8:9], v[4:7], off
	ds_read2_b32 v[4:5], v111 offset0:16 offset1:81
	v_add_u32_e32 v68, s3, v113
	s_waitcnt lgkmcnt(0)
	v_cvt_pk_bf16_f32 v4, v4, v5
	ds_read2_b32 v[6:7], v111 offset0:146 offset1:211
	s_waitcnt lgkmcnt(0)
	v_cvt_pk_bf16_f32 v5, v6, v7
	ds_read2_b32 v[6:7], v10 offset0:20 offset1:85
	s_waitcnt lgkmcnt(0)
	v_cvt_pk_bf16_f32 v6, v6, v7
	ds_read2_b32 v[8:9], v10 offset0:150 offset1:215
	s_waitcnt lgkmcnt(0)
	v_cvt_pk_bf16_f32 v7, v8, v9
	v_lshlrev_b64 v[8:9], 11, v[68:69]
	v_lshl_add_u64 v[8:9], v[2:3], 0, v[8:9]
	global_store_dwordx4 v[8:9], v[4:7], off
	ds_read2_b32 v[4:5], v111 offset0:24 offset1:89
	v_add_u32_e32 v68, s3, v114
	s_waitcnt lgkmcnt(0)
	v_cvt_pk_bf16_f32 v4, v4, v5
	ds_read2_b32 v[6:7], v111 offset0:154 offset1:219
	s_waitcnt lgkmcnt(0)
	v_cvt_pk_bf16_f32 v5, v6, v7
	ds_read2_b32 v[6:7], v10 offset0:28 offset1:93
	s_waitcnt lgkmcnt(0)
	v_cvt_pk_bf16_f32 v6, v6, v7
	ds_read2_b32 v[8:9], v10 offset0:158 offset1:223
	s_waitcnt lgkmcnt(0)
	v_cvt_pk_bf16_f32 v7, v8, v9
	v_lshlrev_b64 v[8:9], 11, v[68:69]
	v_lshl_add_u64 v[8:9], v[2:3], 0, v[8:9]
	global_store_dwordx4 v[8:9], v[4:7], off
	ds_read2_b32 v[4:5], v111 offset0:32 offset1:97
	v_add_u32_e32 v68, s3, v115
	s_waitcnt lgkmcnt(0)
	v_cvt_pk_bf16_f32 v4, v4, v5
	ds_read2_b32 v[6:7], v111 offset0:162 offset1:227
	s_waitcnt lgkmcnt(0)
	v_cvt_pk_bf16_f32 v5, v6, v7
	ds_read2_b32 v[6:7], v10 offset0:36 offset1:101
	s_waitcnt lgkmcnt(0)
	v_cvt_pk_bf16_f32 v6, v6, v7
	ds_read2_b32 v[8:9], v10 offset0:166 offset1:231
	s_waitcnt lgkmcnt(0)
	v_cvt_pk_bf16_f32 v7, v8, v9
	v_lshlrev_b64 v[8:9], 11, v[68:69]
	v_lshl_add_u64 v[8:9], v[2:3], 0, v[8:9]
	global_store_dwordx4 v[8:9], v[4:7], off
	ds_read2_b32 v[4:5], v111 offset0:40 offset1:105
	v_add_u32_e32 v68, s3, v116
	s_waitcnt lgkmcnt(0)
	v_cvt_pk_bf16_f32 v4, v4, v5
	ds_read2_b32 v[6:7], v111 offset0:170 offset1:235
	s_waitcnt lgkmcnt(0)
	v_cvt_pk_bf16_f32 v5, v6, v7
	ds_read2_b32 v[6:7], v10 offset0:44 offset1:109
	s_waitcnt lgkmcnt(0)
	v_cvt_pk_bf16_f32 v6, v6, v7
	ds_read2_b32 v[8:9], v10 offset0:174 offset1:239
	s_waitcnt lgkmcnt(0)
	v_cvt_pk_bf16_f32 v7, v8, v9
	v_lshlrev_b64 v[8:9], 11, v[68:69]
	v_lshl_add_u64 v[8:9], v[2:3], 0, v[8:9]
	global_store_dwordx4 v[8:9], v[4:7], off
	ds_read2_b32 v[4:5], v111 offset0:48 offset1:113
	v_add_u32_e32 v68, s3, v117
	s_waitcnt lgkmcnt(0)
	v_cvt_pk_bf16_f32 v4, v4, v5
	ds_read2_b32 v[6:7], v111 offset0:178 offset1:243
	s_waitcnt lgkmcnt(0)
	v_cvt_pk_bf16_f32 v5, v6, v7
	ds_read2_b32 v[6:7], v10 offset0:52 offset1:117
	s_waitcnt lgkmcnt(0)
	v_cvt_pk_bf16_f32 v6, v6, v7
	ds_read2_b32 v[8:9], v10 offset0:182 offset1:247
	s_waitcnt lgkmcnt(0)
	v_cvt_pk_bf16_f32 v7, v8, v9
	v_lshlrev_b64 v[8:9], 11, v[68:69]
	v_lshl_add_u64 v[8:9], v[2:3], 0, v[8:9]
	global_store_dwordx4 v[8:9], v[4:7], off
	ds_read2_b32 v[4:5], v111 offset0:56 offset1:121
	v_add_u32_e32 v68, s3, v118
	s_waitcnt lgkmcnt(0)
	v_cvt_pk_bf16_f32 v4, v4, v5
	ds_read2_b32 v[6:7], v111 offset0:186 offset1:251
	s_waitcnt lgkmcnt(0)
	v_cvt_pk_bf16_f32 v5, v6, v7
	ds_read2_b32 v[6:7], v10 offset0:60 offset1:125
	s_waitcnt lgkmcnt(0)
	v_cvt_pk_bf16_f32 v6, v6, v7
	ds_read2_b32 v[8:9], v10 offset0:190 offset1:255
	s_waitcnt lgkmcnt(0)
	v_cvt_pk_bf16_f32 v7, v8, v9
	v_lshlrev_b64 v[8:9], 11, v[68:69]
	v_lshl_add_u64 v[2:3], v[2:3], 0, v[8:9]
	global_store_dwordx4 v[2:3], v[4:7], off
	s_waitcnt lgkmcnt(0)

.LBB0_491:
	s_andn2_b64 vcc, exec, s[0:1]
	s_cbranch_vccnz .LBB0_517
	s_add_i32 s0, s3, 0xfd40
	s_and_b32 s1, s0, 0xffff
	s_mul_i32 s1, s1, 0xba2f
	s_lshr_b32 s1, s1, 21
	s_mul_i32 s2, s1, 44
	s_sub_i32 s25, s0, s2
	s_lshl_b32 s24, s1, 6
	v_or_b32_e32 v107, s24, v66
	s_lshl_b32 s0, s25, 8
	s_and_b32 s12, s0, 0x3ff00
	s_waitcnt vmcnt(0)
	v_mul_u32_u24_e32 v6, 0xb00, v107
	v_lshl_add_u64 v[2:3], v[96:97], 0, s[12:13]
	v_lshlrev_b32_e32 v68, 2, v6
	v_mad_u64_u32 v[4:5], s[0:1], v107, s45, v[2:3]
	v_lshl_add_u64 v[2:3], v[2:3], 0, v[68:69]
	v_add_co_u32_e32 v6, vcc, s46, v2
	v_cndmask_b32_e64 v68, 0, 1, s[6:7]
	s_nop 0
	v_addc_co_u32_e32 v7, vcc, 0, v3, vcc
	global_load_dwordx4 v[62:65], v[4:5], off nt
	global_load_dwordx4 v[58:61], v[6:7], off nt
	v_add_co_u32_e32 v4, vcc, s47, v2
	v_cmp_ne_u32_e64 s[0:1], 1, v68
	s_nop 0
	v_addc_co_u32_e32 v5, vcc, 0, v3, vcc
	v_add_co_u32_e32 v6, vcc, s48, v2
	v_add_lshl_u32 v106, s24, v66, 2
	s_nop 0
	v_addc_co_u32_e32 v7, vcc, 0, v3, vcc
	global_load_dwordx4 v[54:57], v[4:5], off nt
	global_load_dwordx4 v[50:53], v[6:7], off nt
	v_add_co_u32_e32 v4, vcc, s49, v2
	s_nop 1
	v_addc_co_u32_e32 v5, vcc, 0, v3, vcc
	v_add_co_u32_e32 v6, vcc, s50, v2
	s_nop 1
	v_addc_co_u32_e32 v7, vcc, 0, v3, vcc
	global_load_dwordx4 v[46:49], v[4:5], off nt
	global_load_dwordx4 v[42:45], v[6:7], off nt
	v_add_co_u32_e32 v4, vcc, s51, v2
	s_nop 1
	v_addc_co_u32_e32 v5, vcc, 0, v3, vcc
	v_add_co_u32_e32 v6, vcc, s62, v2
	s_nop 1
	v_addc_co_u32_e32 v7, vcc, 0, v3, vcc
	global_load_dwordx4 v[38:41], v[4:5], off nt
	global_load_dwordx4 v[34:37], v[6:7], off nt
	v_add_co_u32_e32 v4, vcc, s63, v2
	s_nop 1
	v_addc_co_u32_e32 v5, vcc, 0, v3, vcc
	v_add_co_u32_e32 v6, vcc, s64, v2
	s_nop 1
	v_addc_co_u32_e32 v7, vcc, 0, v3, vcc
	global_load_dwordx4 v[30:33], v[4:5], off nt
	global_load_dwordx4 v[26:29], v[6:7], off nt
	v_add_co_u32_e32 v4, vcc, s65, v2
	s_nop 1
	v_addc_co_u32_e32 v5, vcc, 0, v3, vcc
	v_add_co_u32_e32 v6, vcc, s66, v2
	s_nop 1
	v_addc_co_u32_e32 v7, vcc, 0, v3, vcc
	global_load_dwordx4 v[22:25], v[4:5], off nt
	global_load_dwordx4 v[18:21], v[6:7], off nt
	v_add_co_u32_e32 v4, vcc, s67, v2
	s_nop 1
	v_addc_co_u32_e32 v5, vcc, 0, v3, vcc
	v_add_co_u32_e32 v6, vcc, 0x8f000, v2
	s_nop 1
	v_addc_co_u32_e32 v7, vcc, 0, v3, vcc
	global_load_dwordx4 v[14:17], v[4:5], off nt
	global_load_dwordx4 v[10:13], v[6:7], off nt
	v_add_co_u32_e32 v4, vcc, 0x9a000, v2
	s_nop 1
	v_addc_co_u32_e32 v5, vcc, 0, v3, vcc
	v_add_co_u32_e32 v2, vcc, 0xa5000, v2
	s_nop 1
	v_addc_co_u32_e32 v3, vcc, 0, v3, vcc
	global_load_dwordx4 v[6:9], v[4:5], off nt
	s_nop 0
	global_load_dwordx4 v[2:5], v[2:3], off nt
	s_andn2_b64 vcc, exec, s[6:7]
	s_cbranch_vccnz .LBB0_632
	v_readlane_b32 s72, v254, 45
	v_readlane_b32 s84, v254, 57
	v_readlane_b32 s85, v254, 58
	v_readlane_b32 s86, v254, 59
	v_readlane_b32 s87, v254, 60
	s_mov_b64 s[16:17], s[84:85]
	v_lshlrev_b32_e32 v68, 2, v107
	s_mov_b64 s[18:19], s[86:87]
	global_load_dword v188, v68, s[18:19]
	global_load_dword v190, v106, s[18:19] offset:16
	global_load_dword v192, v106, s[18:19] offset:32
	global_load_dword v194, v106, s[18:19] offset:48
	global_load_dword v196, v106, s[18:19] offset:64
	global_load_dword v198, v106, s[18:19] offset:80
	global_load_dword v200, v106, s[18:19] offset:96
	global_load_dword v202, v106, s[18:19] offset:112
	global_load_dword v204, v106, s[18:19] offset:128
	global_load_dword v206, v106, s[18:19] offset:144
	global_load_dword v208, v106, s[18:19] offset:160
	global_load_dword v210, v106, s[18:19] offset:176
	global_load_dword v212, v106, s[18:19] offset:192
	global_load_dword v214, v106, s[18:19] offset:208
	global_load_dword v216, v106, s[18:19] offset:224
	global_load_dword v218, v106, s[18:19] offset:240
	v_readlane_b32 s73, v254, 46
	v_readlane_b32 s74, v254, 47
	v_readlane_b32 s75, v254, 48
	v_readlane_b32 s76, v254, 49
	v_readlane_b32 s77, v254, 50
	v_readlane_b32 s78, v254, 51
	v_readlane_b32 s79, v254, 52
	v_readlane_b32 s80, v254, 53
	v_readlane_b32 s81, v254, 54
	v_readlane_b32 s82, v254, 55
	v_readlane_b32 s83, v254, 56
	s_waitcnt vmcnt(0)
	v_pk_mul_f32 v[130:131], v[62:63], v[188:189] op_sel_hi:[1,0]
	ds_write2_b32 v109, v130, v131 offset1:1
	v_pk_mul_f32 v[130:131], v[64:65], v[188:189] op_sel_hi:[1,0]
	ds_write2_b32 v109, v130, v131 offset0:2 offset1:3
	s_cbranch_execnz .LBB0_495

.LBB0_495:
	s_waitcnt vmcnt(0)
	v_pk_mul_f32 v[58:59], v[58:59], v[190:191] op_sel_hi:[1,0]
	v_add_u32_e32 v62, v108, v119
	ds_write2_b32 v62, v58, v59 offset1:1
	v_pk_mul_f32 v[58:59], v[60:61], v[190:191] op_sel_hi:[1,0]
	s_and_b64 vcc, exec, s[0:1]
	ds_write2_b32 v62, v58, v59 offset0:2 offset1:3
	s_cbranch_vccnz .LBB0_633
	v_readlane_b32 s72, v254, 45
	v_readlane_b32 s84, v254, 57
	v_readlane_b32 s85, v254, 58
	v_readlane_b32 s86, v254, 59
	v_readlane_b32 s87, v254, 60
	s_mov_b64 s[16:17], s[84:85]
	s_mov_b64 s[18:19], s[86:87]
	v_add_u32_e32 v62, v108, v120
	v_readlane_b32 s73, v254, 46
	v_readlane_b32 s74, v254, 47
	v_readlane_b32 s75, v254, 48
	v_readlane_b32 s76, v254, 49
	v_readlane_b32 s77, v254, 50
	v_readlane_b32 s78, v254, 51
	v_readlane_b32 s79, v254, 52
	v_readlane_b32 s80, v254, 53
	v_readlane_b32 s81, v254, 54
	v_readlane_b32 s82, v254, 55
	v_readlane_b32 s83, v254, 56
	s_waitcnt vmcnt(0)
	v_pk_mul_f32 v[60:61], v[54:55], v[192:193] op_sel_hi:[1,0]
	v_pk_mul_f32 v[58:59], v[56:57], v[192:193] op_sel_hi:[1,0]
	ds_write2_b32 v62, v58, v59 offset0:2 offset1:3
	ds_write2_b32 v62, v60, v61 offset1:1
	s_cbranch_execnz .LBB0_498

.LBB0_498:
	s_waitcnt vmcnt(0)
	v_pk_mul_f32 v[50:51], v[50:51], v[194:195] op_sel_hi:[1,0]
	v_add_u32_e32 v54, v108, v121
	ds_write2_b32 v54, v50, v51 offset1:1
	v_pk_mul_f32 v[50:51], v[52:53], v[194:195] op_sel_hi:[1,0]
	s_and_b64 vcc, exec, s[0:1]
	ds_write2_b32 v54, v50, v51 offset0:2 offset1:3
	s_cbranch_vccnz .LBB0_634
	v_readlane_b32 s72, v254, 45
	v_readlane_b32 s84, v254, 57
	v_readlane_b32 s85, v254, 58
	v_readlane_b32 s86, v254, 59
	v_readlane_b32 s87, v254, 60
	s_mov_b64 s[16:17], s[84:85]
	s_mov_b64 s[18:19], s[86:87]
	v_add_u32_e32 v54, v108, v122
	v_readlane_b32 s73, v254, 46
	v_readlane_b32 s74, v254, 47
	v_readlane_b32 s75, v254, 48
	v_readlane_b32 s76, v254, 49
	v_readlane_b32 s77, v254, 50
	v_readlane_b32 s78, v254, 51
	v_readlane_b32 s79, v254, 52
	v_readlane_b32 s80, v254, 53
	v_readlane_b32 s81, v254, 54
	v_readlane_b32 s82, v254, 55
	v_readlane_b32 s83, v254, 56
	s_waitcnt vmcnt(0)
	v_pk_mul_f32 v[52:53], v[46:47], v[196:197] op_sel_hi:[1,0]
	v_pk_mul_f32 v[50:51], v[48:49], v[196:197] op_sel_hi:[1,0]
	ds_write2_b32 v54, v50, v51 offset0:2 offset1:3
	ds_write2_b32 v54, v52, v53 offset1:1
	s_cbranch_execnz .LBB0_501

.LBB0_501:
	s_waitcnt vmcnt(0)
	v_pk_mul_f32 v[42:43], v[42:43], v[198:199] op_sel_hi:[1,0]
	v_add_u32_e32 v46, v108, v123
	ds_write2_b32 v46, v42, v43 offset1:1
	v_pk_mul_f32 v[42:43], v[44:45], v[198:199] op_sel_hi:[1,0]
	s_and_b64 vcc, exec, s[0:1]
	ds_write2_b32 v46, v42, v43 offset0:2 offset1:3
	s_cbranch_vccnz .LBB0_635
	v_readlane_b32 s72, v254, 45
	v_readlane_b32 s84, v254, 57
	v_readlane_b32 s85, v254, 58
	v_readlane_b32 s86, v254, 59
	v_readlane_b32 s87, v254, 60
	s_mov_b64 s[16:17], s[84:85]
	s_mov_b64 s[18:19], s[86:87]
	v_add_u32_e32 v46, v108, v124
	v_readlane_b32 s73, v254, 46
	v_readlane_b32 s74, v254, 47
	v_readlane_b32 s75, v254, 48
	v_readlane_b32 s76, v254, 49
	v_readlane_b32 s77, v254, 50
	v_readlane_b32 s78, v254, 51
	v_readlane_b32 s79, v254, 52
	v_readlane_b32 s80, v254, 53
	v_readlane_b32 s81, v254, 54
	v_readlane_b32 s82, v254, 55
	v_readlane_b32 s83, v254, 56
	s_waitcnt vmcnt(0)
	v_pk_mul_f32 v[44:45], v[38:39], v[200:201] op_sel_hi:[1,0]
	v_pk_mul_f32 v[42:43], v[40:41], v[200:201] op_sel_hi:[1,0]
	ds_write2_b32 v46, v42, v43 offset0:2 offset1:3
	ds_write2_b32 v46, v44, v45 offset1:1
	s_cbranch_execnz .LBB0_504

.LBB0_504:
	s_waitcnt vmcnt(0)
	v_pk_mul_f32 v[34:35], v[34:35], v[202:203] op_sel_hi:[1,0]
	v_add_u32_e32 v38, v108, v125
	ds_write2_b32 v38, v34, v35 offset1:1
	v_pk_mul_f32 v[34:35], v[36:37], v[202:203] op_sel_hi:[1,0]
	s_and_b64 vcc, exec, s[0:1]
	ds_write2_b32 v38, v34, v35 offset0:2 offset1:3
	s_cbranch_vccnz .LBB0_636
	v_readlane_b32 s72, v254, 45
	v_readlane_b32 s84, v254, 57
	v_readlane_b32 s85, v254, 58
	v_readlane_b32 s86, v254, 59
	v_readlane_b32 s87, v254, 60
	s_mov_b64 s[16:17], s[84:85]
	s_mov_b64 s[18:19], s[86:87]
	v_add_u32_e32 v38, v108, v126
	v_readlane_b32 s73, v254, 46
	v_readlane_b32 s74, v254, 47
	v_readlane_b32 s75, v254, 48
	v_readlane_b32 s76, v254, 49
	v_readlane_b32 s77, v254, 50
	v_readlane_b32 s78, v254, 51
	v_readlane_b32 s79, v254, 52
	v_readlane_b32 s80, v254, 53
	v_readlane_b32 s81, v254, 54
	v_readlane_b32 s82, v254, 55
	v_readlane_b32 s83, v254, 56
	s_waitcnt vmcnt(0)
	v_pk_mul_f32 v[36:37], v[30:31], v[204:205] op_sel_hi:[1,0]
	v_pk_mul_f32 v[34:35], v[32:33], v[204:205] op_sel_hi:[1,0]
	ds_write2_b32 v38, v34, v35 offset0:2 offset1:3
	ds_write2_b32 v38, v36, v37 offset1:1
	s_cbranch_execnz .LBB0_507

.LBB0_507:
	s_waitcnt vmcnt(0)
	v_pk_mul_f32 v[26:27], v[26:27], v[206:207] op_sel_hi:[1,0]
	v_add_u32_e32 v30, v108, v127
	ds_write2_b32 v30, v26, v27 offset1:1
	v_pk_mul_f32 v[26:27], v[28:29], v[206:207] op_sel_hi:[1,0]
	s_and_b64 vcc, exec, s[0:1]
	ds_write2_b32 v30, v26, v27 offset0:2 offset1:3
	s_cbranch_vccnz .LBB0_637
	v_readlane_b32 s72, v254, 45
	v_readlane_b32 s84, v254, 57
	v_readlane_b32 s85, v254, 58
	v_readlane_b32 s86, v254, 59
	v_readlane_b32 s87, v254, 60
	s_mov_b64 s[16:17], s[84:85]
	s_mov_b64 s[18:19], s[86:87]
	v_add_u32_e32 v30, v108, v128
	v_readlane_b32 s73, v254, 46
	v_readlane_b32 s74, v254, 47
	v_readlane_b32 s75, v254, 48
	v_readlane_b32 s76, v254, 49
	v_readlane_b32 s77, v254, 50
	v_readlane_b32 s78, v254, 51
	v_readlane_b32 s79, v254, 52
	v_readlane_b32 s80, v254, 53
	v_readlane_b32 s81, v254, 54
	v_readlane_b32 s82, v254, 55
	v_readlane_b32 s83, v254, 56
	s_waitcnt vmcnt(0)
	v_pk_mul_f32 v[28:29], v[22:23], v[208:209] op_sel_hi:[1,0]
	v_pk_mul_f32 v[26:27], v[24:25], v[208:209] op_sel_hi:[1,0]
	ds_write2_b32 v30, v26, v27 offset0:2 offset1:3
	ds_write2_b32 v30, v28, v29 offset1:1
	s_cbranch_execnz .LBB0_510

.LBB0_510:
	s_waitcnt vmcnt(0)
	v_pk_mul_f32 v[22:23], v[18:19], v[210:211] op_sel_hi:[1,0]
	v_add_u32_e32 v19, v108, v129
	v_pk_mul_f32 v[20:21], v[20:21], v[210:211] op_sel_hi:[1,0]
	ds_write2_b32 v19, v20, v21 offset0:2 offset1:3
	s_and_b64 vcc, exec, s[0:1]
	v_add_u32_e32 v20, 0x410, v19
	v_add_u32_e32 v21, 0x418, v19
	ds_write2_b32 v19, v22, v23 offset1:1
	s_cbranch_vccnz .LBB0_638
	v_readlane_b32 s72, v254, 45
	v_readlane_b32 s84, v254, 57
	v_readlane_b32 s85, v254, 58
	v_readlane_b32 s86, v254, 59
	v_readlane_b32 s87, v254, 60
	s_mov_b64 s[16:17], s[84:85]
	s_mov_b64 s[18:19], s[86:87]
	v_readlane_b32 s73, v254, 46
	v_readlane_b32 s74, v254, 47
	v_readlane_b32 s75, v254, 48
	v_readlane_b32 s76, v254, 49
	v_readlane_b32 s77, v254, 50
	v_readlane_b32 s78, v254, 51
	v_readlane_b32 s79, v254, 52
	v_readlane_b32 s80, v254, 53
	v_readlane_b32 s81, v254, 54
	v_readlane_b32 s82, v254, 55
	v_readlane_b32 s83, v254, 56
	s_waitcnt vmcnt(0)
	v_pk_mul_f32 v[22:23], v[14:15], v[212:213] op_sel_hi:[1,0]
	ds_write2_b32 v20, v22, v23 offset1:1
	v_pk_mul_f32 v[22:23], v[16:17], v[212:213] op_sel_hi:[1,0]
	ds_write2_b32 v21, v22, v23 offset1:1
	s_cbranch_execnz .LBB0_513

.LBB0_513:
	s_waitcnt vmcnt(0)
	v_pk_mul_f32 v[10:11], v[10:11], v[214:215] op_sel_hi:[1,0]
	v_add_u32_e32 v14, 0x820, v19
	ds_write2_b32 v14, v10, v11 offset1:1
	v_pk_mul_f32 v[10:11], v[12:13], v[214:215] op_sel_hi:[1,0]
	v_add_u32_e32 v12, 0x828, v19
	ds_write2_b32 v12, v10, v11 offset1:1
	s_and_b64 vcc, exec, s[0:1]
	v_add_u32_e32 v11, 0xc30, v19
	v_add_u32_e32 v12, 0xc38, v19
	s_cbranch_vccnz .LBB0_639
	v_readlane_b32 s72, v254, 45
	v_readlane_b32 s84, v254, 57
	v_readlane_b32 s85, v254, 58
	v_readlane_b32 s86, v254, 59
	v_readlane_b32 s87, v254, 60
	s_mov_b64 s[16:17], s[84:85]
	s_mov_b64 s[18:19], s[86:87]
	v_readlane_b32 s73, v254, 46
	v_readlane_b32 s74, v254, 47
	v_readlane_b32 s75, v254, 48
	v_readlane_b32 s76, v254, 49
	v_readlane_b32 s77, v254, 50
	v_readlane_b32 s78, v254, 51
	v_readlane_b32 s79, v254, 52
	v_readlane_b32 s80, v254, 53
	v_readlane_b32 s81, v254, 54
	v_readlane_b32 s82, v254, 55
	v_readlane_b32 s83, v254, 56
	s_waitcnt vmcnt(0)
	v_pk_mul_f32 v[14:15], v[6:7], v[216:217] op_sel_hi:[1,0]
	ds_write2_b32 v11, v14, v15 offset1:1
	v_pk_mul_f32 v[14:15], v[8:9], v[216:217] op_sel_hi:[1,0]
	ds_write2_b32 v12, v14, v15 offset1:1
	s_cbranch_execnz .LBB0_516

.LBB0_516:
	s_waitcnt vmcnt(0)
	v_pk_mul_f32 v[2:3], v[2:3], v[218:219] op_sel_hi:[1,0]
	v_add_u32_e32 v6, 0x1040, v19
	ds_write2_b32 v6, v2, v3 offset1:1
	v_pk_mul_f32 v[2:3], v[4:5], v[218:219] op_sel_hi:[1,0]
	v_add_u32_e32 v4, 0x1048, v19
	ds_write2_b32 v4, v2, v3 offset1:1
	s_lshl_b32 s0, s25, 6
	s_waitcnt lgkmcnt(0)
	s_and_b32 s0, 0xffff, s0
	s_lshl_b32 s1, s0, 1
	ds_read2_b32 v[4:5], v111 offset1:65
	s_and_b32 s1, s1, 0x1f00
	s_and_b32 s0, s0, 64
	s_waitcnt lgkmcnt(0)
	v_cvt_pk_bf16_f32 v4, v4, v5
	ds_read2_b32 v[6:7], v111 offset0:130 offset1:195
	v_add_u32_e32 v10, 0x400, v111
	s_or_b32 s0, s0, s1
	s_waitcnt lgkmcnt(0)
	v_cvt_pk_bf16_f32 v5, v6, v7
	ds_read2_b32 v[6:7], v10 offset0:4 offset1:69
	s_bitset1_b32 s0, 7
	s_waitcnt lgkmcnt(0)
	v_cvt_pk_bf16_f32 v6, v6, v7
	ds_read2_b32 v[8:9], v10 offset0:134 offset1:199
	s_lshl_b32 s12, s24, 1
	s_waitcnt lgkmcnt(0)
	v_cvt_pk_bf16_f32 v7, v8, v9
	v_or_b32_e32 v8, s0, v110
	v_lshl_add_u64 v[2:3], v[80:81], 0, s[12:13]
	v_lshlrev_b32_e32 v68, 11, v8
	v_lshl_add_u64 v[8:9], v[2:3], 0, v[68:69]
	global_store_dwordx4 v[8:9], v[4:7], off
	ds_read2_b32 v[4:5], v111 offset0:8 offset1:73
	s_waitcnt lgkmcnt(0)
	v_cvt_pk_bf16_f32 v4, v4, v5
	ds_read2_b32 v[6:7], v111 offset0:138 offset1:203
	s_waitcnt lgkmcnt(0)
	v_cvt_pk_bf16_f32 v5, v6, v7
	ds_read2_b32 v[6:7], v10 offset0:12 offset1:77
	s_waitcnt lgkmcnt(0)
	v_cvt_pk_bf16_f32 v6, v6, v7
	ds_read2_b32 v[8:9], v10 offset0:142 offset1:207
	s_waitcnt lgkmcnt(0)
	v_cvt_pk_bf16_f32 v7, v8, v9
	v_or_b32_e32 v8, s0, v112
	v_lshlrev_b32_e32 v68, 11, v8
	v_lshl_add_u64 v[8:9], v[2:3], 0, v[68:69]
	global_store_dwordx4 v[8:9], v[4:7], off
	ds_read2_b32 v[4:5], v111 offset0:16 offset1:81
	s_waitcnt lgkmcnt(0)
	v_cvt_pk_bf16_f32 v4, v4, v5
	ds_read2_b32 v[6:7], v111 offset0:146 offset1:211
	s_waitcnt lgkmcnt(0)
	v_cvt_pk_bf16_f32 v5, v6, v7
	ds_read2_b32 v[6:7], v10 offset0:20 offset1:85
	s_waitcnt lgkmcnt(0)
	v_cvt_pk_bf16_f32 v6, v6, v7
	ds_read2_b32 v[8:9], v10 offset0:150 offset1:215
	s_waitcnt lgkmcnt(0)
	v_cvt_pk_bf16_f32 v7, v8, v9
	v_or_b32_e32 v8, s0, v113
	v_lshlrev_b32_e32 v68, 11, v8
	v_lshl_add_u64 v[8:9], v[2:3], 0, v[68:69]
	global_store_dwordx4 v[8:9], v[4:7], off
	ds_read2_b32 v[4:5], v111 offset0:24 offset1:89
	s_waitcnt lgkmcnt(0)
	v_cvt_pk_bf16_f32 v4, v4, v5
	ds_read2_b32 v[6:7], v111 offset0:154 offset1:219
	s_waitcnt lgkmcnt(0)
	v_cvt_pk_bf16_f32 v5, v6, v7
	ds_read2_b32 v[6:7], v10 offset0:28 offset1:93
	s_waitcnt lgkmcnt(0)
	v_cvt_pk_bf16_f32 v6, v6, v7
	ds_read2_b32 v[8:9], v10 offset0:158 offset1:223
	s_waitcnt lgkmcnt(0)
	v_cvt_pk_bf16_f32 v7, v8, v9
	v_or_b32_e32 v8, s0, v114
	v_lshlrev_b32_e32 v68, 11, v8
	v_lshl_add_u64 v[8:9], v[2:3], 0, v[68:69]
	global_store_dwordx4 v[8:9], v[4:7], off
	ds_read2_b32 v[4:5], v111 offset0:32 offset1:97
	s_waitcnt lgkmcnt(0)
	v_cvt_pk_bf16_f32 v4, v4, v5
	ds_read2_b32 v[6:7], v111 offset0:162 offset1:227
	s_waitcnt lgkmcnt(0)
	v_cvt_pk_bf16_f32 v5, v6, v7
	ds_read2_b32 v[6:7], v10 offset0:36 offset1:101
	s_waitcnt lgkmcnt(0)
	v_cvt_pk_bf16_f32 v6, v6, v7
	ds_read2_b32 v[8:9], v10 offset0:166 offset1:231
	s_waitcnt lgkmcnt(0)
	v_cvt_pk_bf16_f32 v7, v8, v9
	v_or_b32_e32 v8, s0, v115
	v_lshlrev_b32_e32 v68, 11, v8
	v_lshl_add_u64 v[8:9], v[2:3], 0, v[68:69]
	global_store_dwordx4 v[8:9], v[4:7], off
	ds_read2_b32 v[4:5], v111 offset0:40 offset1:105
	s_waitcnt lgkmcnt(0)
	v_cvt_pk_bf16_f32 v4, v4, v5
	ds_read2_b32 v[6:7], v111 offset0:170 offset1:235
	s_waitcnt lgkmcnt(0)
	v_cvt_pk_bf16_f32 v5, v6, v7
	ds_read2_b32 v[6:7], v10 offset0:44 offset1:109
	s_waitcnt lgkmcnt(0)
	v_cvt_pk_bf16_f32 v6, v6, v7
	ds_read2_b32 v[8:9], v10 offset0:174 offset1:239
	s_waitcnt lgkmcnt(0)
	v_cvt_pk_bf16_f32 v7, v8, v9
	v_or_b32_e32 v8, s0, v116
	v_lshlrev_b32_e32 v68, 11, v8
	v_lshl_add_u64 v[8:9], v[2:3], 0, v[68:69]
	global_store_dwordx4 v[8:9], v[4:7], off
	ds_read2_b32 v[4:5], v111 offset0:48 offset1:113
	s_waitcnt lgkmcnt(0)
	v_cvt_pk_bf16_f32 v4, v4, v5
	ds_read2_b32 v[6:7], v111 offset0:178 offset1:243
	s_waitcnt lgkmcnt(0)
	v_cvt_pk_bf16_f32 v5, v6, v7
	ds_read2_b32 v[6:7], v10 offset0:52 offset1:117
	s_waitcnt lgkmcnt(0)
	v_cvt_pk_bf16_f32 v6, v6, v7
	ds_read2_b32 v[8:9], v10 offset0:182 offset1:247
	s_waitcnt lgkmcnt(0)
	v_cvt_pk_bf16_f32 v7, v8, v9
	v_or_b32_e32 v8, s0, v117
	v_lshlrev_b32_e32 v68, 11, v8
	v_lshl_add_u64 v[8:9], v[2:3], 0, v[68:69]
	global_store_dwordx4 v[8:9], v[4:7], off
	ds_read2_b32 v[4:5], v111 offset0:56 offset1:121
	s_waitcnt lgkmcnt(0)
	v_cvt_pk_bf16_f32 v4, v4, v5
	ds_read2_b32 v[6:7], v111 offset0:186 offset1:251
	s_waitcnt lgkmcnt(0)
	v_cvt_pk_bf16_f32 v5, v6, v7
	ds_read2_b32 v[6:7], v10 offset0:60 offset1:125
	s_waitcnt lgkmcnt(0)
	v_cvt_pk_bf16_f32 v6, v6, v7
	ds_read2_b32 v[8:9], v10 offset0:190 offset1:255
	s_waitcnt lgkmcnt(0)
	v_cvt_pk_bf16_f32 v7, v8, v9
	v_or_b32_e32 v8, s0, v118
	v_lshlrev_b32_e32 v68, 11, v8
	v_lshl_add_u64 v[2:3], v[2:3], 0, v[68:69]
	global_store_dwordx4 v[2:3], v[4:7], off
	s_waitcnt lgkmcnt(0)

.LBB0_518:
	s_andn2_b64 vcc, exec, s[0:1]
	s_cbranch_vccnz .LBB0_544
	s_and_b32 s0, s3, 0xffff
	s_mul_i32 s0, s0, 0xba2f
	s_lshr_b32 s1, s0, 21
	s_mul_i32 s1, s1, 44
	s_sub_i32 s1, s3, s1
	s_lshr_b32 s0, s0, 15
	s_and_b32 s24, s1, 0xffff
	s_and_b32 s3, s0, 0xffc0
	v_or_b32_e32 v107, s3, v66
	s_lshl_b32 s12, s24, 8
	v_lshl_add_u64 v[2:3], v[98:99], 0, s[12:13]
	v_mul_u32_u24_e32 v68, 0x2c00, v107
	v_mad_u64_u32 v[4:5], s[0:1], v107, s45, v[2:3]
	v_lshl_add_u64 v[2:3], v[2:3], 0, v[68:69]
	s_waitcnt vmcnt(0)
	v_add_co_u32_e32 v6, vcc, s46, v2
	v_cndmask_b32_e64 v68, 0, 1, s[6:7]
	s_nop 0
	v_addc_co_u32_e32 v7, vcc, 0, v3, vcc
	global_load_dwordx4 v[62:65], v[4:5], off nt
	global_load_dwordx4 v[58:61], v[6:7], off nt
	v_add_co_u32_e32 v4, vcc, s47, v2
	v_cmp_ne_u32_e64 s[0:1], 1, v68
	s_nop 0
	v_addc_co_u32_e32 v5, vcc, 0, v3, vcc
	v_add_co_u32_e32 v6, vcc, s48, v2
	v_add_lshl_u32 v106, v66, s3, 2
	s_nop 0
	v_addc_co_u32_e32 v7, vcc, 0, v3, vcc
	global_load_dwordx4 v[54:57], v[4:5], off nt
	global_load_dwordx4 v[50:53], v[6:7], off nt
	v_add_co_u32_e32 v4, vcc, s49, v2
	s_nop 1
	v_addc_co_u32_e32 v5, vcc, 0, v3, vcc
	v_add_co_u32_e32 v6, vcc, s50, v2
	s_nop 1
	v_addc_co_u32_e32 v7, vcc, 0, v3, vcc
	global_load_dwordx4 v[46:49], v[4:5], off nt
	global_load_dwordx4 v[42:45], v[6:7], off nt
	v_add_co_u32_e32 v4, vcc, s51, v2
	s_nop 1
	v_addc_co_u32_e32 v5, vcc, 0, v3, vcc
	v_add_co_u32_e32 v6, vcc, s62, v2
	s_nop 1
	v_addc_co_u32_e32 v7, vcc, 0, v3, vcc
	global_load_dwordx4 v[38:41], v[4:5], off nt
	global_load_dwordx4 v[34:37], v[6:7], off nt
	v_add_co_u32_e32 v4, vcc, s63, v2
	s_nop 1
	v_addc_co_u32_e32 v5, vcc, 0, v3, vcc
	v_add_co_u32_e32 v6, vcc, s64, v2
	s_nop 1
	v_addc_co_u32_e32 v7, vcc, 0, v3, vcc
	global_load_dwordx4 v[30:33], v[4:5], off nt
	global_load_dwordx4 v[26:29], v[6:7], off nt
	v_add_co_u32_e32 v4, vcc, s65, v2
	s_nop 1
	v_addc_co_u32_e32 v5, vcc, 0, v3, vcc
	v_add_co_u32_e32 v6, vcc, s66, v2
	s_nop 1
	v_addc_co_u32_e32 v7, vcc, 0, v3, vcc
	global_load_dwordx4 v[22:25], v[4:5], off nt
	global_load_dwordx4 v[18:21], v[6:7], off nt
	v_add_co_u32_e32 v4, vcc, s67, v2
	s_nop 1
	v_addc_co_u32_e32 v5, vcc, 0, v3, vcc
	v_add_co_u32_e32 v6, vcc, 0x8f000, v2
	s_nop 1
	v_addc_co_u32_e32 v7, vcc, 0, v3, vcc
	global_load_dwordx4 v[14:17], v[4:5], off nt
	global_load_dwordx4 v[10:13], v[6:7], off nt
	v_add_co_u32_e32 v4, vcc, 0x9a000, v2
	s_nop 1
	v_addc_co_u32_e32 v5, vcc, 0, v3, vcc
	v_add_co_u32_e32 v2, vcc, 0xa5000, v2
	s_nop 1
	v_addc_co_u32_e32 v3, vcc, 0, v3, vcc
	global_load_dwordx4 v[6:9], v[4:5], off nt
	s_nop 0
	global_load_dwordx4 v[2:5], v[2:3], off nt
	s_andn2_b64 vcc, exec, s[6:7]
	s_cbranch_vccnz .LBB0_616
	v_readlane_b32 s72, v254, 45
	v_readlane_b32 s84, v254, 57
	v_readlane_b32 s85, v254, 58
	v_readlane_b32 s86, v254, 59
	v_readlane_b32 s87, v254, 60
	s_mov_b64 s[16:17], s[84:85]
	v_lshlrev_b32_e32 v68, 2, v107
	s_mov_b64 s[18:19], s[86:87]
	global_load_dword v188, v68, s[18:19]
	global_load_dword v190, v106, s[18:19] offset:16
	global_load_dword v192, v106, s[18:19] offset:32
	global_load_dword v194, v106, s[18:19] offset:48
	global_load_dword v196, v106, s[18:19] offset:64
	global_load_dword v198, v106, s[18:19] offset:80
	global_load_dword v200, v106, s[18:19] offset:96
	global_load_dword v202, v106, s[18:19] offset:112
	global_load_dword v204, v106, s[18:19] offset:128
	global_load_dword v206, v106, s[18:19] offset:144
	global_load_dword v208, v106, s[18:19] offset:160
	global_load_dword v210, v106, s[18:19] offset:176
	global_load_dword v212, v106, s[18:19] offset:192
	global_load_dword v214, v106, s[18:19] offset:208
	global_load_dword v216, v106, s[18:19] offset:224
	global_load_dword v218, v106, s[18:19] offset:240
	v_readlane_b32 s73, v254, 46
	v_readlane_b32 s74, v254, 47
	v_readlane_b32 s75, v254, 48
	v_readlane_b32 s76, v254, 49
	v_readlane_b32 s77, v254, 50
	v_readlane_b32 s78, v254, 51
	v_readlane_b32 s79, v254, 52
	v_readlane_b32 s80, v254, 53
	v_readlane_b32 s81, v254, 54
	v_readlane_b32 s82, v254, 55
	v_readlane_b32 s83, v254, 56
	s_waitcnt vmcnt(0)
	v_pk_mul_f32 v[130:131], v[62:63], v[188:189] op_sel_hi:[1,0]
	ds_write2_b32 v109, v130, v131 offset1:1
	v_pk_mul_f32 v[130:131], v[64:65], v[188:189] op_sel_hi:[1,0]
	ds_write2_b32 v109, v130, v131 offset0:2 offset1:3
	s_cbranch_execnz .LBB0_522

.LBB0_543:
	s_waitcnt vmcnt(0)
	v_pk_mul_f32 v[2:3], v[2:3], v[218:219] op_sel_hi:[1,0]
	v_add_u32_e32 v6, 0x1040, v19
	ds_write2_b32 v6, v2, v3 offset1:1
	v_pk_mul_f32 v[2:3], v[4:5], v[218:219] op_sel_hi:[1,0]
	v_add_u32_e32 v4, 0x1048, v19
	ds_write2_b32 v4, v2, v3 offset1:1
	s_waitcnt lgkmcnt(0)
	ds_read2_b32 v[4:5], v111 offset1:65
	s_lshl_b32 s0, s24, 6
	s_lshl_b32 s1, s24, 7
	s_waitcnt lgkmcnt(0)
	v_cvt_pk_bf16_f32 v4, v4, v5
	ds_read2_b32 v[6:7], v111 offset0:130 offset1:195
	v_add_u32_e32 v10, 0x400, v111
	s_and_b32 s1, s1, 0x1f00
	s_and_b32 s0, s0, 64
	s_waitcnt lgkmcnt(0)
	v_cvt_pk_bf16_f32 v5, v6, v7
	ds_read2_b32 v[6:7], v10 offset0:4 offset1:69
	s_or_b32 s0, s1, s0
	s_waitcnt lgkmcnt(0)
	v_cvt_pk_bf16_f32 v6, v6, v7
	ds_read2_b32 v[8:9], v10 offset0:134 offset1:199
	s_lshl_b32 s12, s3, 1
	s_waitcnt lgkmcnt(0)
	v_cvt_pk_bf16_f32 v7, v8, v9
	v_or_b32_e32 v8, s0, v110
	v_lshl_add_u64 v[2:3], v[80:81], 0, s[12:13]
	v_lshlrev_b32_e32 v68, 11, v8
	v_lshl_add_u64 v[8:9], v[2:3], 0, v[68:69]
	global_store_dwordx4 v[8:9], v[4:7], off
	ds_read2_b32 v[4:5], v111 offset0:8 offset1:73
	s_waitcnt lgkmcnt(0)
	v_cvt_pk_bf16_f32 v4, v4, v5
	ds_read2_b32 v[6:7], v111 offset0:138 offset1:203
	s_waitcnt lgkmcnt(0)
	v_cvt_pk_bf16_f32 v5, v6, v7
	ds_read2_b32 v[6:7], v10 offset0:12 offset1:77
	s_waitcnt lgkmcnt(0)
	v_cvt_pk_bf16_f32 v6, v6, v7
	ds_read2_b32 v[8:9], v10 offset0:142 offset1:207
	s_waitcnt lgkmcnt(0)
	v_cvt_pk_bf16_f32 v7, v8, v9
	v_or_b32_e32 v8, s0, v112
	v_lshlrev_b32_e32 v68, 11, v8
	v_lshl_add_u64 v[8:9], v[2:3], 0, v[68:69]
	global_store_dwordx4 v[8:9], v[4:7], off
	ds_read2_b32 v[4:5], v111 offset0:16 offset1:81
	s_waitcnt lgkmcnt(0)
	v_cvt_pk_bf16_f32 v4, v4, v5
	ds_read2_b32 v[6:7], v111 offset0:146 offset1:211
	s_waitcnt lgkmcnt(0)
	v_cvt_pk_bf16_f32 v5, v6, v7
	ds_read2_b32 v[6:7], v10 offset0:20 offset1:85
	s_waitcnt lgkmcnt(0)
	v_cvt_pk_bf16_f32 v6, v6, v7
	ds_read2_b32 v[8:9], v10 offset0:150 offset1:215
	s_waitcnt lgkmcnt(0)
	v_cvt_pk_bf16_f32 v7, v8, v9
	v_or_b32_e32 v8, s0, v113
	v_lshlrev_b32_e32 v68, 11, v8
	v_lshl_add_u64 v[8:9], v[2:3], 0, v[68:69]
	global_store_dwordx4 v[8:9], v[4:7], off
	ds_read2_b32 v[4:5], v111 offset0:24 offset1:89
	s_waitcnt lgkmcnt(0)
	v_cvt_pk_bf16_f32 v4, v4, v5
	ds_read2_b32 v[6:7], v111 offset0:154 offset1:219
	s_waitcnt lgkmcnt(0)
	v_cvt_pk_bf16_f32 v5, v6, v7
	ds_read2_b32 v[6:7], v10 offset0:28 offset1:93
	s_waitcnt lgkmcnt(0)
	v_cvt_pk_bf16_f32 v6, v6, v7
	ds_read2_b32 v[8:9], v10 offset0:158 offset1:223
	s_waitcnt lgkmcnt(0)
	v_cvt_pk_bf16_f32 v7, v8, v9
	v_or_b32_e32 v8, s0, v114
	v_lshlrev_b32_e32 v68, 11, v8
	v_lshl_add_u64 v[8:9], v[2:3], 0, v[68:69]
	global_store_dwordx4 v[8:9], v[4:7], off
	ds_read2_b32 v[4:5], v111 offset0:32 offset1:97
	s_waitcnt lgkmcnt(0)
	v_cvt_pk_bf16_f32 v4, v4, v5
	ds_read2_b32 v[6:7], v111 offset0:162 offset1:227
	s_waitcnt lgkmcnt(0)
	v_cvt_pk_bf16_f32 v5, v6, v7
	ds_read2_b32 v[6:7], v10 offset0:36 offset1:101
	s_waitcnt lgkmcnt(0)
	v_cvt_pk_bf16_f32 v6, v6, v7
	ds_read2_b32 v[8:9], v10 offset0:166 offset1:231
	s_waitcnt lgkmcnt(0)
	v_cvt_pk_bf16_f32 v7, v8, v9
	v_or_b32_e32 v8, s0, v115
	v_lshlrev_b32_e32 v68, 11, v8
	v_lshl_add_u64 v[8:9], v[2:3], 0, v[68:69]
	global_store_dwordx4 v[8:9], v[4:7], off
	ds_read2_b32 v[4:5], v111 offset0:40 offset1:105
	s_waitcnt lgkmcnt(0)
	v_cvt_pk_bf16_f32 v4, v4, v5
	ds_read2_b32 v[6:7], v111 offset0:170 offset1:235
	s_waitcnt lgkmcnt(0)
	v_cvt_pk_bf16_f32 v5, v6, v7
	ds_read2_b32 v[6:7], v10 offset0:44 offset1:109
	s_waitcnt lgkmcnt(0)
	v_cvt_pk_bf16_f32 v6, v6, v7
	ds_read2_b32 v[8:9], v10 offset0:174 offset1:239
	s_waitcnt lgkmcnt(0)
	v_cvt_pk_bf16_f32 v7, v8, v9
	v_or_b32_e32 v8, s0, v116
	v_lshlrev_b32_e32 v68, 11, v8
	v_lshl_add_u64 v[8:9], v[2:3], 0, v[68:69]
	global_store_dwordx4 v[8:9], v[4:7], off
	ds_read2_b32 v[4:5], v111 offset0:48 offset1:113
	s_waitcnt lgkmcnt(0)
	v_cvt_pk_bf16_f32 v4, v4, v5
	ds_read2_b32 v[6:7], v111 offset0:178 offset1:243
	s_waitcnt lgkmcnt(0)
	v_cvt_pk_bf16_f32 v5, v6, v7
	ds_read2_b32 v[6:7], v10 offset0:52 offset1:117
	s_waitcnt lgkmcnt(0)
	v_cvt_pk_bf16_f32 v6, v6, v7
	ds_read2_b32 v[8:9], v10 offset0:182 offset1:247
	s_waitcnt lgkmcnt(0)
	v_cvt_pk_bf16_f32 v7, v8, v9
	v_or_b32_e32 v8, s0, v117
	v_lshlrev_b32_e32 v68, 11, v8
	v_lshl_add_u64 v[8:9], v[2:3], 0, v[68:69]
	global_store_dwordx4 v[8:9], v[4:7], off
	ds_read2_b32 v[4:5], v111 offset0:56 offset1:121
	s_waitcnt lgkmcnt(0)
	v_cvt_pk_bf16_f32 v4, v4, v5
	ds_read2_b32 v[6:7], v111 offset0:186 offset1:251
	s_waitcnt lgkmcnt(0)
	v_cvt_pk_bf16_f32 v5, v6, v7
	ds_read2_b32 v[6:7], v10 offset0:60 offset1:125
	s_waitcnt lgkmcnt(0)
	v_cvt_pk_bf16_f32 v6, v6, v7
	ds_read2_b32 v[8:9], v10 offset0:190 offset1:255
	s_waitcnt lgkmcnt(0)
	v_cvt_pk_bf16_f32 v7, v8, v9
	v_or_b32_e32 v8, s0, v118
	v_lshlrev_b32_e32 v68, 11, v8
	v_lshl_add_u64 v[2:3], v[2:3], 0, v[68:69]
	global_store_dwordx4 v[2:3], v[4:7], off
	s_waitcnt lgkmcnt(0)

.LBB0_549:
	s_andn2_b64 vcc, exec, s[0:1]
	s_cbranch_vccnz .LBB0_575
	s_add_i32 s0, s29, 0xfd40
	s_and_b32 s1, s0, 0xffff
	s_mul_i32 s1, s1, 0xba2f
	s_lshr_b32 s1, s1, 21
	s_mul_i32 s2, s1, 44
	s_sub_i32 s24, s0, s2
	s_lshl_b32 s3, s1, 6
	v_or_b32_e32 v107, s3, v66
	s_lshl_b32 s0, s24, 8
	s_and_b32 s12, s0, 0x3ff00
	s_waitcnt vmcnt(0)
	v_mul_u32_u24_e32 v6, 0xb00, v107
	v_lshl_add_u64 v[2:3], v[102:103], 0, s[12:13]
	v_lshlrev_b32_e32 v68, 2, v6
	v_mad_u64_u32 v[4:5], s[0:1], v107, s45, v[2:3]
	v_lshl_add_u64 v[2:3], v[2:3], 0, v[68:69]
	v_add_co_u32_e32 v6, vcc, s46, v2
	v_cndmask_b32_e64 v68, 0, 1, s[8:9]
	s_nop 0
	v_addc_co_u32_e32 v7, vcc, 0, v3, vcc
	global_load_dwordx4 v[62:65], v[4:5], off nt
	global_load_dwordx4 v[58:61], v[6:7], off nt
	v_add_co_u32_e32 v4, vcc, s47, v2
	v_cmp_ne_u32_e64 s[0:1], 1, v68
	s_nop 0
	v_addc_co_u32_e32 v5, vcc, 0, v3, vcc
	v_add_co_u32_e32 v6, vcc, s48, v2
	v_add_lshl_u32 v106, s3, v66, 2
	s_nop 0
	v_addc_co_u32_e32 v7, vcc, 0, v3, vcc
	global_load_dwordx4 v[54:57], v[4:5], off nt
	global_load_dwordx4 v[50:53], v[6:7], off nt
	v_add_co_u32_e32 v4, vcc, s49, v2
	s_nop 1
	v_addc_co_u32_e32 v5, vcc, 0, v3, vcc
	v_add_co_u32_e32 v6, vcc, s50, v2
	s_nop 1
	v_addc_co_u32_e32 v7, vcc, 0, v3, vcc
	global_load_dwordx4 v[46:49], v[4:5], off nt
	global_load_dwordx4 v[42:45], v[6:7], off nt
	v_add_co_u32_e32 v4, vcc, s51, v2
	s_nop 1
	v_addc_co_u32_e32 v5, vcc, 0, v3, vcc
	v_add_co_u32_e32 v6, vcc, s62, v2
	s_nop 1
	v_addc_co_u32_e32 v7, vcc, 0, v3, vcc
	global_load_dwordx4 v[38:41], v[4:5], off nt
	global_load_dwordx4 v[34:37], v[6:7], off nt
	v_add_co_u32_e32 v4, vcc, s63, v2
	s_nop 1
	v_addc_co_u32_e32 v5, vcc, 0, v3, vcc
	v_add_co_u32_e32 v6, vcc, s64, v2
	s_nop 1
	v_addc_co_u32_e32 v7, vcc, 0, v3, vcc
	global_load_dwordx4 v[30:33], v[4:5], off nt
	global_load_dwordx4 v[26:29], v[6:7], off nt
	v_add_co_u32_e32 v4, vcc, s65, v2
	s_nop 1
	v_addc_co_u32_e32 v5, vcc, 0, v3, vcc
	v_add_co_u32_e32 v6, vcc, s66, v2
	s_nop 1
	v_addc_co_u32_e32 v7, vcc, 0, v3, vcc
	global_load_dwordx4 v[22:25], v[4:5], off nt
	global_load_dwordx4 v[18:21], v[6:7], off nt
	v_add_co_u32_e32 v4, vcc, s67, v2
	s_nop 1
	v_addc_co_u32_e32 v5, vcc, 0, v3, vcc
	v_add_co_u32_e32 v6, vcc, 0x8f000, v2
	s_nop 1
	v_addc_co_u32_e32 v7, vcc, 0, v3, vcc
	global_load_dwordx4 v[14:17], v[4:5], off nt
	global_load_dwordx4 v[10:13], v[6:7], off nt
	v_add_co_u32_e32 v4, vcc, 0x9a000, v2
	s_nop 1
	v_addc_co_u32_e32 v5, vcc, 0, v3, vcc
	v_add_co_u32_e32 v2, vcc, 0xa5000, v2
	s_nop 1
	v_addc_co_u32_e32 v3, vcc, 0, v3, vcc
	global_load_dwordx4 v[6:9], v[4:5], off nt
	s_nop 0
	global_load_dwordx4 v[2:5], v[2:3], off nt
	s_andn2_b64 vcc, exec, s[8:9]
	s_cbranch_vccnz .LBB0_624
	v_readlane_b32 s80, v254, 10
	v_lshlrev_b32_e32 v68, 2, v107
	v_readlane_b32 s90, v254, 20
	v_readlane_b32 s91, v254, 21
	v_readlane_b32 s81, v254, 11
	v_readlane_b32 s82, v254, 12
	v_readlane_b32 s83, v254, 13
	v_readlane_b32 s84, v254, 14
	s_nop 0
	global_load_dword v188, v68, s[90:91]
	global_load_dword v190, v106, s[90:91] offset:16
	global_load_dword v192, v106, s[90:91] offset:32
	global_load_dword v194, v106, s[90:91] offset:48
	global_load_dword v196, v106, s[90:91] offset:64
	global_load_dword v198, v106, s[90:91] offset:80
	global_load_dword v200, v106, s[90:91] offset:96
	global_load_dword v202, v106, s[90:91] offset:112
	global_load_dword v204, v106, s[90:91] offset:128
	global_load_dword v206, v106, s[90:91] offset:144
	global_load_dword v208, v106, s[90:91] offset:160
	global_load_dword v210, v106, s[90:91] offset:176
	global_load_dword v212, v106, s[90:91] offset:192
	global_load_dword v214, v106, s[90:91] offset:208
	global_load_dword v216, v106, s[90:91] offset:224
	global_load_dword v218, v106, s[90:91] offset:240
	v_readlane_b32 s85, v254, 15
	v_readlane_b32 s86, v254, 16
	v_readlane_b32 s87, v254, 17
	v_readlane_b32 s88, v254, 18
	v_readlane_b32 s89, v254, 19
	v_readlane_b32 s92, v254, 22
	v_readlane_b32 s93, v254, 23
	v_readlane_b32 s94, v254, 24
	v_readlane_b32 s95, v254, 25
	s_waitcnt vmcnt(0)
	v_pk_mul_f32 v[130:131], v[62:63], v[188:189] op_sel_hi:[1,0]
	ds_write2_b32 v109, v130, v131 offset1:1
	v_pk_mul_f32 v[130:131], v[64:65], v[188:189] op_sel_hi:[1,0]
	ds_write2_b32 v109, v130, v131 offset0:2 offset1:3
	s_cbranch_execnz .LBB0_553

.LBB0_553:
	s_waitcnt vmcnt(0)
	v_pk_mul_f32 v[58:59], v[58:59], v[190:191] op_sel_hi:[1,0]
	v_add_u32_e32 v62, v108, v119
	ds_write2_b32 v62, v58, v59 offset1:1
	v_pk_mul_f32 v[58:59], v[60:61], v[190:191] op_sel_hi:[1,0]
	s_and_b64 vcc, exec, s[0:1]
	ds_write2_b32 v62, v58, v59 offset0:2 offset1:3
	s_cbranch_vccnz .LBB0_625
	v_readlane_b32 s80, v254, 10
	v_readlane_b32 s90, v254, 20
	v_readlane_b32 s91, v254, 21
	v_add_u32_e32 v62, v108, v120
	v_readlane_b32 s81, v254, 11
	v_readlane_b32 s82, v254, 12
	v_readlane_b32 s83, v254, 13
	s_nop 0
	v_readlane_b32 s84, v254, 14
	v_readlane_b32 s85, v254, 15
	v_readlane_b32 s86, v254, 16
	v_readlane_b32 s87, v254, 17
	v_readlane_b32 s88, v254, 18
	v_readlane_b32 s89, v254, 19
	v_readlane_b32 s92, v254, 22
	v_readlane_b32 s93, v254, 23
	v_readlane_b32 s94, v254, 24
	v_readlane_b32 s95, v254, 25
	s_waitcnt vmcnt(0)
	v_pk_mul_f32 v[60:61], v[54:55], v[192:193] op_sel_hi:[1,0]
	v_pk_mul_f32 v[58:59], v[56:57], v[192:193] op_sel_hi:[1,0]
	ds_write2_b32 v62, v58, v59 offset0:2 offset1:3
	ds_write2_b32 v62, v60, v61 offset1:1
	s_cbranch_execnz .LBB0_556

.LBB0_556:
	s_waitcnt vmcnt(0)
	v_pk_mul_f32 v[50:51], v[50:51], v[194:195] op_sel_hi:[1,0]
	v_add_u32_e32 v54, v108, v121
	ds_write2_b32 v54, v50, v51 offset1:1
	v_pk_mul_f32 v[50:51], v[52:53], v[194:195] op_sel_hi:[1,0]
	s_and_b64 vcc, exec, s[0:1]
	ds_write2_b32 v54, v50, v51 offset0:2 offset1:3
	s_cbranch_vccnz .LBB0_626
	v_readlane_b32 s80, v254, 10
	v_readlane_b32 s90, v254, 20
	v_readlane_b32 s91, v254, 21
	v_add_u32_e32 v54, v108, v122
	v_readlane_b32 s81, v254, 11
	v_readlane_b32 s82, v254, 12
	v_readlane_b32 s83, v254, 13
	s_nop 0
	v_readlane_b32 s84, v254, 14
	v_readlane_b32 s85, v254, 15
	v_readlane_b32 s86, v254, 16
	v_readlane_b32 s87, v254, 17
	v_readlane_b32 s88, v254, 18
	v_readlane_b32 s89, v254, 19
	v_readlane_b32 s92, v254, 22
	v_readlane_b32 s93, v254, 23
	v_readlane_b32 s94, v254, 24
	v_readlane_b32 s95, v254, 25
	s_waitcnt vmcnt(0)
	v_pk_mul_f32 v[52:53], v[46:47], v[196:197] op_sel_hi:[1,0]
	v_pk_mul_f32 v[50:51], v[48:49], v[196:197] op_sel_hi:[1,0]
	ds_write2_b32 v54, v50, v51 offset0:2 offset1:3
	ds_write2_b32 v54, v52, v53 offset1:1
	s_cbranch_execnz .LBB0_559

.LBB0_559:
	s_waitcnt vmcnt(0)
	v_pk_mul_f32 v[42:43], v[42:43], v[198:199] op_sel_hi:[1,0]
	v_add_u32_e32 v46, v108, v123
	ds_write2_b32 v46, v42, v43 offset1:1
	v_pk_mul_f32 v[42:43], v[44:45], v[198:199] op_sel_hi:[1,0]
	s_and_b64 vcc, exec, s[0:1]
	ds_write2_b32 v46, v42, v43 offset0:2 offset1:3
	s_cbranch_vccnz .LBB0_627
	v_readlane_b32 s80, v254, 10
	v_readlane_b32 s90, v254, 20
	v_readlane_b32 s91, v254, 21
	v_add_u32_e32 v46, v108, v124
	v_readlane_b32 s81, v254, 11
	v_readlane_b32 s82, v254, 12
	v_readlane_b32 s83, v254, 13
	s_nop 0
	v_readlane_b32 s84, v254, 14
	v_readlane_b32 s85, v254, 15
	v_readlane_b32 s86, v254, 16
	v_readlane_b32 s87, v254, 17
	v_readlane_b32 s88, v254, 18
	v_readlane_b32 s89, v254, 19
	v_readlane_b32 s92, v254, 22
	v_readlane_b32 s93, v254, 23
	v_readlane_b32 s94, v254, 24
	v_readlane_b32 s95, v254, 25
	s_waitcnt vmcnt(0)
	v_pk_mul_f32 v[44:45], v[38:39], v[200:201] op_sel_hi:[1,0]
	v_pk_mul_f32 v[42:43], v[40:41], v[200:201] op_sel_hi:[1,0]
	ds_write2_b32 v46, v42, v43 offset0:2 offset1:3
	ds_write2_b32 v46, v44, v45 offset1:1
	s_cbranch_execnz .LBB0_562

.LBB0_562:
	s_waitcnt vmcnt(0)
	v_pk_mul_f32 v[34:35], v[34:35], v[202:203] op_sel_hi:[1,0]
	v_add_u32_e32 v38, v108, v125
	ds_write2_b32 v38, v34, v35 offset1:1
	v_pk_mul_f32 v[34:35], v[36:37], v[202:203] op_sel_hi:[1,0]
	s_and_b64 vcc, exec, s[0:1]
	ds_write2_b32 v38, v34, v35 offset0:2 offset1:3
	s_cbranch_vccnz .LBB0_628
	v_readlane_b32 s80, v254, 10
	v_readlane_b32 s90, v254, 20
	v_readlane_b32 s91, v254, 21
	v_add_u32_e32 v38, v108, v126
	v_readlane_b32 s81, v254, 11
	v_readlane_b32 s82, v254, 12
	v_readlane_b32 s83, v254, 13
	s_nop 0
	v_readlane_b32 s84, v254, 14
	v_readlane_b32 s85, v254, 15
	v_readlane_b32 s86, v254, 16
	v_readlane_b32 s87, v254, 17
	v_readlane_b32 s88, v254, 18
	v_readlane_b32 s89, v254, 19
	v_readlane_b32 s92, v254, 22
	v_readlane_b32 s93, v254, 23
	v_readlane_b32 s94, v254, 24
	v_readlane_b32 s95, v254, 25
	s_waitcnt vmcnt(0)
	v_pk_mul_f32 v[36:37], v[30:31], v[204:205] op_sel_hi:[1,0]
	v_pk_mul_f32 v[34:35], v[32:33], v[204:205] op_sel_hi:[1,0]
	ds_write2_b32 v38, v34, v35 offset0:2 offset1:3
	ds_write2_b32 v38, v36, v37 offset1:1
	s_cbranch_execnz .LBB0_565

.LBB0_565:
	s_waitcnt vmcnt(0)
	v_pk_mul_f32 v[26:27], v[26:27], v[206:207] op_sel_hi:[1,0]
	v_add_u32_e32 v30, v108, v127
	ds_write2_b32 v30, v26, v27 offset1:1
	v_pk_mul_f32 v[26:27], v[28:29], v[206:207] op_sel_hi:[1,0]
	s_and_b64 vcc, exec, s[0:1]
	ds_write2_b32 v30, v26, v27 offset0:2 offset1:3
	s_cbranch_vccnz .LBB0_629
	v_readlane_b32 s80, v254, 10
	v_readlane_b32 s90, v254, 20
	v_readlane_b32 s91, v254, 21
	v_add_u32_e32 v30, v108, v128
	v_readlane_b32 s81, v254, 11
	v_readlane_b32 s82, v254, 12
	v_readlane_b32 s83, v254, 13
	s_nop 0
	v_readlane_b32 s84, v254, 14
	v_readlane_b32 s85, v254, 15
	v_readlane_b32 s86, v254, 16
	v_readlane_b32 s87, v254, 17
	v_readlane_b32 s88, v254, 18
	v_readlane_b32 s89, v254, 19
	v_readlane_b32 s92, v254, 22
	v_readlane_b32 s93, v254, 23
	v_readlane_b32 s94, v254, 24
	v_readlane_b32 s95, v254, 25
	s_waitcnt vmcnt(0)
	v_pk_mul_f32 v[28:29], v[22:23], v[208:209] op_sel_hi:[1,0]
	v_pk_mul_f32 v[26:27], v[24:25], v[208:209] op_sel_hi:[1,0]
	ds_write2_b32 v30, v26, v27 offset0:2 offset1:3
	ds_write2_b32 v30, v28, v29 offset1:1
	s_cbranch_execnz .LBB0_568

.LBB0_568:
	s_waitcnt vmcnt(0)
	v_pk_mul_f32 v[22:23], v[18:19], v[210:211] op_sel_hi:[1,0]
	v_add_u32_e32 v19, v108, v129
	v_pk_mul_f32 v[20:21], v[20:21], v[210:211] op_sel_hi:[1,0]
	ds_write2_b32 v19, v20, v21 offset0:2 offset1:3
	s_and_b64 vcc, exec, s[0:1]
	v_add_u32_e32 v20, 0x410, v19
	v_add_u32_e32 v21, 0x418, v19
	ds_write2_b32 v19, v22, v23 offset1:1
	s_cbranch_vccnz .LBB0_630
	v_readlane_b32 s80, v254, 10
	v_readlane_b32 s90, v254, 20
	v_readlane_b32 s91, v254, 21
	v_readlane_b32 s81, v254, 11
	v_readlane_b32 s82, v254, 12
	v_readlane_b32 s83, v254, 13
	v_readlane_b32 s84, v254, 14
	s_nop 0
	v_readlane_b32 s85, v254, 15
	v_readlane_b32 s86, v254, 16
	v_readlane_b32 s87, v254, 17
	v_readlane_b32 s88, v254, 18
	v_readlane_b32 s89, v254, 19
	v_readlane_b32 s92, v254, 22
	v_readlane_b32 s93, v254, 23
	v_readlane_b32 s94, v254, 24
	v_readlane_b32 s95, v254, 25
	s_waitcnt vmcnt(0)
	v_pk_mul_f32 v[22:23], v[14:15], v[212:213] op_sel_hi:[1,0]
	ds_write2_b32 v20, v22, v23 offset1:1
	v_pk_mul_f32 v[22:23], v[16:17], v[212:213] op_sel_hi:[1,0]
	ds_write2_b32 v21, v22, v23 offset1:1
	s_cbranch_execnz .LBB0_571

.LBB0_571:
	s_waitcnt vmcnt(0)
	v_pk_mul_f32 v[10:11], v[10:11], v[214:215] op_sel_hi:[1,0]
	v_add_u32_e32 v14, 0x820, v19
	ds_write2_b32 v14, v10, v11 offset1:1
	v_pk_mul_f32 v[10:11], v[12:13], v[214:215] op_sel_hi:[1,0]
	v_add_u32_e32 v12, 0x828, v19
	ds_write2_b32 v12, v10, v11 offset1:1
	s_and_b64 vcc, exec, s[0:1]
	v_add_u32_e32 v11, 0xc30, v19
	v_add_u32_e32 v12, 0xc38, v19
	s_cbranch_vccnz .LBB0_631
	v_readlane_b32 s80, v254, 10
	v_readlane_b32 s90, v254, 20
	v_readlane_b32 s91, v254, 21
	v_readlane_b32 s81, v254, 11
	v_readlane_b32 s82, v254, 12
	v_readlane_b32 s83, v254, 13
	v_readlane_b32 s84, v254, 14
	s_nop 0
	v_readlane_b32 s85, v254, 15
	v_readlane_b32 s86, v254, 16
	v_readlane_b32 s87, v254, 17
	v_readlane_b32 s88, v254, 18
	v_readlane_b32 s89, v254, 19
	v_readlane_b32 s92, v254, 22
	v_readlane_b32 s93, v254, 23
	v_readlane_b32 s94, v254, 24
	v_readlane_b32 s95, v254, 25
	s_waitcnt vmcnt(0)
	v_pk_mul_f32 v[14:15], v[6:7], v[216:217] op_sel_hi:[1,0]
	ds_write2_b32 v11, v14, v15 offset1:1
	v_pk_mul_f32 v[14:15], v[8:9], v[216:217] op_sel_hi:[1,0]
	ds_write2_b32 v12, v14, v15 offset1:1
	s_cbranch_execnz .LBB0_574

.LBB0_574:
	s_waitcnt vmcnt(0)
	v_pk_mul_f32 v[2:3], v[2:3], v[218:219] op_sel_hi:[1,0]
	v_add_u32_e32 v6, 0x1040, v19
	ds_write2_b32 v6, v2, v3 offset1:1
	v_pk_mul_f32 v[2:3], v[4:5], v[218:219] op_sel_hi:[1,0]
	v_add_u32_e32 v4, 0x1048, v19
	ds_write2_b32 v4, v2, v3 offset1:1
	s_lshl_b32 s0, s24, 6
	s_waitcnt lgkmcnt(0)
	s_and_b32 s0, 0xffff, s0
	s_lshl_b32 s1, s0, 1
	ds_read2_b32 v[4:5], v111 offset1:65
	s_and_b32 s1, s1, 0x1f00
	s_and_b32 s0, s0, 64
	s_waitcnt lgkmcnt(0)
	v_cvt_pk_bf16_f32 v4, v4, v5
	ds_read2_b32 v[6:7], v111 offset0:130 offset1:195
	v_add_u32_e32 v10, 0x400, v111
	s_or_b32 s0, s0, s1
	s_waitcnt lgkmcnt(0)
	v_cvt_pk_bf16_f32 v5, v6, v7
	ds_read2_b32 v[6:7], v10 offset0:4 offset1:69
	s_bitset1_b32 s0, 7
	s_waitcnt lgkmcnt(0)
	v_cvt_pk_bf16_f32 v6, v6, v7
	ds_read2_b32 v[8:9], v10 offset0:134 offset1:199
	s_lshl_b32 s12, s3, 1
	s_waitcnt lgkmcnt(0)
	v_cvt_pk_bf16_f32 v7, v8, v9
	v_or_b32_e32 v8, s0, v110
	v_lshl_add_u64 v[2:3], v[84:85], 0, s[12:13]
	v_lshlrev_b32_e32 v68, 11, v8
	v_lshl_add_u64 v[8:9], v[2:3], 0, v[68:69]
	global_store_dwordx4 v[8:9], v[4:7], off
	ds_read2_b32 v[4:5], v111 offset0:8 offset1:73
	s_waitcnt lgkmcnt(0)
	v_cvt_pk_bf16_f32 v4, v4, v5
	ds_read2_b32 v[6:7], v111 offset0:138 offset1:203
	s_waitcnt lgkmcnt(0)
	v_cvt_pk_bf16_f32 v5, v6, v7
	ds_read2_b32 v[6:7], v10 offset0:12 offset1:77
	s_waitcnt lgkmcnt(0)
	v_cvt_pk_bf16_f32 v6, v6, v7
	ds_read2_b32 v[8:9], v10 offset0:142 offset1:207
	s_waitcnt lgkmcnt(0)
	v_cvt_pk_bf16_f32 v7, v8, v9
	v_or_b32_e32 v8, s0, v112
	v_lshlrev_b32_e32 v68, 11, v8
	v_lshl_add_u64 v[8:9], v[2:3], 0, v[68:69]
	global_store_dwordx4 v[8:9], v[4:7], off
	ds_read2_b32 v[4:5], v111 offset0:16 offset1:81
	s_waitcnt lgkmcnt(0)
	v_cvt_pk_bf16_f32 v4, v4, v5
	ds_read2_b32 v[6:7], v111 offset0:146 offset1:211
	s_waitcnt lgkmcnt(0)
	v_cvt_pk_bf16_f32 v5, v6, v7
	ds_read2_b32 v[6:7], v10 offset0:20 offset1:85
	s_waitcnt lgkmcnt(0)
	v_cvt_pk_bf16_f32 v6, v6, v7
	ds_read2_b32 v[8:9], v10 offset0:150 offset1:215
	s_waitcnt lgkmcnt(0)
	v_cvt_pk_bf16_f32 v7, v8, v9
	v_or_b32_e32 v8, s0, v113
	v_lshlrev_b32_e32 v68, 11, v8
	v_lshl_add_u64 v[8:9], v[2:3], 0, v[68:69]
	global_store_dwordx4 v[8:9], v[4:7], off
	ds_read2_b32 v[4:5], v111 offset0:24 offset1:89
	s_waitcnt lgkmcnt(0)
	v_cvt_pk_bf16_f32 v4, v4, v5
	ds_read2_b32 v[6:7], v111 offset0:154 offset1:219
	s_waitcnt lgkmcnt(0)
	v_cvt_pk_bf16_f32 v5, v6, v7
	ds_read2_b32 v[6:7], v10 offset0:28 offset1:93
	s_waitcnt lgkmcnt(0)
	v_cvt_pk_bf16_f32 v6, v6, v7
	ds_read2_b32 v[8:9], v10 offset0:158 offset1:223
	s_waitcnt lgkmcnt(0)
	v_cvt_pk_bf16_f32 v7, v8, v9
	v_or_b32_e32 v8, s0, v114
	v_lshlrev_b32_e32 v68, 11, v8
	v_lshl_add_u64 v[8:9], v[2:3], 0, v[68:69]
	global_store_dwordx4 v[8:9], v[4:7], off
	ds_read2_b32 v[4:5], v111 offset0:32 offset1:97
	s_waitcnt lgkmcnt(0)
	v_cvt_pk_bf16_f32 v4, v4, v5
	ds_read2_b32 v[6:7], v111 offset0:162 offset1:227
	s_waitcnt lgkmcnt(0)
	v_cvt_pk_bf16_f32 v5, v6, v7
	ds_read2_b32 v[6:7], v10 offset0:36 offset1:101
	s_waitcnt lgkmcnt(0)
	v_cvt_pk_bf16_f32 v6, v6, v7
	ds_read2_b32 v[8:9], v10 offset0:166 offset1:231
	s_waitcnt lgkmcnt(0)
	v_cvt_pk_bf16_f32 v7, v8, v9
	v_or_b32_e32 v8, s0, v115
	v_lshlrev_b32_e32 v68, 11, v8
	v_lshl_add_u64 v[8:9], v[2:3], 0, v[68:69]
	global_store_dwordx4 v[8:9], v[4:7], off
	ds_read2_b32 v[4:5], v111 offset0:40 offset1:105
	s_waitcnt lgkmcnt(0)
	v_cvt_pk_bf16_f32 v4, v4, v5
	ds_read2_b32 v[6:7], v111 offset0:170 offset1:235
	s_waitcnt lgkmcnt(0)
	v_cvt_pk_bf16_f32 v5, v6, v7
	ds_read2_b32 v[6:7], v10 offset0:44 offset1:109
	s_waitcnt lgkmcnt(0)
	v_cvt_pk_bf16_f32 v6, v6, v7
	ds_read2_b32 v[8:9], v10 offset0:174 offset1:239
	s_waitcnt lgkmcnt(0)
	v_cvt_pk_bf16_f32 v7, v8, v9
	v_or_b32_e32 v8, s0, v116
	v_lshlrev_b32_e32 v68, 11, v8
	v_lshl_add_u64 v[8:9], v[2:3], 0, v[68:69]
	global_store_dwordx4 v[8:9], v[4:7], off
	ds_read2_b32 v[4:5], v111 offset0:48 offset1:113
	s_waitcnt lgkmcnt(0)
	v_cvt_pk_bf16_f32 v4, v4, v5
	ds_read2_b32 v[6:7], v111 offset0:178 offset1:243
	s_waitcnt lgkmcnt(0)
	v_cvt_pk_bf16_f32 v5, v6, v7
	ds_read2_b32 v[6:7], v10 offset0:52 offset1:117
	s_waitcnt lgkmcnt(0)
	v_cvt_pk_bf16_f32 v6, v6, v7
	ds_read2_b32 v[8:9], v10 offset0:182 offset1:247
	s_waitcnt lgkmcnt(0)
	v_cvt_pk_bf16_f32 v7, v8, v9
	v_or_b32_e32 v8, s0, v117
	v_lshlrev_b32_e32 v68, 11, v8
	v_lshl_add_u64 v[8:9], v[2:3], 0, v[68:69]
	global_store_dwordx4 v[8:9], v[4:7], off
	ds_read2_b32 v[4:5], v111 offset0:56 offset1:121
	s_waitcnt lgkmcnt(0)
	v_cvt_pk_bf16_f32 v4, v4, v5
	ds_read2_b32 v[6:7], v111 offset0:186 offset1:251
	s_waitcnt lgkmcnt(0)
	v_cvt_pk_bf16_f32 v5, v6, v7
	ds_read2_b32 v[6:7], v10 offset0:60 offset1:125
	s_waitcnt lgkmcnt(0)
	v_cvt_pk_bf16_f32 v6, v6, v7
	ds_read2_b32 v[8:9], v10 offset0:190 offset1:255
	s_waitcnt lgkmcnt(0)
	v_cvt_pk_bf16_f32 v7, v8, v9
	v_or_b32_e32 v8, s0, v118
	v_lshlrev_b32_e32 v68, 11, v8
	v_lshl_add_u64 v[2:3], v[2:3], 0, v[68:69]
	global_store_dwordx4 v[2:3], v[4:7], off
	s_waitcnt lgkmcnt(0)

.LBB0_1514:
	s_cmpk_gt_i32 s3, 0x83f
	s_mov_b64 s[0:1], -1
	s_cbranch_scc0 .LBB0_1567
	s_add_i32 s14, s3, 0xfffff7c0
	s_cmpk_gt_u32 s14, 0x2bf
	s_mov_b64 s[10:11], -1
	v_cmp_ne_u32_e64 s[0:1], 1, v110
	s_cbranch_scc0 .LBB0_1541
	s_add_i32 s4, s14, 0xfd40
	s_and_b32 s10, s4, 0xffff
	s_mul_i32 s10, s10, 0xba2f
	s_lshr_b32 s10, s10, 21
	s_mul_i32 s11, s10, 44
	s_sub_i32 s16, s4, s11
	s_lshl_b32 s15, s10, 6
	v_or_b32_e32 v87, s15, v66
	s_lshl_b32 s4, s16, 8
	s_and_b32 s4, s4, 0x3ff00
	s_waitcnt vmcnt(0)
	v_mul_u32_u24_e32 v6, 0xb00, v87
	v_lshl_add_u64 v[2:3], v[76:77], 0, s[4:5]
	v_lshlrev_b32_e32 v68, 2, v6
	v_mad_u64_u32 v[4:5], s[10:11], v87, s28, v[2:3]
	v_lshl_add_u64 v[2:3], v[2:3], 0, v[68:69]
	v_add_co_u32_e32 v6, vcc, s29, v2
	v_add_lshl_u32 v86, s15, v66, 2
	s_nop 0
	v_addc_co_u32_e32 v7, vcc, 0, v3, vcc
	global_load_dwordx4 v[62:65], v[4:5], off nt
	global_load_dwordx4 v[58:61], v[6:7], off nt
	v_add_co_u32_e32 v4, vcc, s30, v2
	s_nop 1
	v_addc_co_u32_e32 v5, vcc, 0, v3, vcc
	v_add_co_u32_e32 v6, vcc, s31, v2
	s_nop 1
	v_addc_co_u32_e32 v7, vcc, 0, v3, vcc
	global_load_dwordx4 v[54:57], v[4:5], off nt
	global_load_dwordx4 v[50:53], v[6:7], off nt
	v_add_co_u32_e32 v4, vcc, s34, v2
	s_nop 1
	v_addc_co_u32_e32 v5, vcc, 0, v3, vcc
	v_add_co_u32_e32 v6, vcc, s35, v2
	s_nop 1
	v_addc_co_u32_e32 v7, vcc, 0, v3, vcc
	global_load_dwordx4 v[46:49], v[4:5], off nt
	global_load_dwordx4 v[42:45], v[6:7], off nt
	v_add_co_u32_e32 v4, vcc, s38, v2
	s_nop 1
	v_addc_co_u32_e32 v5, vcc, 0, v3, vcc
	v_add_co_u32_e32 v6, vcc, s39, v2
	s_nop 1
	v_addc_co_u32_e32 v7, vcc, 0, v3, vcc
	global_load_dwordx4 v[38:41], v[4:5], off nt
	global_load_dwordx4 v[34:37], v[6:7], off nt
	v_add_co_u32_e32 v4, vcc, s40, v2
	s_nop 1
	v_addc_co_u32_e32 v5, vcc, 0, v3, vcc
	v_add_co_u32_e32 v6, vcc, s41, v2
	s_nop 1
	v_addc_co_u32_e32 v7, vcc, 0, v3, vcc
	global_load_dwordx4 v[30:33], v[4:5], off nt
	global_load_dwordx4 v[26:29], v[6:7], off nt
	v_add_co_u32_e32 v4, vcc, s44, v2
	s_nop 1
	v_addc_co_u32_e32 v5, vcc, 0, v3, vcc
	v_add_co_u32_e32 v6, vcc, s45, v2
	s_nop 1
	v_addc_co_u32_e32 v7, vcc, 0, v3, vcc
	global_load_dwordx4 v[22:25], v[4:5], off nt
	global_load_dwordx4 v[18:21], v[6:7], off nt
	v_add_co_u32_e32 v4, vcc, s46, v2
	s_nop 1
	v_addc_co_u32_e32 v5, vcc, 0, v3, vcc
	v_add_co_u32_e32 v6, vcc, 0x8f000, v2
	s_nop 1
	v_addc_co_u32_e32 v7, vcc, 0, v3, vcc
	global_load_dwordx4 v[14:17], v[4:5], off nt
	global_load_dwordx4 v[10:13], v[6:7], off nt
	v_add_co_u32_e32 v4, vcc, 0x9a000, v2
	s_nop 1
	v_addc_co_u32_e32 v5, vcc, 0, v3, vcc
	v_add_co_u32_e32 v2, vcc, 0xa5000, v2
	s_nop 1
	v_addc_co_u32_e32 v3, vcc, 0, v3, vcc
	global_load_dwordx4 v[6:9], v[4:5], off nt
	s_nop 0
	global_load_dwordx4 v[2:5], v[2:3], off nt
	s_and_b64 vcc, exec, s[0:1]
	s_cbranch_vccnz .LBB0_1623
	v_readlane_b32 s72, v254, 45
	v_lshlrev_b32_e32 v68, 2, v87
	v_readlane_b32 s86, v254, 59
	v_readlane_b32 s87, v254, 60
	s_nop 4
	global_load_dword v188, v68, s[86:87]
	global_load_dword v190, v86, s[86:87] offset:16
	global_load_dword v192, v86, s[86:87] offset:32
	global_load_dword v194, v86, s[86:87] offset:48
	global_load_dword v196, v86, s[86:87] offset:64
	global_load_dword v198, v86, s[86:87] offset:80
	global_load_dword v200, v86, s[86:87] offset:96
	global_load_dword v202, v86, s[86:87] offset:112
	global_load_dword v204, v86, s[86:87] offset:128
	global_load_dword v206, v86, s[86:87] offset:144
	global_load_dword v208, v86, s[86:87] offset:160
	global_load_dword v210, v86, s[86:87] offset:176
	global_load_dword v212, v86, s[86:87] offset:192
	global_load_dword v214, v86, s[86:87] offset:208
	global_load_dword v216, v86, s[86:87] offset:224
	global_load_dword v218, v86, s[86:87] offset:240
	s_nop 0
	v_add_u32_e32 v87, v88, v89
	v_readlane_b32 s73, v254, 46
	v_readlane_b32 s74, v254, 47
	v_readlane_b32 s75, v254, 48
	v_readlane_b32 s76, v254, 49
	v_readlane_b32 s77, v254, 50
	v_readlane_b32 s78, v254, 51
	v_readlane_b32 s79, v254, 52
	v_readlane_b32 s80, v254, 53
	v_readlane_b32 s81, v254, 54
	v_readlane_b32 s82, v254, 55
	v_readlane_b32 s83, v254, 56
	v_readlane_b32 s84, v254, 57
	v_readlane_b32 s85, v254, 58
	s_waitcnt vmcnt(0)
	v_pk_mul_f32 v[114:115], v[62:63], v[188:189] op_sel_hi:[1,0]
	v_pk_mul_f32 v[112:113], v[64:65], v[188:189] op_sel_hi:[1,0]
	ds_write2_b32 v87, v114, v115 offset1:1
	ds_write2_b32 v87, v112, v113 offset0:2 offset1:3
	s_cbranch_execnz .LBB0_1519
.LBB0_1518:
	s_waitcnt vmcnt(0)
	v_add_u32_e32 v68, v88, v89
	ds_write2_b32 v68, v62, v63 offset1:1
	ds_write2_b32 v68, v64, v65 offset0:2 offset1:3
	v_mov_b32_e32 v190, 1.0
.LBB0_1519:
	s_waitcnt vmcnt(0)
	v_pk_mul_f32 v[58:59], v[58:59], v[190:191] op_sel_hi:[1,0]
	v_add_u32_e32 v62, v88, v99
	ds_write2_b32 v62, v58, v59 offset1:1
	v_pk_mul_f32 v[58:59], v[60:61], v[190:191] op_sel_hi:[1,0]
	s_and_b64 vcc, exec, s[0:1]
	ds_write2_b32 v62, v58, v59 offset0:2 offset1:3
	s_cbranch_vccnz .LBB0_1624
	v_readlane_b32 s72, v254, 45
	v_readlane_b32 s86, v254, 59
	v_readlane_b32 s87, v254, 60
	s_nop 4
	v_add_u32_e32 v59, v88, v100
	v_readlane_b32 s73, v254, 46
	v_readlane_b32 s74, v254, 47
	v_readlane_b32 s75, v254, 48
	v_readlane_b32 s76, v254, 49
	v_readlane_b32 s77, v254, 50
	v_readlane_b32 s78, v254, 51
	v_readlane_b32 s79, v254, 52
	v_readlane_b32 s80, v254, 53
	v_readlane_b32 s81, v254, 54
	v_readlane_b32 s82, v254, 55
	v_readlane_b32 s83, v254, 56
	v_readlane_b32 s84, v254, 57
	v_readlane_b32 s85, v254, 58
	s_waitcnt vmcnt(1)
	v_pk_mul_f32 v[62:63], v[54:55], v[192:193] op_sel_hi:[1,0]
	v_pk_mul_f32 v[60:61], v[56:57], v[192:193] op_sel_hi:[1,0]
	ds_write2_b32 v59, v62, v63 offset1:1
	ds_write2_b32 v59, v60, v61 offset0:2 offset1:3
	s_cbranch_execnz .LBB0_1522
.LBB0_1521:
	s_waitcnt vmcnt(0)
	v_add_u32_e32 v58, v88, v100
	ds_write2_b32 v58, v54, v55 offset1:1
	ds_write2_b32 v58, v56, v57 offset0:2 offset1:3
	v_mov_b32_e32 v194, 1.0
.LBB0_1522:
	s_waitcnt vmcnt(0)
	v_pk_mul_f32 v[50:51], v[50:51], v[194:195] op_sel_hi:[1,0]
	v_add_u32_e32 v54, v88, v101
	ds_write2_b32 v54, v50, v51 offset1:1
	v_pk_mul_f32 v[50:51], v[52:53], v[194:195] op_sel_hi:[1,0]
	s_and_b64 vcc, exec, s[0:1]
	ds_write2_b32 v54, v50, v51 offset0:2 offset1:3
	s_cbranch_vccnz .LBB0_1625
	v_readlane_b32 s72, v254, 45
	v_readlane_b32 s86, v254, 59
	v_readlane_b32 s87, v254, 60
	s_nop 4
	v_add_u32_e32 v51, v88, v102
	v_readlane_b32 s73, v254, 46
	v_readlane_b32 s74, v254, 47
	v_readlane_b32 s75, v254, 48
	v_readlane_b32 s76, v254, 49
	v_readlane_b32 s77, v254, 50
	v_readlane_b32 s78, v254, 51
	v_readlane_b32 s79, v254, 52
	v_readlane_b32 s80, v254, 53
	v_readlane_b32 s81, v254, 54
	v_readlane_b32 s82, v254, 55
	v_readlane_b32 s83, v254, 56
	v_readlane_b32 s84, v254, 57
	v_readlane_b32 s85, v254, 58
	s_waitcnt vmcnt(1)
	v_pk_mul_f32 v[54:55], v[46:47], v[196:197] op_sel_hi:[1,0]
	v_pk_mul_f32 v[52:53], v[48:49], v[196:197] op_sel_hi:[1,0]
	ds_write2_b32 v51, v54, v55 offset1:1
	ds_write2_b32 v51, v52, v53 offset0:2 offset1:3
	s_cbranch_execnz .LBB0_1525
.LBB0_1524:
	s_waitcnt vmcnt(0)
	v_add_u32_e32 v50, v88, v102
	ds_write2_b32 v50, v46, v47 offset1:1
	ds_write2_b32 v50, v48, v49 offset0:2 offset1:3
	v_mov_b32_e32 v198, 1.0
.LBB0_1525:
	s_waitcnt vmcnt(0)
	v_pk_mul_f32 v[42:43], v[42:43], v[198:199] op_sel_hi:[1,0]
	v_add_u32_e32 v46, v88, v103
	ds_write2_b32 v46, v42, v43 offset1:1
	v_pk_mul_f32 v[42:43], v[44:45], v[198:199] op_sel_hi:[1,0]
	s_and_b64 vcc, exec, s[0:1]
	ds_write2_b32 v46, v42, v43 offset0:2 offset1:3
	s_cbranch_vccnz .LBB0_1626
	v_readlane_b32 s72, v254, 45
	v_readlane_b32 s86, v254, 59
	v_readlane_b32 s87, v254, 60
	s_nop 4
	v_add_u32_e32 v43, v88, v104
	v_readlane_b32 s73, v254, 46
	v_readlane_b32 s74, v254, 47
	v_readlane_b32 s75, v254, 48
	v_readlane_b32 s76, v254, 49
	v_readlane_b32 s77, v254, 50
	v_readlane_b32 s78, v254, 51
	v_readlane_b32 s79, v254, 52
	v_readlane_b32 s80, v254, 53
	v_readlane_b32 s81, v254, 54
	v_readlane_b32 s82, v254, 55
	v_readlane_b32 s83, v254, 56
	v_readlane_b32 s84, v254, 57
	v_readlane_b32 s85, v254, 58
	s_waitcnt vmcnt(1)
	v_pk_mul_f32 v[46:47], v[38:39], v[200:201] op_sel_hi:[1,0]
	v_pk_mul_f32 v[44:45], v[40:41], v[200:201] op_sel_hi:[1,0]
	ds_write2_b32 v43, v46, v47 offset1:1
	ds_write2_b32 v43, v44, v45 offset0:2 offset1:3
	s_cbranch_execnz .LBB0_1528
.LBB0_1527:
	s_waitcnt vmcnt(0)
	v_add_u32_e32 v42, v88, v104
	ds_write2_b32 v42, v38, v39 offset1:1
	ds_write2_b32 v42, v40, v41 offset0:2 offset1:3
	v_mov_b32_e32 v202, 1.0
.LBB0_1528:
	s_waitcnt vmcnt(0)
	v_pk_mul_f32 v[34:35], v[34:35], v[202:203] op_sel_hi:[1,0]
	v_add_u32_e32 v38, v88, v105
	ds_write2_b32 v38, v34, v35 offset1:1
	v_pk_mul_f32 v[34:35], v[36:37], v[202:203] op_sel_hi:[1,0]
	s_and_b64 vcc, exec, s[0:1]
	ds_write2_b32 v38, v34, v35 offset0:2 offset1:3
	s_cbranch_vccnz .LBB0_1627
	v_readlane_b32 s72, v254, 45
	v_readlane_b32 s86, v254, 59
	v_readlane_b32 s87, v254, 60
	s_nop 4
	v_add_u32_e32 v35, v88, v106
	v_readlane_b32 s73, v254, 46
	v_readlane_b32 s74, v254, 47
	v_readlane_b32 s75, v254, 48
	v_readlane_b32 s76, v254, 49
	v_readlane_b32 s77, v254, 50
	v_readlane_b32 s78, v254, 51
	v_readlane_b32 s79, v254, 52
	v_readlane_b32 s80, v254, 53
	v_readlane_b32 s81, v254, 54
	v_readlane_b32 s82, v254, 55
	v_readlane_b32 s83, v254, 56
	v_readlane_b32 s84, v254, 57
	v_readlane_b32 s85, v254, 58
	s_waitcnt vmcnt(1)
	v_pk_mul_f32 v[38:39], v[30:31], v[204:205] op_sel_hi:[1,0]
	v_pk_mul_f32 v[36:37], v[32:33], v[204:205] op_sel_hi:[1,0]
	ds_write2_b32 v35, v38, v39 offset1:1
	ds_write2_b32 v35, v36, v37 offset0:2 offset1:3
	s_cbranch_execnz .LBB0_1531
.LBB0_1530:
	s_waitcnt vmcnt(0)
	v_add_u32_e32 v34, v88, v106
	ds_write2_b32 v34, v30, v31 offset1:1
	ds_write2_b32 v34, v32, v33 offset0:2 offset1:3
	v_mov_b32_e32 v206, 1.0
.LBB0_1531:
	s_waitcnt vmcnt(0)
	v_pk_mul_f32 v[26:27], v[26:27], v[206:207] op_sel_hi:[1,0]
	v_add_u32_e32 v30, v88, v107
	ds_write2_b32 v30, v26, v27 offset1:1
	v_pk_mul_f32 v[26:27], v[28:29], v[206:207] op_sel_hi:[1,0]
	s_and_b64 vcc, exec, s[0:1]
	ds_write2_b32 v30, v26, v27 offset0:2 offset1:3
	s_cbranch_vccnz .LBB0_1628
	v_readlane_b32 s72, v254, 45
	v_readlane_b32 s86, v254, 59
	v_readlane_b32 s87, v254, 60
	s_nop 4
	v_add_u32_e32 v27, v88, v108
	v_readlane_b32 s73, v254, 46
	v_readlane_b32 s74, v254, 47
	v_readlane_b32 s75, v254, 48
	v_readlane_b32 s76, v254, 49
	v_readlane_b32 s77, v254, 50
	v_readlane_b32 s78, v254, 51
	v_readlane_b32 s79, v254, 52
	v_readlane_b32 s80, v254, 53
	v_readlane_b32 s81, v254, 54
	v_readlane_b32 s82, v254, 55
	v_readlane_b32 s83, v254, 56
	v_readlane_b32 s84, v254, 57
	v_readlane_b32 s85, v254, 58
	s_waitcnt vmcnt(1)
	v_pk_mul_f32 v[30:31], v[22:23], v[208:209] op_sel_hi:[1,0]
	v_pk_mul_f32 v[28:29], v[24:25], v[208:209] op_sel_hi:[1,0]
	ds_write2_b32 v27, v30, v31 offset1:1
	ds_write2_b32 v27, v28, v29 offset0:2 offset1:3
	s_cbranch_execnz .LBB0_1534
.LBB0_1533:
	s_waitcnt vmcnt(0)
	v_add_u32_e32 v26, v88, v108
	ds_write2_b32 v26, v22, v23 offset1:1
	ds_write2_b32 v26, v24, v25 offset0:2 offset1:3
	v_mov_b32_e32 v210, 1.0
.LBB0_1534:
	s_waitcnt vmcnt(0)
	v_pk_mul_f32 v[22:23], v[18:19], v[210:211] op_sel_hi:[1,0]
	v_add_u32_e32 v19, v88, v109
	v_pk_mul_f32 v[20:21], v[20:21], v[210:211] op_sel_hi:[1,0]
	ds_write2_b32 v19, v20, v21 offset0:2 offset1:3
	s_and_b64 vcc, exec, s[0:1]
	v_add_u32_e32 v20, 0x410, v19
	v_add_u32_e32 v21, 0x418, v19
	ds_write2_b32 v19, v22, v23 offset1:1
	s_cbranch_vccnz .LBB0_1629
	v_readlane_b32 s72, v254, 45
	v_readlane_b32 s86, v254, 59
	v_readlane_b32 s87, v254, 60
	s_nop 4
	v_readlane_b32 s73, v254, 46
	v_readlane_b32 s74, v254, 47
	v_readlane_b32 s75, v254, 48
	v_readlane_b32 s76, v254, 49
	v_readlane_b32 s77, v254, 50
	v_readlane_b32 s78, v254, 51
	v_readlane_b32 s79, v254, 52
	v_readlane_b32 s80, v254, 53
	v_readlane_b32 s81, v254, 54
	v_readlane_b32 s82, v254, 55
	v_readlane_b32 s83, v254, 56
	v_readlane_b32 s84, v254, 57
	v_readlane_b32 s85, v254, 58
	s_waitcnt vmcnt(1)
	v_pk_mul_f32 v[24:25], v[14:15], v[212:213] op_sel_hi:[1,0]
	v_pk_mul_f32 v[22:23], v[16:17], v[212:213] op_sel_hi:[1,0]
	ds_write2_b32 v20, v24, v25 offset1:1
	ds_write2_b32 v21, v22, v23 offset1:1
	s_cbranch_execnz .LBB0_1537

.LBB0_1537:
	s_waitcnt vmcnt(0)
	v_pk_mul_f32 v[10:11], v[10:11], v[214:215] op_sel_hi:[1,0]
	v_add_u32_e32 v14, 0x820, v19
	ds_write2_b32 v14, v10, v11 offset1:1
	v_pk_mul_f32 v[10:11], v[12:13], v[214:215] op_sel_hi:[1,0]
	v_add_u32_e32 v12, 0x828, v19
	ds_write2_b32 v12, v10, v11 offset1:1
	s_and_b64 vcc, exec, s[0:1]
	v_add_u32_e32 v11, 0xc30, v19
	v_add_u32_e32 v12, 0xc38, v19
	s_cbranch_vccnz .LBB0_1630
	v_readlane_b32 s72, v254, 45
	v_readlane_b32 s86, v254, 59
	v_readlane_b32 s87, v254, 60
	s_nop 4
	v_readlane_b32 s73, v254, 46
	v_readlane_b32 s74, v254, 47
	v_readlane_b32 s75, v254, 48
	v_readlane_b32 s76, v254, 49
	v_readlane_b32 s77, v254, 50
	v_readlane_b32 s78, v254, 51
	v_readlane_b32 s79, v254, 52
	v_readlane_b32 s80, v254, 53
	v_readlane_b32 s81, v254, 54
	v_readlane_b32 s82, v254, 55
	v_readlane_b32 s83, v254, 56
	v_readlane_b32 s84, v254, 57
	v_readlane_b32 s85, v254, 58
	s_waitcnt vmcnt(1)
	v_pk_mul_f32 v[16:17], v[6:7], v[216:217] op_sel_hi:[1,0]
	v_pk_mul_f32 v[14:15], v[8:9], v[216:217] op_sel_hi:[1,0]
	ds_write2_b32 v11, v16, v17 offset1:1
	ds_write2_b32 v12, v14, v15 offset1:1
	s_cbranch_execnz .LBB0_1540

.LBB0_1540:
	s_waitcnt vmcnt(0)
	v_pk_mul_f32 v[2:3], v[2:3], v[218:219] op_sel_hi:[1,0]
	v_add_u32_e32 v6, 0x1040, v19
	s_lshl_b32 s4, s16, 6
	ds_write2_b32 v6, v2, v3 offset1:1
	v_pk_mul_f32 v[2:3], v[4:5], v[218:219] op_sel_hi:[1,0]
	v_add_u32_e32 v4, 0x1048, v19
	s_and_b32 s4, 0xffff, s4
	ds_write2_b32 v4, v2, v3 offset1:1
	s_lshl_b32 s10, s4, 1
	s_waitcnt lgkmcnt(0)
	s_and_b32 s4, s4, 64
	s_and_b32 s10, s10, 0x1f00
	s_or_b32 s10, s4, s10
	ds_read2_b32 v[2:3], v91 offset1:65
	s_bitset1_b32 s10, 7
	s_waitcnt lgkmcnt(0)
	v_cvt_pk_bf16_f32 v2, v2, v3
	ds_read2_b32 v[4:5], v91 offset0:130 offset1:195
	v_add_u32_e32 v12, 0x400, v91
	s_lshl_b32 s4, s15, 1
	v_or_b32_e32 v10, s10, v90
	s_waitcnt lgkmcnt(0)
	v_cvt_pk_bf16_f32 v3, v4, v5
	ds_read2_b32 v[4:5], v12 offset0:4 offset1:69
	v_lshl_add_u64 v[8:9], v[70:71], 0, s[4:5]
	v_lshlrev_b32_e32 v68, 11, v10
	s_waitcnt lgkmcnt(0)
	v_cvt_pk_bf16_f32 v4, v4, v5
	ds_read2_b32 v[6:7], v12 offset0:134 offset1:199
	s_waitcnt lgkmcnt(0)
	v_cvt_pk_bf16_f32 v5, v6, v7
	v_lshl_add_u64 v[10:11], v[8:9], 0, v[68:69]
	ds_read2_b32 v[6:7], v91 offset0:8 offset1:73
	global_store_dwordx4 v[10:11], v[2:5], off
	v_or_b32_e32 v10, s10, v92
	v_lshlrev_b32_e32 v68, 11, v10
	s_waitcnt lgkmcnt(0)
	v_cvt_pk_bf16_f32 v2, v6, v7
	ds_read2_b32 v[4:5], v91 offset0:138 offset1:203
	s_waitcnt lgkmcnt(0)
	v_cvt_pk_bf16_f32 v3, v4, v5
	ds_read2_b32 v[4:5], v12 offset0:12 offset1:77
	s_waitcnt lgkmcnt(0)
	v_cvt_pk_bf16_f32 v4, v4, v5
	ds_read2_b32 v[6:7], v12 offset0:142 offset1:207
	s_waitcnt lgkmcnt(0)
	v_cvt_pk_bf16_f32 v5, v6, v7
	v_lshl_add_u64 v[10:11], v[8:9], 0, v[68:69]
	ds_read2_b32 v[6:7], v91 offset0:16 offset1:81
	global_store_dwordx4 v[10:11], v[2:5], off
	v_or_b32_e32 v10, s10, v93
	v_lshlrev_b32_e32 v68, 11, v10
	s_waitcnt lgkmcnt(0)
	v_cvt_pk_bf16_f32 v2, v6, v7
	ds_read2_b32 v[4:5], v91 offset0:146 offset1:211
	s_waitcnt lgkmcnt(0)
	v_cvt_pk_bf16_f32 v3, v4, v5
	ds_read2_b32 v[4:5], v12 offset0:20 offset1:85
	s_waitcnt lgkmcnt(0)
	v_cvt_pk_bf16_f32 v4, v4, v5
	ds_read2_b32 v[6:7], v12 offset0:150 offset1:215
	s_waitcnt lgkmcnt(0)
	v_cvt_pk_bf16_f32 v5, v6, v7
	v_lshl_add_u64 v[10:11], v[8:9], 0, v[68:69]
	ds_read2_b32 v[6:7], v91 offset0:24 offset1:89
	global_store_dwordx4 v[10:11], v[2:5], off
	v_or_b32_e32 v10, s10, v94
	v_lshlrev_b32_e32 v68, 11, v10
	s_waitcnt lgkmcnt(0)
	v_cvt_pk_bf16_f32 v2, v6, v7
	ds_read2_b32 v[4:5], v91 offset0:154 offset1:219
	s_waitcnt lgkmcnt(0)
	v_cvt_pk_bf16_f32 v3, v4, v5
	ds_read2_b32 v[4:5], v12 offset0:28 offset1:93
	s_waitcnt lgkmcnt(0)
	v_cvt_pk_bf16_f32 v4, v4, v5
	ds_read2_b32 v[6:7], v12 offset0:158 offset1:223
	s_waitcnt lgkmcnt(0)
	v_cvt_pk_bf16_f32 v5, v6, v7
	v_lshl_add_u64 v[10:11], v[8:9], 0, v[68:69]
	ds_read2_b32 v[6:7], v91 offset0:32 offset1:97
	global_store_dwordx4 v[10:11], v[2:5], off
	v_or_b32_e32 v10, s10, v95
	v_lshlrev_b32_e32 v68, 11, v10
	s_waitcnt lgkmcnt(0)
	v_cvt_pk_bf16_f32 v2, v6, v7
	ds_read2_b32 v[4:5], v91 offset0:162 offset1:227
	s_waitcnt lgkmcnt(0)
	v_cvt_pk_bf16_f32 v3, v4, v5
	ds_read2_b32 v[4:5], v12 offset0:36 offset1:101
	s_waitcnt lgkmcnt(0)
	v_cvt_pk_bf16_f32 v4, v4, v5
	ds_read2_b32 v[6:7], v12 offset0:166 offset1:231
	s_waitcnt lgkmcnt(0)
	v_cvt_pk_bf16_f32 v5, v6, v7
	v_lshl_add_u64 v[10:11], v[8:9], 0, v[68:69]
	ds_read2_b32 v[6:7], v91 offset0:40 offset1:105
	global_store_dwordx4 v[10:11], v[2:5], off
	v_or_b32_e32 v10, s10, v96
	v_lshlrev_b32_e32 v68, 11, v10
	s_waitcnt lgkmcnt(0)
	v_cvt_pk_bf16_f32 v2, v6, v7
	ds_read2_b32 v[4:5], v91 offset0:170 offset1:235
	s_waitcnt lgkmcnt(0)
	v_cvt_pk_bf16_f32 v3, v4, v5
	ds_read2_b32 v[4:5], v12 offset0:44 offset1:109
	s_waitcnt lgkmcnt(0)
	v_cvt_pk_bf16_f32 v4, v4, v5
	ds_read2_b32 v[6:7], v12 offset0:174 offset1:239
	s_waitcnt lgkmcnt(0)
	v_cvt_pk_bf16_f32 v5, v6, v7
	v_lshl_add_u64 v[10:11], v[8:9], 0, v[68:69]
	ds_read2_b32 v[6:7], v91 offset0:48 offset1:113
	global_store_dwordx4 v[10:11], v[2:5], off
	v_or_b32_e32 v10, s10, v97
	v_lshlrev_b32_e32 v68, 11, v10
	s_waitcnt lgkmcnt(0)
	v_cvt_pk_bf16_f32 v2, v6, v7
	ds_read2_b32 v[4:5], v91 offset0:178 offset1:243
	s_waitcnt lgkmcnt(0)
	v_cvt_pk_bf16_f32 v3, v4, v5
	ds_read2_b32 v[4:5], v12 offset0:52 offset1:117
	s_waitcnt lgkmcnt(0)
	v_cvt_pk_bf16_f32 v4, v4, v5
	ds_read2_b32 v[6:7], v12 offset0:182 offset1:247
	s_waitcnt lgkmcnt(0)
	v_cvt_pk_bf16_f32 v5, v6, v7
	v_lshl_add_u64 v[10:11], v[8:9], 0, v[68:69]
	ds_read2_b32 v[6:7], v91 offset0:56 offset1:121
	global_store_dwordx4 v[10:11], v[2:5], off
	s_waitcnt lgkmcnt(0)
	s_nop 0
	v_cvt_pk_bf16_f32 v2, v6, v7
	ds_read2_b32 v[4:5], v91 offset0:186 offset1:251
	s_waitcnt lgkmcnt(0)
	v_cvt_pk_bf16_f32 v3, v4, v5
	ds_read2_b32 v[4:5], v12 offset0:60 offset1:125
	s_waitcnt lgkmcnt(0)
	v_cvt_pk_bf16_f32 v4, v4, v5
	v_or_b32_e32 v5, s10, v98
	ds_read2_b32 v[6:7], v12 offset0:190 offset1:255
	v_lshlrev_b32_e32 v68, 11, v5
	s_waitcnt lgkmcnt(0)
	v_cvt_pk_bf16_f32 v5, v6, v7
	v_lshl_add_u64 v[6:7], v[8:9], 0, v[68:69]
	global_store_dwordx4 v[6:7], v[2:5], off
	s_waitcnt lgkmcnt(0)
	s_mov_b64 s[10:11], 0
.LBB0_1541:
	s_and_b64 vcc, exec, s[10:11]
	s_cbranch_vccz .LBB0_1622
	s_and_b32 s4, 0xffff, s14
	s_mul_i32 s4, s4, 0xba2f
	s_lshr_b32 s10, s4, 21
	s_mul_i32 s10, s10, 44
	s_sub_i32 s10, s14, s10
	s_lshr_b32 s4, s4, 15
	s_and_b32 s14, s10, 0xffff
	s_and_b32 s15, s4, 0xffc0
	v_or_b32_e32 v87, s15, v66
	s_lshl_b32 s4, s14, 8
	v_lshl_add_u64 v[2:3], v[78:79], 0, s[4:5]
	v_mul_u32_u24_e32 v68, 0x2c00, v87
	v_mad_u64_u32 v[4:5], s[10:11], v87, s28, v[2:3]
	v_lshl_add_u64 v[2:3], v[2:3], 0, v[68:69]
	s_waitcnt vmcnt(0)
	v_add_co_u32_e32 v6, vcc, s29, v2
	v_add_lshl_u32 v86, v66, s15, 2
	s_nop 0
	v_addc_co_u32_e32 v7, vcc, 0, v3, vcc
	global_load_dwordx4 v[62:65], v[4:5], off nt
	global_load_dwordx4 v[58:61], v[6:7], off nt
	v_add_co_u32_e32 v4, vcc, s30, v2
	s_nop 1
	v_addc_co_u32_e32 v5, vcc, 0, v3, vcc
	v_add_co_u32_e32 v6, vcc, s31, v2
	s_nop 1
	v_addc_co_u32_e32 v7, vcc, 0, v3, vcc
	global_load_dwordx4 v[54:57], v[4:5], off nt
	global_load_dwordx4 v[50:53], v[6:7], off nt
	v_add_co_u32_e32 v4, vcc, s34, v2
	s_nop 1
	v_addc_co_u32_e32 v5, vcc, 0, v3, vcc
	v_add_co_u32_e32 v6, vcc, s35, v2
	s_nop 1
	v_addc_co_u32_e32 v7, vcc, 0, v3, vcc
	global_load_dwordx4 v[46:49], v[4:5], off nt
	global_load_dwordx4 v[42:45], v[6:7], off nt
	v_add_co_u32_e32 v4, vcc, s38, v2
	s_nop 1
	v_addc_co_u32_e32 v5, vcc, 0, v3, vcc
	v_add_co_u32_e32 v6, vcc, s39, v2
	s_nop 1
	v_addc_co_u32_e32 v7, vcc, 0, v3, vcc
	global_load_dwordx4 v[38:41], v[4:5], off nt
	global_load_dwordx4 v[34:37], v[6:7], off nt
	v_add_co_u32_e32 v4, vcc, s40, v2
	s_nop 1
	v_addc_co_u32_e32 v5, vcc, 0, v3, vcc
	v_add_co_u32_e32 v6, vcc, s41, v2
	s_nop 1
	v_addc_co_u32_e32 v7, vcc, 0, v3, vcc
	global_load_dwordx4 v[30:33], v[4:5], off nt
	global_load_dwordx4 v[26:29], v[6:7], off nt
	v_add_co_u32_e32 v4, vcc, s44, v2
	s_nop 1
	v_addc_co_u32_e32 v5, vcc, 0, v3, vcc
	v_add_co_u32_e32 v6, vcc, s45, v2
	s_nop 1
	v_addc_co_u32_e32 v7, vcc, 0, v3, vcc
	global_load_dwordx4 v[22:25], v[4:5], off nt
	global_load_dwordx4 v[18:21], v[6:7], off nt
	v_add_co_u32_e32 v4, vcc, s46, v2
	s_nop 1
	v_addc_co_u32_e32 v5, vcc, 0, v3, vcc
	v_add_co_u32_e32 v6, vcc, 0x8f000, v2
	s_nop 1
	v_addc_co_u32_e32 v7, vcc, 0, v3, vcc
	global_load_dwordx4 v[14:17], v[4:5], off nt
	global_load_dwordx4 v[10:13], v[6:7], off nt
	v_add_co_u32_e32 v4, vcc, 0x9a000, v2
	s_nop 1
	v_addc_co_u32_e32 v5, vcc, 0, v3, vcc
	v_add_co_u32_e32 v2, vcc, 0xa5000, v2
	s_nop 1
	v_addc_co_u32_e32 v3, vcc, 0, v3, vcc
	global_load_dwordx4 v[6:9], v[4:5], off nt
	s_nop 0
	global_load_dwordx4 v[2:5], v[2:3], off nt
	s_and_b64 vcc, exec, s[0:1]
	s_cbranch_vccnz .LBB0_1631
	v_readlane_b32 s72, v254, 45
	v_lshlrev_b32_e32 v68, 2, v87
	v_readlane_b32 s86, v254, 59
	v_readlane_b32 s87, v254, 60
	s_nop 4
	global_load_dword v188, v68, s[86:87]
	global_load_dword v190, v86, s[86:87] offset:16
	global_load_dword v192, v86, s[86:87] offset:32
	global_load_dword v194, v86, s[86:87] offset:48
	global_load_dword v196, v86, s[86:87] offset:64
	global_load_dword v198, v86, s[86:87] offset:80
	global_load_dword v200, v86, s[86:87] offset:96
	global_load_dword v202, v86, s[86:87] offset:112
	global_load_dword v204, v86, s[86:87] offset:128
	global_load_dword v206, v86, s[86:87] offset:144
	global_load_dword v208, v86, s[86:87] offset:160
	global_load_dword v210, v86, s[86:87] offset:176
	global_load_dword v212, v86, s[86:87] offset:192
	global_load_dword v214, v86, s[86:87] offset:208
	global_load_dword v216, v86, s[86:87] offset:224
	global_load_dword v218, v86, s[86:87] offset:240
	s_nop 0
	v_add_u32_e32 v87, v88, v89
	v_readlane_b32 s73, v254, 46
	v_readlane_b32 s74, v254, 47
	v_readlane_b32 s75, v254, 48
	v_readlane_b32 s76, v254, 49
	v_readlane_b32 s77, v254, 50
	v_readlane_b32 s78, v254, 51
	v_readlane_b32 s79, v254, 52
	v_readlane_b32 s80, v254, 53
	v_readlane_b32 s81, v254, 54
	v_readlane_b32 s82, v254, 55
	v_readlane_b32 s83, v254, 56
	v_readlane_b32 s84, v254, 57
	v_readlane_b32 s85, v254, 58
	s_waitcnt vmcnt(0)
	v_pk_mul_f32 v[114:115], v[62:63], v[188:189] op_sel_hi:[1,0]
	v_pk_mul_f32 v[112:113], v[64:65], v[188:189] op_sel_hi:[1,0]
	ds_write2_b32 v87, v114, v115 offset1:1
	ds_write2_b32 v87, v112, v113 offset0:2 offset1:3
	s_cbranch_execnz .LBB0_1545

.LBB0_1566:
	s_waitcnt vmcnt(0)
	v_pk_mul_f32 v[2:3], v[2:3], v[218:219] op_sel_hi:[1,0]
	v_add_u32_e32 v6, 0x1040, v19
	ds_write2_b32 v6, v2, v3 offset1:1
	v_pk_mul_f32 v[2:3], v[4:5], v[218:219] op_sel_hi:[1,0]
	v_add_u32_e32 v4, 0x1048, v19
	ds_write2_b32 v4, v2, v3 offset1:1
	s_waitcnt lgkmcnt(0)
	s_lshl_b32 s0, s14, 6
	s_lshl_b32 s1, s14, 7
	s_and_b32 s1, s1, 0x1f00
	s_and_b32 s0, s0, 64
	ds_read2_b32 v[2:3], v91 offset1:65
	s_or_b32 s0, s1, s0
	s_waitcnt lgkmcnt(0)
	v_cvt_pk_bf16_f32 v2, v2, v3
	ds_read2_b32 v[4:5], v91 offset0:130 offset1:195
	v_add_u32_e32 v12, 0x400, v91
	s_lshl_b32 s4, s15, 1
	v_or_b32_e32 v10, s0, v90
	s_waitcnt lgkmcnt(0)
	v_cvt_pk_bf16_f32 v3, v4, v5
	ds_read2_b32 v[4:5], v12 offset0:4 offset1:69
	v_lshl_add_u64 v[8:9], v[70:71], 0, s[4:5]
	v_lshlrev_b32_e32 v68, 11, v10
	s_waitcnt lgkmcnt(0)
	v_cvt_pk_bf16_f32 v4, v4, v5
	ds_read2_b32 v[6:7], v12 offset0:134 offset1:199
	s_waitcnt lgkmcnt(0)
	v_cvt_pk_bf16_f32 v5, v6, v7
	v_lshl_add_u64 v[10:11], v[8:9], 0, v[68:69]
	ds_read2_b32 v[6:7], v91 offset0:8 offset1:73
	global_store_dwordx4 v[10:11], v[2:5], off
	v_or_b32_e32 v10, s0, v92
	v_lshlrev_b32_e32 v68, 11, v10
	s_waitcnt lgkmcnt(0)
	v_cvt_pk_bf16_f32 v2, v6, v7
	ds_read2_b32 v[4:5], v91 offset0:138 offset1:203
	s_waitcnt lgkmcnt(0)
	v_cvt_pk_bf16_f32 v3, v4, v5
	ds_read2_b32 v[4:5], v12 offset0:12 offset1:77
	s_waitcnt lgkmcnt(0)
	v_cvt_pk_bf16_f32 v4, v4, v5
	ds_read2_b32 v[6:7], v12 offset0:142 offset1:207
	s_waitcnt lgkmcnt(0)
	v_cvt_pk_bf16_f32 v5, v6, v7
	v_lshl_add_u64 v[10:11], v[8:9], 0, v[68:69]
	ds_read2_b32 v[6:7], v91 offset0:16 offset1:81
	global_store_dwordx4 v[10:11], v[2:5], off
	v_or_b32_e32 v10, s0, v93
	v_lshlrev_b32_e32 v68, 11, v10
	s_waitcnt lgkmcnt(0)
	v_cvt_pk_bf16_f32 v2, v6, v7
	ds_read2_b32 v[4:5], v91 offset0:146 offset1:211
	s_waitcnt lgkmcnt(0)
	v_cvt_pk_bf16_f32 v3, v4, v5
	ds_read2_b32 v[4:5], v12 offset0:20 offset1:85
	s_waitcnt lgkmcnt(0)
	v_cvt_pk_bf16_f32 v4, v4, v5
	ds_read2_b32 v[6:7], v12 offset0:150 offset1:215
	s_waitcnt lgkmcnt(0)
	v_cvt_pk_bf16_f32 v5, v6, v7
	v_lshl_add_u64 v[10:11], v[8:9], 0, v[68:69]
	ds_read2_b32 v[6:7], v91 offset0:24 offset1:89
	global_store_dwordx4 v[10:11], v[2:5], off
	v_or_b32_e32 v10, s0, v94
	v_lshlrev_b32_e32 v68, 11, v10
	s_waitcnt lgkmcnt(0)
	v_cvt_pk_bf16_f32 v2, v6, v7
	ds_read2_b32 v[4:5], v91 offset0:154 offset1:219
	s_waitcnt lgkmcnt(0)
	v_cvt_pk_bf16_f32 v3, v4, v5
	ds_read2_b32 v[4:5], v12 offset0:28 offset1:93
	s_waitcnt lgkmcnt(0)
	v_cvt_pk_bf16_f32 v4, v4, v5
	ds_read2_b32 v[6:7], v12 offset0:158 offset1:223
	s_waitcnt lgkmcnt(0)
	v_cvt_pk_bf16_f32 v5, v6, v7
	v_lshl_add_u64 v[10:11], v[8:9], 0, v[68:69]
	ds_read2_b32 v[6:7], v91 offset0:32 offset1:97
	global_store_dwordx4 v[10:11], v[2:5], off
	v_or_b32_e32 v10, s0, v95
	v_lshlrev_b32_e32 v68, 11, v10
	s_waitcnt lgkmcnt(0)
	v_cvt_pk_bf16_f32 v2, v6, v7
	ds_read2_b32 v[4:5], v91 offset0:162 offset1:227
	s_waitcnt lgkmcnt(0)
	v_cvt_pk_bf16_f32 v3, v4, v5
	ds_read2_b32 v[4:5], v12 offset0:36 offset1:101
	s_waitcnt lgkmcnt(0)
	v_cvt_pk_bf16_f32 v4, v4, v5
	ds_read2_b32 v[6:7], v12 offset0:166 offset1:231
	s_waitcnt lgkmcnt(0)
	v_cvt_pk_bf16_f32 v5, v6, v7
	v_lshl_add_u64 v[10:11], v[8:9], 0, v[68:69]
	ds_read2_b32 v[6:7], v91 offset0:40 offset1:105
	global_store_dwordx4 v[10:11], v[2:5], off
	v_or_b32_e32 v10, s0, v96
	v_lshlrev_b32_e32 v68, 11, v10
	s_waitcnt lgkmcnt(0)
	v_cvt_pk_bf16_f32 v2, v6, v7
	ds_read2_b32 v[4:5], v91 offset0:170 offset1:235
	s_waitcnt lgkmcnt(0)
	v_cvt_pk_bf16_f32 v3, v4, v5
	ds_read2_b32 v[4:5], v12 offset0:44 offset1:109
	s_waitcnt lgkmcnt(0)
	v_cvt_pk_bf16_f32 v4, v4, v5
	ds_read2_b32 v[6:7], v12 offset0:174 offset1:239
	s_waitcnt lgkmcnt(0)
	v_cvt_pk_bf16_f32 v5, v6, v7
	v_lshl_add_u64 v[10:11], v[8:9], 0, v[68:69]
	ds_read2_b32 v[6:7], v91 offset0:48 offset1:113
	global_store_dwordx4 v[10:11], v[2:5], off
	v_or_b32_e32 v10, s0, v97
	v_lshlrev_b32_e32 v68, 11, v10
	s_waitcnt lgkmcnt(0)
	v_cvt_pk_bf16_f32 v2, v6, v7
	ds_read2_b32 v[4:5], v91 offset0:178 offset1:243
	s_waitcnt lgkmcnt(0)
	v_cvt_pk_bf16_f32 v3, v4, v5
	ds_read2_b32 v[4:5], v12 offset0:52 offset1:117
	s_waitcnt lgkmcnt(0)
	v_cvt_pk_bf16_f32 v4, v4, v5
	ds_read2_b32 v[6:7], v12 offset0:182 offset1:247
	s_waitcnt lgkmcnt(0)
	v_cvt_pk_bf16_f32 v5, v6, v7
	v_lshl_add_u64 v[10:11], v[8:9], 0, v[68:69]
	ds_read2_b32 v[6:7], v91 offset0:56 offset1:121
	global_store_dwordx4 v[10:11], v[2:5], off
	s_waitcnt lgkmcnt(0)
	s_nop 0
	v_cvt_pk_bf16_f32 v2, v6, v7
	ds_read2_b32 v[4:5], v91 offset0:186 offset1:251
	s_waitcnt lgkmcnt(0)
	v_cvt_pk_bf16_f32 v3, v4, v5
	ds_read2_b32 v[4:5], v12 offset0:60 offset1:125
	s_waitcnt lgkmcnt(0)
	v_cvt_pk_bf16_f32 v4, v4, v5
	v_or_b32_e32 v5, s0, v98
	ds_read2_b32 v[6:7], v12 offset0:190 offset1:255
	v_lshlrev_b32_e32 v68, 11, v5
	s_waitcnt lgkmcnt(0)
	v_cvt_pk_bf16_f32 v5, v6, v7
	v_lshl_add_u64 v[6:7], v[8:9], 0, v[68:69]
	global_store_dwordx4 v[6:7], v[2:5], off
	s_waitcnt lgkmcnt(0)
	s_mov_b64 s[0:1], 0

.LBB0_1571:
	s_andn2_b64 vcc, exec, s[0:1]
	s_cbranch_vccnz .LBB0_1597
	s_add_i32 s0, s3, 0xfd40
	s_and_b32 s1, s0, 0xffff
	s_mul_i32 s1, s1, 0xba2f
	s_lshr_b32 s1, s1, 21
	s_mul_i32 s4, s1, 44
	s_sub_i32 s15, s0, s4
	s_lshl_b32 s14, s1, 6
	v_or_b32_e32 v87, s14, v66
	s_lshl_b32 s0, s15, 8
	s_and_b32 s4, s0, 0x3ff00
	s_waitcnt vmcnt(0)
	v_mul_u32_u24_e32 v6, 0xb00, v87
	v_lshl_add_u64 v[2:3], v[82:83], 0, s[4:5]
	v_lshlrev_b32_e32 v68, 2, v6
	v_mad_u64_u32 v[4:5], s[0:1], v87, s28, v[2:3]
	v_lshl_add_u64 v[2:3], v[2:3], 0, v[68:69]
	v_add_co_u32_e32 v6, vcc, s29, v2
	v_cndmask_b32_e64 v68, 0, 1, s[6:7]
	s_nop 0
	v_addc_co_u32_e32 v7, vcc, 0, v3, vcc
	global_load_dwordx4 v[62:65], v[4:5], off nt
	global_load_dwordx4 v[58:61], v[6:7], off nt
	v_add_co_u32_e32 v4, vcc, s30, v2
	v_cmp_ne_u32_e64 s[0:1], 1, v68
	s_nop 0
	v_addc_co_u32_e32 v5, vcc, 0, v3, vcc
	v_add_co_u32_e32 v6, vcc, s31, v2
	v_add_lshl_u32 v86, s14, v66, 2
	s_nop 0
	v_addc_co_u32_e32 v7, vcc, 0, v3, vcc
	global_load_dwordx4 v[54:57], v[4:5], off nt
	global_load_dwordx4 v[50:53], v[6:7], off nt
	v_add_co_u32_e32 v4, vcc, s34, v2
	s_nop 1
	v_addc_co_u32_e32 v5, vcc, 0, v3, vcc
	v_add_co_u32_e32 v6, vcc, s35, v2
	s_nop 1
	v_addc_co_u32_e32 v7, vcc, 0, v3, vcc
	global_load_dwordx4 v[46:49], v[4:5], off nt
	global_load_dwordx4 v[42:45], v[6:7], off nt
	v_add_co_u32_e32 v4, vcc, s38, v2
	s_nop 1
	v_addc_co_u32_e32 v5, vcc, 0, v3, vcc
	v_add_co_u32_e32 v6, vcc, s39, v2
	s_nop 1
	v_addc_co_u32_e32 v7, vcc, 0, v3, vcc
	global_load_dwordx4 v[38:41], v[4:5], off nt
	global_load_dwordx4 v[34:37], v[6:7], off nt
	v_add_co_u32_e32 v4, vcc, s40, v2
	s_nop 1
	v_addc_co_u32_e32 v5, vcc, 0, v3, vcc
	v_add_co_u32_e32 v6, vcc, s41, v2
	s_nop 1
	v_addc_co_u32_e32 v7, vcc, 0, v3, vcc
	global_load_dwordx4 v[30:33], v[4:5], off nt
	global_load_dwordx4 v[26:29], v[6:7], off nt
	v_add_co_u32_e32 v4, vcc, s44, v2
	s_nop 1
	v_addc_co_u32_e32 v5, vcc, 0, v3, vcc
	v_add_co_u32_e32 v6, vcc, s45, v2
	s_nop 1
	v_addc_co_u32_e32 v7, vcc, 0, v3, vcc
	global_load_dwordx4 v[22:25], v[4:5], off nt
	global_load_dwordx4 v[18:21], v[6:7], off nt
	v_add_co_u32_e32 v4, vcc, s46, v2
	s_nop 1
	v_addc_co_u32_e32 v5, vcc, 0, v3, vcc
	v_add_co_u32_e32 v6, vcc, 0x8f000, v2
	s_nop 1
	v_addc_co_u32_e32 v7, vcc, 0, v3, vcc
	global_load_dwordx4 v[14:17], v[4:5], off nt
	global_load_dwordx4 v[10:13], v[6:7], off nt
	v_add_co_u32_e32 v4, vcc, 0x9a000, v2
	s_nop 1
	v_addc_co_u32_e32 v5, vcc, 0, v3, vcc
	v_add_co_u32_e32 v2, vcc, 0xa5000, v2
	s_nop 1
	v_addc_co_u32_e32 v3, vcc, 0, v3, vcc
	global_load_dwordx4 v[6:9], v[4:5], off nt
	s_nop 0
	global_load_dwordx4 v[2:5], v[2:3], off nt
	s_andn2_b64 vcc, exec, s[6:7]
	s_cbranch_vccnz .LBB0_1647
	v_readlane_b32 s72, v254, 10
	v_lshlrev_b32_e32 v68, 2, v87
	v_readlane_b32 s82, v254, 20
	v_readlane_b32 s83, v254, 21
	s_nop 4
	global_load_dword v188, v68, s[82:83]
	global_load_dword v190, v86, s[82:83] offset:16
	global_load_dword v192, v86, s[82:83] offset:32
	global_load_dword v194, v86, s[82:83] offset:48
	global_load_dword v196, v86, s[82:83] offset:64
	global_load_dword v198, v86, s[82:83] offset:80
	global_load_dword v200, v86, s[82:83] offset:96
	global_load_dword v202, v86, s[82:83] offset:112
	global_load_dword v204, v86, s[82:83] offset:128
	global_load_dword v206, v86, s[82:83] offset:144
	global_load_dword v208, v86, s[82:83] offset:160
	global_load_dword v210, v86, s[82:83] offset:176
	global_load_dword v212, v86, s[82:83] offset:192
	global_load_dword v214, v86, s[82:83] offset:208
	global_load_dword v216, v86, s[82:83] offset:224
	global_load_dword v218, v86, s[82:83] offset:240
	s_nop 0
	v_add_u32_e32 v87, v88, v89
	v_readlane_b32 s73, v254, 11
	v_readlane_b32 s74, v254, 12
	v_readlane_b32 s75, v254, 13
	v_readlane_b32 s76, v254, 14
	v_readlane_b32 s77, v254, 15
	v_readlane_b32 s78, v254, 16
	v_readlane_b32 s79, v254, 17
	v_readlane_b32 s80, v254, 18
	v_readlane_b32 s81, v254, 19
	v_readlane_b32 s84, v254, 22
	v_readlane_b32 s85, v254, 23
	v_readlane_b32 s86, v254, 24
	v_readlane_b32 s87, v254, 25
	s_waitcnt vmcnt(0)
	v_pk_mul_f32 v[114:115], v[62:63], v[188:189] op_sel_hi:[1,0]
	v_pk_mul_f32 v[112:113], v[64:65], v[188:189] op_sel_hi:[1,0]
	ds_write2_b32 v87, v114, v115 offset1:1
	ds_write2_b32 v87, v112, v113 offset0:2 offset1:3
	s_cbranch_execnz .LBB0_1575

.LBB0_1575:
	s_waitcnt vmcnt(0)
	v_pk_mul_f32 v[58:59], v[58:59], v[190:191] op_sel_hi:[1,0]
	v_add_u32_e32 v62, v88, v99
	ds_write2_b32 v62, v58, v59 offset1:1
	v_pk_mul_f32 v[58:59], v[60:61], v[190:191] op_sel_hi:[1,0]
	s_and_b64 vcc, exec, s[0:1]
	ds_write2_b32 v62, v58, v59 offset0:2 offset1:3
	s_cbranch_vccnz .LBB0_1648
	v_readlane_b32 s72, v254, 10
	v_readlane_b32 s82, v254, 20
	v_readlane_b32 s83, v254, 21
	s_nop 4
	v_add_u32_e32 v59, v88, v100
	v_readlane_b32 s73, v254, 11
	v_readlane_b32 s74, v254, 12
	v_readlane_b32 s75, v254, 13
	v_readlane_b32 s76, v254, 14
	v_readlane_b32 s77, v254, 15
	v_readlane_b32 s78, v254, 16
	v_readlane_b32 s79, v254, 17
	v_readlane_b32 s80, v254, 18
	v_readlane_b32 s81, v254, 19
	v_readlane_b32 s84, v254, 22
	v_readlane_b32 s85, v254, 23
	v_readlane_b32 s86, v254, 24
	v_readlane_b32 s87, v254, 25
	s_waitcnt vmcnt(1)
	v_pk_mul_f32 v[62:63], v[54:55], v[192:193] op_sel_hi:[1,0]
	v_pk_mul_f32 v[60:61], v[56:57], v[192:193] op_sel_hi:[1,0]
	ds_write2_b32 v59, v62, v63 offset1:1
	ds_write2_b32 v59, v60, v61 offset0:2 offset1:3
	s_cbranch_execnz .LBB0_1578

.LBB0_1578:
	s_waitcnt vmcnt(0)
	v_pk_mul_f32 v[50:51], v[50:51], v[194:195] op_sel_hi:[1,0]
	v_add_u32_e32 v54, v88, v101
	ds_write2_b32 v54, v50, v51 offset1:1
	v_pk_mul_f32 v[50:51], v[52:53], v[194:195] op_sel_hi:[1,0]
	s_and_b64 vcc, exec, s[0:1]
	ds_write2_b32 v54, v50, v51 offset0:2 offset1:3
	s_cbranch_vccnz .LBB0_1649
	v_readlane_b32 s72, v254, 10
	v_readlane_b32 s82, v254, 20
	v_readlane_b32 s83, v254, 21
	s_nop 4
	v_add_u32_e32 v51, v88, v102
	v_readlane_b32 s73, v254, 11
	v_readlane_b32 s74, v254, 12
	v_readlane_b32 s75, v254, 13
	v_readlane_b32 s76, v254, 14
	v_readlane_b32 s77, v254, 15
	v_readlane_b32 s78, v254, 16
	v_readlane_b32 s79, v254, 17
	v_readlane_b32 s80, v254, 18
	v_readlane_b32 s81, v254, 19
	v_readlane_b32 s84, v254, 22
	v_readlane_b32 s85, v254, 23
	v_readlane_b32 s86, v254, 24
	v_readlane_b32 s87, v254, 25
	s_waitcnt vmcnt(1)
	v_pk_mul_f32 v[54:55], v[46:47], v[196:197] op_sel_hi:[1,0]
	v_pk_mul_f32 v[52:53], v[48:49], v[196:197] op_sel_hi:[1,0]
	ds_write2_b32 v51, v54, v55 offset1:1
	ds_write2_b32 v51, v52, v53 offset0:2 offset1:3
	s_cbranch_execnz .LBB0_1581

.LBB0_1581:
	s_waitcnt vmcnt(0)
	v_pk_mul_f32 v[42:43], v[42:43], v[198:199] op_sel_hi:[1,0]
	v_add_u32_e32 v46, v88, v103
	ds_write2_b32 v46, v42, v43 offset1:1
	v_pk_mul_f32 v[42:43], v[44:45], v[198:199] op_sel_hi:[1,0]
	s_and_b64 vcc, exec, s[0:1]
	ds_write2_b32 v46, v42, v43 offset0:2 offset1:3
	s_cbranch_vccnz .LBB0_1650
	v_readlane_b32 s72, v254, 10
	v_readlane_b32 s82, v254, 20
	v_readlane_b32 s83, v254, 21
	s_nop 4
	v_add_u32_e32 v43, v88, v104
	v_readlane_b32 s73, v254, 11
	v_readlane_b32 s74, v254, 12
	v_readlane_b32 s75, v254, 13
	v_readlane_b32 s76, v254, 14
	v_readlane_b32 s77, v254, 15
	v_readlane_b32 s78, v254, 16
	v_readlane_b32 s79, v254, 17
	v_readlane_b32 s80, v254, 18
	v_readlane_b32 s81, v254, 19
	v_readlane_b32 s84, v254, 22
	v_readlane_b32 s85, v254, 23
	v_readlane_b32 s86, v254, 24
	v_readlane_b32 s87, v254, 25
	s_waitcnt vmcnt(1)
	v_pk_mul_f32 v[46:47], v[38:39], v[200:201] op_sel_hi:[1,0]
	v_pk_mul_f32 v[44:45], v[40:41], v[200:201] op_sel_hi:[1,0]
	ds_write2_b32 v43, v46, v47 offset1:1
	ds_write2_b32 v43, v44, v45 offset0:2 offset1:3
	s_cbranch_execnz .LBB0_1584

.LBB0_1584:
	s_waitcnt vmcnt(0)
	v_pk_mul_f32 v[34:35], v[34:35], v[202:203] op_sel_hi:[1,0]
	v_add_u32_e32 v38, v88, v105
	ds_write2_b32 v38, v34, v35 offset1:1
	v_pk_mul_f32 v[34:35], v[36:37], v[202:203] op_sel_hi:[1,0]
	s_and_b64 vcc, exec, s[0:1]
	ds_write2_b32 v38, v34, v35 offset0:2 offset1:3
	s_cbranch_vccnz .LBB0_1651
	v_readlane_b32 s72, v254, 10
	v_readlane_b32 s82, v254, 20
	v_readlane_b32 s83, v254, 21
	s_nop 4
	v_add_u32_e32 v35, v88, v106
	v_readlane_b32 s73, v254, 11
	v_readlane_b32 s74, v254, 12
	v_readlane_b32 s75, v254, 13
	v_readlane_b32 s76, v254, 14
	v_readlane_b32 s77, v254, 15
	v_readlane_b32 s78, v254, 16
	v_readlane_b32 s79, v254, 17
	v_readlane_b32 s80, v254, 18
	v_readlane_b32 s81, v254, 19
	v_readlane_b32 s84, v254, 22
	v_readlane_b32 s85, v254, 23
	v_readlane_b32 s86, v254, 24
	v_readlane_b32 s87, v254, 25
	s_waitcnt vmcnt(1)
	v_pk_mul_f32 v[38:39], v[30:31], v[204:205] op_sel_hi:[1,0]
	v_pk_mul_f32 v[36:37], v[32:33], v[204:205] op_sel_hi:[1,0]
	ds_write2_b32 v35, v38, v39 offset1:1
	ds_write2_b32 v35, v36, v37 offset0:2 offset1:3
	s_cbranch_execnz .LBB0_1587

.LBB0_1587:
	s_waitcnt vmcnt(0)
	v_pk_mul_f32 v[26:27], v[26:27], v[206:207] op_sel_hi:[1,0]
	v_add_u32_e32 v30, v88, v107
	ds_write2_b32 v30, v26, v27 offset1:1
	v_pk_mul_f32 v[26:27], v[28:29], v[206:207] op_sel_hi:[1,0]
	s_and_b64 vcc, exec, s[0:1]
	ds_write2_b32 v30, v26, v27 offset0:2 offset1:3
	s_cbranch_vccnz .LBB0_1652
	v_readlane_b32 s72, v254, 10
	v_readlane_b32 s82, v254, 20
	v_readlane_b32 s83, v254, 21
	s_nop 4
	v_add_u32_e32 v27, v88, v108
	v_readlane_b32 s73, v254, 11
	v_readlane_b32 s74, v254, 12
	v_readlane_b32 s75, v254, 13
	v_readlane_b32 s76, v254, 14
	v_readlane_b32 s77, v254, 15
	v_readlane_b32 s78, v254, 16
	v_readlane_b32 s79, v254, 17
	v_readlane_b32 s80, v254, 18
	v_readlane_b32 s81, v254, 19
	v_readlane_b32 s84, v254, 22
	v_readlane_b32 s85, v254, 23
	v_readlane_b32 s86, v254, 24
	v_readlane_b32 s87, v254, 25
	s_waitcnt vmcnt(1)
	v_pk_mul_f32 v[30:31], v[22:23], v[208:209] op_sel_hi:[1,0]
	v_pk_mul_f32 v[28:29], v[24:25], v[208:209] op_sel_hi:[1,0]
	ds_write2_b32 v27, v30, v31 offset1:1
	ds_write2_b32 v27, v28, v29 offset0:2 offset1:3
	s_cbranch_execnz .LBB0_1590

.LBB0_1590:
	s_waitcnt vmcnt(0)
	v_pk_mul_f32 v[22:23], v[18:19], v[210:211] op_sel_hi:[1,0]
	v_add_u32_e32 v19, v88, v109
	v_pk_mul_f32 v[20:21], v[20:21], v[210:211] op_sel_hi:[1,0]
	ds_write2_b32 v19, v20, v21 offset0:2 offset1:3
	s_and_b64 vcc, exec, s[0:1]
	v_add_u32_e32 v20, 0x410, v19
	v_add_u32_e32 v21, 0x418, v19
	ds_write2_b32 v19, v22, v23 offset1:1
	s_cbranch_vccnz .LBB0_1653
	v_readlane_b32 s72, v254, 10
	v_readlane_b32 s82, v254, 20
	v_readlane_b32 s83, v254, 21
	s_nop 4
	v_readlane_b32 s73, v254, 11
	v_readlane_b32 s74, v254, 12
	v_readlane_b32 s75, v254, 13
	v_readlane_b32 s76, v254, 14
	v_readlane_b32 s77, v254, 15
	v_readlane_b32 s78, v254, 16
	v_readlane_b32 s79, v254, 17
	v_readlane_b32 s80, v254, 18
	v_readlane_b32 s81, v254, 19
	v_readlane_b32 s84, v254, 22
	v_readlane_b32 s85, v254, 23
	v_readlane_b32 s86, v254, 24
	v_readlane_b32 s87, v254, 25
	s_waitcnt vmcnt(1)
	v_pk_mul_f32 v[24:25], v[14:15], v[212:213] op_sel_hi:[1,0]
	v_pk_mul_f32 v[22:23], v[16:17], v[212:213] op_sel_hi:[1,0]
	ds_write2_b32 v20, v24, v25 offset1:1
	ds_write2_b32 v21, v22, v23 offset1:1
	s_cbranch_execnz .LBB0_1593

.LBB0_1593:
	s_waitcnt vmcnt(0)
	v_pk_mul_f32 v[10:11], v[10:11], v[214:215] op_sel_hi:[1,0]
	v_add_u32_e32 v14, 0x820, v19
	ds_write2_b32 v14, v10, v11 offset1:1
	v_pk_mul_f32 v[10:11], v[12:13], v[214:215] op_sel_hi:[1,0]
	v_add_u32_e32 v12, 0x828, v19
	ds_write2_b32 v12, v10, v11 offset1:1
	s_and_b64 vcc, exec, s[0:1]
	v_add_u32_e32 v11, 0xc30, v19
	v_add_u32_e32 v12, 0xc38, v19
	s_cbranch_vccnz .LBB0_1654
	v_readlane_b32 s72, v254, 10
	v_readlane_b32 s82, v254, 20
	v_readlane_b32 s83, v254, 21
	s_nop 4
	v_readlane_b32 s73, v254, 11
	v_readlane_b32 s74, v254, 12
	v_readlane_b32 s75, v254, 13
	v_readlane_b32 s76, v254, 14
	v_readlane_b32 s77, v254, 15
	v_readlane_b32 s78, v254, 16
	v_readlane_b32 s79, v254, 17
	v_readlane_b32 s80, v254, 18
	v_readlane_b32 s81, v254, 19
	v_readlane_b32 s84, v254, 22
	v_readlane_b32 s85, v254, 23
	v_readlane_b32 s86, v254, 24
	v_readlane_b32 s87, v254, 25
	s_waitcnt vmcnt(1)
	v_pk_mul_f32 v[16:17], v[6:7], v[216:217] op_sel_hi:[1,0]
	v_pk_mul_f32 v[14:15], v[8:9], v[216:217] op_sel_hi:[1,0]
	ds_write2_b32 v11, v16, v17 offset1:1
	ds_write2_b32 v12, v14, v15 offset1:1
	s_cbranch_execnz .LBB0_1596

.LBB0_1596:
	s_waitcnt vmcnt(0)
	v_pk_mul_f32 v[2:3], v[2:3], v[218:219] op_sel_hi:[1,0]
	v_add_u32_e32 v6, 0x1040, v19
	s_lshl_b32 s0, s15, 6
	ds_write2_b32 v6, v2, v3 offset1:1
	v_pk_mul_f32 v[2:3], v[4:5], v[218:219] op_sel_hi:[1,0]
	v_add_u32_e32 v4, 0x1048, v19
	s_and_b32 s0, 0xffff, s0
	ds_write2_b32 v4, v2, v3 offset1:1
	s_lshl_b32 s1, s0, 1
	s_waitcnt lgkmcnt(0)
	s_and_b32 s0, s0, 64
	s_and_b32 s1, s1, 0x1f00
	s_or_b32 s0, s0, s1
	ds_read2_b32 v[2:3], v91 offset1:65
	s_bitset1_b32 s0, 7
	s_waitcnt lgkmcnt(0)
	v_cvt_pk_bf16_f32 v2, v2, v3
	ds_read2_b32 v[4:5], v91 offset0:130 offset1:195
	v_add_u32_e32 v12, 0x400, v91
	s_lshl_b32 s4, s14, 1
	v_or_b32_e32 v10, s0, v90
	s_waitcnt lgkmcnt(0)
	v_cvt_pk_bf16_f32 v3, v4, v5
	ds_read2_b32 v[4:5], v12 offset0:4 offset1:69
	v_lshl_add_u64 v[8:9], v[74:75], 0, s[4:5]
	v_lshlrev_b32_e32 v68, 11, v10
	s_waitcnt lgkmcnt(0)
	v_cvt_pk_bf16_f32 v4, v4, v5
	ds_read2_b32 v[6:7], v12 offset0:134 offset1:199
	s_waitcnt lgkmcnt(0)
	v_cvt_pk_bf16_f32 v5, v6, v7
	v_lshl_add_u64 v[10:11], v[8:9], 0, v[68:69]
	ds_read2_b32 v[6:7], v91 offset0:8 offset1:73
	global_store_dwordx4 v[10:11], v[2:5], off
	v_or_b32_e32 v10, s0, v92
	v_lshlrev_b32_e32 v68, 11, v10
	s_waitcnt lgkmcnt(0)
	v_cvt_pk_bf16_f32 v2, v6, v7
	ds_read2_b32 v[4:5], v91 offset0:138 offset1:203
	s_waitcnt lgkmcnt(0)
	v_cvt_pk_bf16_f32 v3, v4, v5
	ds_read2_b32 v[4:5], v12 offset0:12 offset1:77
	s_waitcnt lgkmcnt(0)
	v_cvt_pk_bf16_f32 v4, v4, v5
	ds_read2_b32 v[6:7], v12 offset0:142 offset1:207
	s_waitcnt lgkmcnt(0)
	v_cvt_pk_bf16_f32 v5, v6, v7
	v_lshl_add_u64 v[10:11], v[8:9], 0, v[68:69]
	ds_read2_b32 v[6:7], v91 offset0:16 offset1:81
	global_store_dwordx4 v[10:11], v[2:5], off
	v_or_b32_e32 v10, s0, v93
	v_lshlrev_b32_e32 v68, 11, v10
	s_waitcnt lgkmcnt(0)
	v_cvt_pk_bf16_f32 v2, v6, v7
	ds_read2_b32 v[4:5], v91 offset0:146 offset1:211
	s_waitcnt lgkmcnt(0)
	v_cvt_pk_bf16_f32 v3, v4, v5
	ds_read2_b32 v[4:5], v12 offset0:20 offset1:85
	s_waitcnt lgkmcnt(0)
	v_cvt_pk_bf16_f32 v4, v4, v5
	ds_read2_b32 v[6:7], v12 offset0:150 offset1:215
	s_waitcnt lgkmcnt(0)
	v_cvt_pk_bf16_f32 v5, v6, v7
	v_lshl_add_u64 v[10:11], v[8:9], 0, v[68:69]
	ds_read2_b32 v[6:7], v91 offset0:24 offset1:89
	global_store_dwordx4 v[10:11], v[2:5], off
	v_or_b32_e32 v10, s0, v94
	v_lshlrev_b32_e32 v68, 11, v10
	s_waitcnt lgkmcnt(0)
	v_cvt_pk_bf16_f32 v2, v6, v7
	ds_read2_b32 v[4:5], v91 offset0:154 offset1:219
	s_waitcnt lgkmcnt(0)
	v_cvt_pk_bf16_f32 v3, v4, v5
	ds_read2_b32 v[4:5], v12 offset0:28 offset1:93
	s_waitcnt lgkmcnt(0)
	v_cvt_pk_bf16_f32 v4, v4, v5
	ds_read2_b32 v[6:7], v12 offset0:158 offset1:223
	s_waitcnt lgkmcnt(0)
	v_cvt_pk_bf16_f32 v5, v6, v7
	v_lshl_add_u64 v[10:11], v[8:9], 0, v[68:69]
	ds_read2_b32 v[6:7], v91 offset0:32 offset1:97
	global_store_dwordx4 v[10:11], v[2:5], off
	v_or_b32_e32 v10, s0, v95
	v_lshlrev_b32_e32 v68, 11, v10
	s_waitcnt lgkmcnt(0)
	v_cvt_pk_bf16_f32 v2, v6, v7
	ds_read2_b32 v[4:5], v91 offset0:162 offset1:227
	s_waitcnt lgkmcnt(0)
	v_cvt_pk_bf16_f32 v3, v4, v5
	ds_read2_b32 v[4:5], v12 offset0:36 offset1:101
	s_waitcnt lgkmcnt(0)
	v_cvt_pk_bf16_f32 v4, v4, v5
	ds_read2_b32 v[6:7], v12 offset0:166 offset1:231
	s_waitcnt lgkmcnt(0)
	v_cvt_pk_bf16_f32 v5, v6, v7
	v_lshl_add_u64 v[10:11], v[8:9], 0, v[68:69]
	ds_read2_b32 v[6:7], v91 offset0:40 offset1:105
	global_store_dwordx4 v[10:11], v[2:5], off
	v_or_b32_e32 v10, s0, v96
	v_lshlrev_b32_e32 v68, 11, v10
	s_waitcnt lgkmcnt(0)
	v_cvt_pk_bf16_f32 v2, v6, v7
	ds_read2_b32 v[4:5], v91 offset0:170 offset1:235
	s_waitcnt lgkmcnt(0)
	v_cvt_pk_bf16_f32 v3, v4, v5
	ds_read2_b32 v[4:5], v12 offset0:44 offset1:109
	s_waitcnt lgkmcnt(0)
	v_cvt_pk_bf16_f32 v4, v4, v5
	ds_read2_b32 v[6:7], v12 offset0:174 offset1:239
	s_waitcnt lgkmcnt(0)
	v_cvt_pk_bf16_f32 v5, v6, v7
	v_lshl_add_u64 v[10:11], v[8:9], 0, v[68:69]
	ds_read2_b32 v[6:7], v91 offset0:48 offset1:113
	global_store_dwordx4 v[10:11], v[2:5], off
	v_or_b32_e32 v10, s0, v97
	v_lshlrev_b32_e32 v68, 11, v10
	s_waitcnt lgkmcnt(0)
	v_cvt_pk_bf16_f32 v2, v6, v7
	ds_read2_b32 v[4:5], v91 offset0:178 offset1:243
	s_waitcnt lgkmcnt(0)
	v_cvt_pk_bf16_f32 v3, v4, v5
	ds_read2_b32 v[4:5], v12 offset0:52 offset1:117
	s_waitcnt lgkmcnt(0)
	v_cvt_pk_bf16_f32 v4, v4, v5
	ds_read2_b32 v[6:7], v12 offset0:182 offset1:247
	s_waitcnt lgkmcnt(0)
	v_cvt_pk_bf16_f32 v5, v6, v7
	v_lshl_add_u64 v[10:11], v[8:9], 0, v[68:69]
	ds_read2_b32 v[6:7], v91 offset0:56 offset1:121
	global_store_dwordx4 v[10:11], v[2:5], off
	s_waitcnt lgkmcnt(0)
	s_nop 0
	v_cvt_pk_bf16_f32 v2, v6, v7
	ds_read2_b32 v[4:5], v91 offset0:186 offset1:251
	s_waitcnt lgkmcnt(0)
	v_cvt_pk_bf16_f32 v3, v4, v5
	ds_read2_b32 v[4:5], v12 offset0:60 offset1:125
	s_waitcnt lgkmcnt(0)
	v_cvt_pk_bf16_f32 v4, v4, v5
	v_or_b32_e32 v5, s0, v98
	ds_read2_b32 v[6:7], v12 offset0:190 offset1:255
	v_lshlrev_b32_e32 v68, 11, v5
	s_waitcnt lgkmcnt(0)
	v_cvt_pk_bf16_f32 v5, v6, v7
	v_lshl_add_u64 v[6:7], v[8:9], 0, v[68:69]
	global_store_dwordx4 v[6:7], v[2:5], off
	s_waitcnt lgkmcnt(0)
